# prep1: second virtual block does its transpose steps before the gate/decay loops (overlaps the first block's VALU work); dead generic prep0 loop removed
# speedup vs baseline: 1.0057x; 1.0014x over previous
.LBB0_756:
	v_readlane_b32 s40, v254, 24
	s_andn2_b64 vcc, exec, s[0:1]
	v_readlane_b32 s41, v254, 25
	s_cbranch_vccnz .LBB0_766
	s_mov_b32 s99, 0
	v_mov_b32_e32 v2, v0
	v_mov_b32_e32 v5, v0
	s_mov_b32 s0, s87
	v_mov_b32_e32 v1, v0
	s_nop 0
	v_ashrrev_i32_e32 v1, 8, v1
	v_lshl_add_u32 v1, s0, 1, v1
	s_movk_i32 s0, 0x200
	v_cmp_gt_i32_e32 vcc, s0, v1
	s_and_saveexec_b64 s[6:7], vcc
	s_cbranch_execz .LBB0_762
	s_load_dword s0, s[20:21], 0x0
	v_lshlrev_b32_e32 v2, 8, v2
	v_and_b32_e32 v6, 0xffff0000, v2
	v_lshlrev_b32_e32 v2, 3, v5
	v_add_u32_e32 v7, 0, v6
	v_and_b32_e32 v4, 0x78, v2
	v_lshl_add_u32 v12, v4, 1, v7
	v_bfe_u32 v13, v5, 4, 4
	v_and_b32_e32 v140, 0xff, v5
	s_waitcnt lgkmcnt(0)
	s_lshl_b32 s3, s0, 1
	s_movk_i32 s0, 0x80
	v_lshl_add_u32 v16, v13, 8, v12
	v_or_b32_e32 v19, 16, v13
	v_and_b32_e32 v8, 0x7f, v5
	v_cmp_gt_u32_e64 s[4:5], s0, v140
	v_add_u32_e32 v15, 0x2000, v16
	v_add_u32_e32 v17, 0x6000, v16
	v_lshl_add_u32 v16, v19, 8, v12
	v_or_b32_e32 v25, 32, v13
	v_or_b32_e32 v31, 48, v13
	v_cndmask_b32_e64 v10, 63, 0, s[4:5]
	v_add_u32_e32 v21, 0x2000, v16
	v_add_u32_e32 v23, 0x6000, v16
	v_lshl_add_u32 v16, v25, 8, v12
	v_lshl_add_u32 v12, v31, 8, v12
	v_lshlrev_b32_e32 v141, 1, v8
	v_add_u32_e32 v33, 0x2000, v12
	v_add_u32_e32 v35, 0x6000, v12
	v_lshl_or_b32 v12, v10, 8, v141
	v_bfe_u32 v14, v5, 7, 1
	v_add_u32_e32 v41, v7, v12
	v_cndmask_b32_e64 v12, 62, 1, s[4:5]
	v_lshl_add_u32 v9, v14, 6, v7
	v_lshlrev_b32_e32 v11, 2, v14
	v_lshl_or_b32 v37, v14, 13, v8
	v_lshl_or_b32 v39, v14, 9, v8
	v_lshl_or_b32 v14, v12, 8, v141
	v_add_u32_e32 v43, v7, v14
	v_cndmask_b32_e64 v14, 61, 2, s[4:5]
	v_add_u32_e32 v27, 0x2000, v16
	v_add_u32_e32 v29, 0x6000, v16
	v_lshl_or_b32 v16, v14, 8, v141
	v_add_u32_e32 v45, v7, v16
	v_cndmask_b32_e64 v16, 60, 3, s[4:5]
	v_lshl_or_b32 v18, v16, 8, v141
	v_add_u32_e32 v47, v7, v18
	v_cndmask_b32_e64 v18, 59, 4, s[4:5]
	v_lshl_or_b32 v20, v18, 8, v141
	v_add_u32_e32 v49, v7, v20
	v_cndmask_b32_e64 v20, 58, 5, s[4:5]
	v_lshl_or_b32 v22, v20, 8, v141
	v_add_u32_e32 v51, v7, v22
	v_cndmask_b32_e64 v22, 57, 6, s[4:5]
	v_lshl_or_b32 v24, v22, 8, v141
	v_add_u32_e32 v53, v7, v24
	v_cndmask_b32_e64 v24, 56, 7, s[4:5]
	v_lshl_or_b32 v26, v24, 8, v141
	v_add_u32_e32 v55, v7, v26
	v_cndmask_b32_e64 v26, 55, 8, s[4:5]
	v_lshl_or_b32 v28, v26, 8, v141
	v_add_u32_e32 v57, v7, v28
	v_cndmask_b32_e64 v28, 54, 9, s[4:5]
	v_lshl_or_b32 v30, v28, 8, v141
	v_add_u32_e32 v59, v7, v30
	v_cndmask_b32_e64 v30, 53, 10, s[4:5]
	v_lshl_or_b32 v32, v30, 8, v141
	v_add_u32_e32 v61, v7, v32
	v_cndmask_b32_e64 v32, 52, 11, s[4:5]
	v_lshl_or_b32 v34, v32, 8, v141
	v_add_u32_e32 v63, v7, v34
	v_cndmask_b32_e64 v34, 51, 12, s[4:5]
	v_lshl_or_b32 v38, v34, 8, v141
	v_add_u32_e32 v65, v7, v38
	v_cndmask_b32_e64 v38, 50, 13, s[4:5]
	v_lshl_or_b32 v40, v38, 8, v141
	v_add_u32_e32 v67, v7, v40
	v_cndmask_b32_e64 v40, 49, 14, s[4:5]
	v_lshl_or_b32 v42, v40, 8, v141
	v_add_u32_e32 v69, v7, v42
	v_cndmask_b32_e64 v42, 48, 15, s[4:5]
	v_lshl_or_b32 v44, v42, 8, v141
	v_add_u32_e32 v71, v7, v44
	v_cndmask_b32_e64 v44, 47, 16, s[4:5]
	v_lshl_or_b32 v46, v44, 8, v141
	v_add_u32_e32 v73, v7, v46
	v_cndmask_b32_e64 v46, 46, 17, s[4:5]
	v_lshl_or_b32 v48, v46, 8, v141
	v_add_u32_e32 v75, v7, v48
	v_cndmask_b32_e64 v48, 45, 18, s[4:5]
	v_lshl_or_b32 v50, v48, 8, v141
	v_add_u32_e32 v77, v7, v50
	v_cndmask_b32_e64 v50, 44, 19, s[4:5]
	v_lshl_or_b32 v52, v50, 8, v141
	v_add_u32_e32 v79, v7, v52
	v_cndmask_b32_e64 v52, 43, 20, s[4:5]
	v_lshl_or_b32 v54, v52, 8, v141
	v_add_u32_e32 v81, v7, v54
	v_cndmask_b32_e64 v54, 42, 21, s[4:5]
	v_lshl_or_b32 v56, v54, 8, v141
	v_add_u32_e32 v83, v7, v56
	v_cndmask_b32_e64 v56, 41, 22, s[4:5]
	v_lshl_or_b32 v58, v56, 8, v141
	v_add_u32_e32 v85, v7, v58
	v_cndmask_b32_e64 v58, 40, 23, s[4:5]
	v_lshl_or_b32 v60, v58, 8, v141
	s_waitcnt vmcnt(0)
	v_add_u32_e32 v87, v7, v60
	v_cndmask_b32_e64 v60, 39, 24, s[4:5]
	v_lshl_or_b32 v62, v60, 8, v141
	v_add_u32_e32 v89, v7, v62
	v_cndmask_b32_e64 v62, 38, 25, s[4:5]
	v_lshl_or_b32 v64, v62, 8, v141
	v_add_u32_e32 v91, v7, v64
	v_cndmask_b32_e64 v64, 37, 26, s[4:5]
	v_lshl_or_b32 v66, v64, 8, v141
	v_add_u32_e32 v93, v7, v66
	v_cndmask_b32_e64 v66, 36, 27, s[4:5]
	v_lshl_or_b32 v68, v66, 8, v141
	v_add_u32_e32 v95, v7, v68
	v_cndmask_b32_e64 v68, 35, 28, s[4:5]
	v_lshl_or_b32 v70, v68, 8, v141
	v_add_u32_e32 v97, v7, v70
	v_cndmask_b32_e64 v70, 34, 29, s[4:5]
	v_lshl_or_b32 v72, v70, 8, v141
	v_add_u32_e32 v99, v7, v72
	v_cndmask_b32_e64 v72, 33, 30, s[4:5]
	v_lshl_or_b32 v74, v72, 8, v141
	v_add_u32_e32 v101, v7, v74
	v_cndmask_b32_e64 v74, 32, 31, s[4:5]
	v_lshl_or_b32 v76, v74, 8, v141
	v_add_u32_e32 v103, v7, v76
	v_cndmask_b32_e64 v76, 31, 32, s[4:5]
	v_lshl_or_b32 v78, v76, 8, v141
	v_add_u32_e32 v105, v7, v78
	v_cndmask_b32_e64 v78, 30, 33, s[4:5]
	v_lshl_or_b32 v80, v78, 8, v141
	v_add_u32_e32 v107, v7, v80
	v_cndmask_b32_e64 v80, 29, 34, s[4:5]
	v_lshl_or_b32 v82, v80, 8, v141
	v_add_u32_e32 v109, v7, v82
	v_cndmask_b32_e64 v82, 28, 35, s[4:5]
	v_lshl_or_b32 v84, v82, 8, v141
	v_add_u32_e32 v111, v7, v84
	v_cndmask_b32_e64 v84, 27, 36, s[4:5]
	v_lshl_or_b32 v86, v84, 8, v141
	v_add_u32_e32 v113, v7, v86
	v_cndmask_b32_e64 v86, 26, 37, s[4:5]
	v_lshl_or_b32 v88, v86, 8, v141
	v_add_u32_e32 v115, v7, v88
	v_cndmask_b32_e64 v88, 25, 38, s[4:5]
	v_lshl_or_b32 v90, v88, 8, v141
	v_add_u32_e32 v117, v7, v90
	v_cndmask_b32_e64 v90, 24, 39, s[4:5]
	v_lshl_or_b32 v92, v90, 8, v141
	v_add_u32_e32 v119, v7, v92
	v_cndmask_b32_e64 v92, 23, 40, s[4:5]
	v_lshl_or_b32 v94, v92, 8, v141
	v_add_u32_e32 v121, v7, v94
	v_cndmask_b32_e64 v94, 22, 41, s[4:5]
	v_lshl_or_b32 v96, v94, 8, v141
	v_add_u32_e32 v123, v7, v96
	v_cndmask_b32_e64 v96, 21, 42, s[4:5]
	v_lshl_or_b32 v98, v96, 8, v141
	v_add_u32_e32 v125, v7, v98
	v_cndmask_b32_e64 v98, 20, 43, s[4:5]
	v_lshl_or_b32 v100, v98, 8, v141
	v_add_u32_e32 v127, v7, v100
	v_cndmask_b32_e64 v100, 19, 44, s[4:5]
	v_lshl_or_b32 v102, v100, 8, v141
	v_add_u32_e32 v129, v7, v102
	v_cndmask_b32_e64 v102, 18, 45, s[4:5]
	v_lshl_or_b32 v104, v102, 8, v141
	v_add_u32_e32 v131, v7, v104
	v_cndmask_b32_e64 v104, 17, 46, s[4:5]
	v_lshl_or_b32 v106, v104, 8, v141
	v_add_u32_e32 v133, v7, v106
	v_cndmask_b32_e64 v106, 16, 47, s[4:5]
	v_lshl_or_b32 v108, v106, 8, v141
	v_add_u32_e32 v135, v7, v108
	v_cndmask_b32_e64 v108, 15, 48, s[4:5]
	v_lshl_or_b32 v110, v108, 8, v141
	v_add_u32_e32 v137, v7, v110
	v_cndmask_b32_e64 v110, 14, 49, s[4:5]
	v_lshl_or_b32 v112, v110, 8, v141
	v_add_u32_e32 v139, v7, v112
	v_cndmask_b32_e64 v112, 13, 50, s[4:5]
	v_lshl_or_b32 v114, v112, 8, v141
	v_add_u32_e32 v148, v7, v114
	v_cndmask_b32_e64 v114, 12, 51, s[4:5]
	v_lshl_or_b32 v116, v114, 8, v141
	v_add_u32_e32 v149, v7, v116
	v_cndmask_b32_e64 v116, 11, 52, s[4:5]
	v_lshl_or_b32 v118, v116, 8, v141
	v_add_u32_e32 v150, v7, v118
	v_cndmask_b32_e64 v118, 10, 53, s[4:5]
	v_lshl_or_b32 v120, v118, 8, v141
	v_add_u32_e32 v151, v7, v120
	v_cndmask_b32_e64 v120, 9, 54, s[4:5]
	v_lshl_or_b32 v122, v120, 8, v141
	v_add_u32_e32 v152, v7, v122
	v_cndmask_b32_e64 v122, 8, 55, s[4:5]
	v_lshl_or_b32 v124, v122, 8, v141
	v_add_u32_e32 v153, v7, v124
	v_cndmask_b32_e64 v124, 7, 56, s[4:5]
	v_lshl_or_b32 v126, v124, 8, v141
	v_add_u32_e32 v162, v7, v126
	v_cndmask_b32_e64 v126, 6, 57, s[4:5]
	v_lshl_or_b32 v128, v126, 8, v141
	v_add_u32_e32 v163, v7, v128
	v_cndmask_b32_e64 v128, 5, 58, s[4:5]
	v_lshl_or_b32 v130, v128, 8, v141
	v_add_u32_e32 v164, v7, v130
	v_cndmask_b32_e64 v130, 4, 59, s[4:5]
	v_lshl_or_b32 v132, v130, 8, v141
	v_add_u32_e32 v165, v7, v132
	v_cndmask_b32_e64 v132, 3, 60, s[4:5]
	v_lshl_or_b32 v134, v132, 8, v141
	v_add_u32_e32 v166, v7, v134
	v_cndmask_b32_e64 v134, 2, 61, s[4:5]
	v_lshl_or_b32 v136, v134, 8, v141
	s_load_dwordx4 s[8:11], s[30:31], 0xd8
	v_add_u32_e32 v167, v7, v136
	v_cndmask_b32_e64 v136, 1, 62, s[4:5]
	v_lshl_or_b32 v138, v136, 8, v141
	v_add_u32_e32 v168, v7, v138
	v_cndmask_b32_e64 v138, 0, 63, s[4:5]
	v_and_b32_e32 v2, 31, v5
	v_lshl_or_b32 v141, v138, 8, v141
	v_lshl_or_b32 v6, v140, 2, v6
	v_add_u32_e32 v169, v7, v141
	v_or_b32_e32 v170, 0xffffff00, v140
	v_add_u32_e32 v171, 0, v6
	v_bfe_u32 v172, v5, 5, 3
	s_mov_b64 s[12:13], 0
	v_lshlrev_b32_e32 v2, 1, v2
	v_lshlrev_b32_e32 v140, 1, v4

.LBB0_760:
	v_mov_b64_e32 v[146:147], s[34:35]
	v_mad_i64_i32 v[146:147], s[14:15], v4, s27, v[146:147]
	v_lshl_add_u64 v[146:147], v[146:147], 0, v[2:3]
	v_add_co_u32_e32 v146, vcc, 0x1000, v146
	v_add_u32_e32 v6, 0x100, v6
	s_nop 0
	v_addc_co_u32_e32 v147, vcc, 0, v147, vcc
	global_load_ushort v7, v[146:147], off offset:2048
	s_movk_i32 s2, 0x6ff
	v_cmp_lt_u32_e32 vcc, s2, v6
	v_add_u32_e32 v4, 8, v4
	s_or_b64 s[0:1], vcc, s[0:1]
	s_waitcnt vmcnt(0)
	v_lshlrev_b32_e32 v7, 16, v7
	ds_write_b32 v5, v7
	v_add_u32_e32 v5, 0x400, v5
	s_andn2_b64 exec, exec, s[0:1]
	s_cbranch_execnz .LBB0_760
	s_or_b64 exec, exec, s[0:1]
	v_and_b32_e32 v143, 3, v1
	v_or_b32_e32 v4, v142, v13
	v_mov_b64_e32 v[146:147], s[34:35]
	v_mad_i64_i32 v[4:5], s[0:1], v4, s27, v[146:147]
	v_lshlrev_b32_e32 v154, 8, v143
	v_mov_b32_e32 v155, v3
	v_lshl_add_u64 v[4:5], v[4:5], 0, v[154:155]
	v_mov_b32_e32 v141, v3
	v_lshl_add_u64 v[156:157], v[4:5], 0, v[140:141]
	global_load_dwordx4 v[4:7], v[156:157], off
	v_lshlrev_b32_e32 v173, 7, v143
	v_add_u32_e32 v1, s3, v1
	s_waitcnt vmcnt(0)
	ds_write_b128 v15, v[4:7]
	global_load_dwordx4 v[4:7], v[156:157], off offset:1024
	s_waitcnt vmcnt(0)
	ds_write_b128 v17, v[4:7]
	v_or_b32_e32 v4, v142, v19
	v_mad_i64_i32 v[4:5], s[0:1], v4, s27, v[146:147]
	v_lshl_add_u64 v[4:5], v[4:5], 0, v[154:155]
	v_lshl_add_u64 v[156:157], v[4:5], 0, v[140:141]
	global_load_dwordx4 v[4:7], v[156:157], off
	s_waitcnt vmcnt(0)
	ds_write_b128 v21, v[4:7]
	global_load_dwordx4 v[4:7], v[156:157], off offset:1024
	s_waitcnt vmcnt(0)
	ds_write_b128 v23, v[4:7]
	v_or_b32_e32 v4, v142, v25
	v_mad_i64_i32 v[4:5], s[0:1], v4, s27, v[146:147]
	v_lshl_add_u64 v[4:5], v[4:5], 0, v[154:155]
	v_lshl_add_u64 v[156:157], v[4:5], 0, v[140:141]
	global_load_dwordx4 v[4:7], v[156:157], off
	s_waitcnt vmcnt(0)
	ds_write_b128 v27, v[4:7]
	global_load_dwordx4 v[4:7], v[156:157], off offset:1024
	s_waitcnt vmcnt(0)
	ds_write_b128 v29, v[4:7]
	v_or_b32_e32 v4, v142, v31
	v_mad_i64_i32 v[4:5], s[0:1], v4, s27, v[146:147]
	v_lshl_add_u64 v[4:5], v[4:5], 0, v[154:155]
	v_lshl_add_u64 v[146:147], v[4:5], 0, v[140:141]
	global_load_dwordx4 v[4:7], v[146:147], off
	s_movk_i32 s0, 0x1000
	v_or_b32_e32 v141, v173, v39
	v_lshlrev_b32_e32 v141, 2, v141
	s_waitcnt vmcnt(0)
	ds_write_b128 v33, v[4:7]
	global_load_dwordx4 v[4:7], v[146:147], off offset:1024
	s_waitcnt vmcnt(0)
	ds_write_b128 v35, v[4:7]
	v_or_b32_e32 v4, v173, v37
	v_lshlrev_b32_e32 v6, 2, v4
	v_mov_b32_e32 v7, v3
	v_lshl_add_u64 v[158:159], s[8:9], 0, v[6:7]
	v_add_co_u32_e32 v146, vcc, s0, v158
	s_movk_i32 s0, 0x2000
	s_nop 0
	v_addc_co_u32_e32 v147, vcc, 0, v159, vcc
	v_add_co_u32_e32 v154, vcc, s0, v158
	s_movk_i32 s0, 0x3000
	s_nop 0
	v_addc_co_u32_e32 v155, vcc, 0, v159, vcc
	s_waitcnt lgkmcnt(0)
	s_barrier
	v_cmp_lt_u32_e32 vcc, 0xff, v0
	s_cbranch_vccz .Lp1e_skip
	s_load_dword s98, s[20:21], 0x0
	s_waitcnt lgkmcnt(0)
	s_cmp_lg_u32 s98, 0x100
	s_cbranch_scc1 .Lp1e_skip
	s_mov_b32 s99, 1
	v_lshl_add_u32 v173, s87, 9, v0
	v_mov_b32_e32 v193, 0
	s_mov_b32 s98, 8
.Lp1e_loop:
	v_lshrrev_b32_e32 v176, 9, v173
	v_bfe_u32 v192, v173, 3, 3
	v_lshrrev_b32_e32 v177, 4, v176
	v_lshl_or_b32 v192, v177, 3, v192
	v_and_b32_e32 v180, 15, v176
	v_bfe_u32 v177, v173, 6, 3
	v_lshl_or_b32 v180, v180, 3, v177
	v_and_b32_e32 v177, 7, v173
	v_lshl_or_b32 v180, v180, 3, v177
	v_lshlrev_b32_e32 v184, 3, v192
	v_ashrrev_i32_e32 v181, 31, v180
	v_mov_b64_e32 v[176:177], s[34:35]
	v_mad_i64_i32 v[178:179], vcc, v184, s27, v[176:177]
	v_lshlrev_b64 v[182:183], 1, v[180:181]
	v_lshl_add_u64 v[178:179], v[178:179], 0, v[182:183]
	global_load_ushort v185, v[178:179], off offset:2048
	v_or_b32_e32 v178, 1, v184
	v_mad_i64_i32 v[178:179], vcc, v178, s27, v[176:177]
	v_lshl_add_u64 v[178:179], v[178:179], 0, v[182:183]
	global_load_ushort v186, v[178:179], off offset:2048
	v_or_b32_e32 v178, 2, v184
	v_mad_i64_i32 v[178:179], vcc, v178, s27, v[176:177]
	v_lshl_add_u64 v[178:179], v[178:179], 0, v[182:183]
	global_load_ushort v187, v[178:179], off offset:2048
	v_or_b32_e32 v178, 3, v184
	v_mad_i64_i32 v[178:179], vcc, v178, s27, v[176:177]
	v_lshl_add_u64 v[178:179], v[178:179], 0, v[182:183]
	global_load_ushort v188, v[178:179], off offset:2048
	v_or_b32_e32 v178, 4, v184
	v_mad_i64_i32 v[178:179], vcc, v178, s27, v[176:177]
	v_lshl_add_u64 v[178:179], v[178:179], 0, v[182:183]
	global_load_ushort v189, v[178:179], off offset:2048
	v_or_b32_e32 v178, 5, v184
	v_mad_i64_i32 v[178:179], vcc, v178, s27, v[176:177]
	v_lshl_add_u64 v[178:179], v[178:179], 0, v[182:183]
	global_load_ushort v190, v[178:179], off offset:2048
	v_or_b32_e32 v178, 6, v184
	v_mad_i64_i32 v[178:179], vcc, v178, s27, v[176:177]
	v_lshl_add_u64 v[178:179], v[178:179], 0, v[182:183]
	global_load_ushort v178, v[178:179], off offset:2048
	v_or_b32_e32 v179, 7, v184
	v_mad_i64_i32 v[176:177], vcc, v179, s27, v[176:177]
	v_lshl_add_u64 v[176:177], v[176:177], 0, v[182:183]
	global_load_ushort v176, v[176:177], off offset:2048
	v_lshlrev_b64 v[180:181], 14, v[180:181]
	v_and_b32_e32 v182, -16, v184
	v_lshl_add_u64 v[180:181], s[52:53], 0, v[180:181]
	v_ashrrev_i32_e32 v183, 31, v182
	v_lshlrev_b32_e32 v192, 4, v192
	v_lshl_add_u64 v[180:181], v[182:183], 1, v[180:181]
	v_and_b32_e32 v192, 16, v192
	v_lshl_add_u64 v[180:181], v[180:181], 0, v[192:193]
	s_waitcnt vmcnt(0)
	v_perm_b32 v177, v188, v187, s23
	v_perm_b32 v179, v176, v178, s23
	v_perm_b32 v178, v190, v189, s23
	v_perm_b32 v176, v186, v185, s23
	global_store_dwordx4 v[180:181], v[176:179], off
	v_add_u32_e32 v173, 0x20000, v173
	s_sub_u32 s98, s98, 1
	s_cmp_lg_u32 s98, 0
	s_cbranch_scc1 .Lp1e_loop
	s_waitcnt vmcnt(0)
.Lp1e_skip:
	global_load_dword v4, v6, s[8:9]
	global_load_dword v5, v6, s[8:9] offset:2048
	s_nop 0
	global_load_dword v6, v[154:155], off offset:-4096
	global_load_dword v7, v[146:147], off offset:2048
	global_load_dword v228, v[154:155], off
	s_nop 0
	global_load_dword v154, v[154:155], off offset:2048
	v_add_co_u32_e32 v146, vcc, s0, v158
	s_movk_i32 s0, 0x5000
	s_nop 0
	v_addc_co_u32_e32 v147, vcc, 0, v159, vcc
	v_add_co_u32_e32 v160, vcc, s17, v158
	s_nop 1
	v_addc_co_u32_e32 v161, vcc, 0, v159, vcc
	global_load_dword v155, v[160:161], off offset:-4096
	global_load_dword v156, v[146:147], off offset:2048
	s_nop 0
	global_load_dword v146, v[160:161], off
	global_load_dword v252, v[160:161], off offset:2048
	v_add_co_u32_e32 v160, vcc, s0, v158
	s_movk_i32 s0, 0x7000
	s_nop 0
	v_addc_co_u32_e32 v161, vcc, 0, v159, vcc
	v_add_co_u32_e32 v174, vcc, s62, v158
	s_nop 1
	v_addc_co_u32_e32 v175, vcc, 0, v159, vcc
	v_add_co_u32_e32 v158, vcc, s0, v158
	global_load_dword v253, v[174:175], off offset:-4096
	global_load_dword v227, v[160:161], off offset:2048
	global_load_dword v145, v[174:175], off
	global_load_dword v147, v[174:175], off offset:2048
	v_addc_co_u32_e32 v159, vcc, 0, v159, vcc
	global_load_dword v230, v[158:159], off
	global_load_dword v231, v[158:159], off offset:2048
	global_load_dword v157, v141, s[10:11]
	ds_read_b128 v[174:177], v9
	ds_read_b128 v[178:181], v9 offset:16
	ds_read_b128 v[182:185], v9 offset:32
	ds_read_b128 v[186:189], v9 offset:48
	ds_read_b128 v[212:215], v9 offset:4480
	ds_read_b128 v[234:237], v9 offset:4992
	s_waitcnt vmcnt(15) lgkmcnt(5)
	v_mul_f32_e32 v141, v5, v175
	v_fmac_f32_e32 v141, v4, v174
	s_waitcnt vmcnt(11) lgkmcnt(4)
	v_mul_f32_e32 v158, v154, v179
	v_fmac_f32_e32 v141, v6, v176
	v_fmac_f32_e32 v158, v228, v178
	v_fmac_f32_e32 v141, v7, v177
	ds_read_b128 v[174:177], v9 offset:128
	s_waitcnt vmcnt(10)
	v_fmac_f32_e32 v158, v155, v180
	s_waitcnt vmcnt(9)
	v_fmac_f32_e32 v158, v156, v181
	s_waitcnt vmcnt(0)
	v_add_f32_e32 v141, v157, v141
	v_add_f32_e32 v141, v141, v158
	s_waitcnt lgkmcnt(4)
	v_mul_f32_e32 v158, v252, v183
	v_fmac_f32_e32 v158, v146, v182
	v_fmac_f32_e32 v158, v253, v184
	v_fmac_f32_e32 v158, v227, v185
	v_add_f32_e32 v141, v141, v158
	s_waitcnt lgkmcnt(3)
	v_mul_f32_e32 v158, v147, v187
	v_fmac_f32_e32 v158, v145, v186
	v_fmac_f32_e32 v158, v230, v188
	v_fmac_f32_e32 v158, v231, v189
	v_add_f32_e32 v141, v141, v158
	v_min_f32_e32 v158, 0, v141
	v_mul_f32_e64 v141, |v141|, s18
	v_exp_f32_e32 v141, v141
	s_nop 0
	v_add_f32_e32 v141, 1.0, v141
	v_cmp_gt_f32_e32 vcc, s71, v141
	s_nop 1
	v_cndmask_b32_e64 v159, 0, 32, vcc
	v_ldexp_f32 v141, v141, v159
	v_log_f32_e32 v141, v141
	s_nop 0
	v_mul_f32_e32 v159, 0x3f317217, v141
	v_fma_f32 v159, v141, s48, -v159
	v_fmac_f32_e32 v159, 0x3377d1cf, v141
	v_fmac_f32_e32 v159, 0x3f317217, v141
	v_cmp_lt_f32_e64 s[0:1], |v141|, s49
	s_nop 1
	v_cndmask_b32_e64 v141, v141, v159, s[0:1]
	v_cndmask_b32_e32 v159, 0, v233, vcc
	v_sub_f32_e32 v141, v141, v159
	v_sub_f32_e32 v141, v158, v141
	s_waitcnt lgkmcnt(0)
	v_mul_f32_e32 v158, v5, v175
	v_fmac_f32_e32 v158, v4, v174
	v_fmac_f32_e32 v158, v6, v176
	v_fmac_f32_e32 v158, v7, v177
	ds_read_b128 v[174:177], v9 offset:144
	v_add_f32_e32 v158, v157, v158
	s_mov_b32 s0, 0x3d800000
	v_mul_f32_e32 v173, 0x3d800000, v141
	v_fma_f32 v141, v141, s0, 0
	s_waitcnt lgkmcnt(0)
	v_mul_f32_e32 v159, v154, v175
	v_fmac_f32_e32 v159, v228, v174
	v_fmac_f32_e32 v159, v155, v176
	v_fmac_f32_e32 v159, v156, v177
	ds_read_b128 v[174:177], v9 offset:160
	v_add_f32_e32 v158, v158, v159
	s_waitcnt lgkmcnt(0)
	v_mul_f32_e32 v159, v252, v175
	v_fmac_f32_e32 v159, v146, v174
	v_fmac_f32_e32 v159, v253, v176
	v_fmac_f32_e32 v159, v227, v177
	ds_read_b128 v[174:177], v9 offset:176
	v_add_f32_e32 v158, v158, v159
	s_waitcnt lgkmcnt(0)
	v_mul_f32_e32 v159, v147, v175
	v_fmac_f32_e32 v159, v145, v174
	v_fmac_f32_e32 v159, v230, v176
	v_fmac_f32_e32 v159, v231, v177
	v_add_f32_e32 v158, v158, v159
	v_min_f32_e32 v159, 0, v158
	v_mul_f32_e64 v158, |v158|, s18
	v_exp_f32_e32 v158, v158
	ds_read_b128 v[176:179], v9 offset:256
	v_add_f32_e32 v158, 1.0, v158
	v_cmp_gt_f32_e32 vcc, s71, v158
	s_nop 1
	v_cndmask_b32_e64 v160, 0, 32, vcc
	v_ldexp_f32 v158, v158, v160
	v_log_f32_e32 v158, v158
	s_nop 0
	v_mul_f32_e32 v160, 0x3f317217, v158
	v_fma_f32 v160, v158, s48, -v160
	v_fmac_f32_e32 v160, 0x3377d1cf, v158
	v_fmac_f32_e32 v160, 0x3f317217, v158
	v_cmp_lt_f32_e64 s[0:1], |v158|, s49
	s_nop 1
	v_cndmask_b32_e64 v158, v158, v160, s[0:1]
	v_cndmask_b32_e32 v160, 0, v233, vcc
	v_sub_f32_e32 v158, v158, v160
	v_sub_f32_e32 v158, v159, v158
	v_mul_f32_e32 v174, 0x3d800000, v158
	v_fmac_f32_e32 v141, 0x3d800000, v158
	s_waitcnt lgkmcnt(0)
	v_mul_f32_e32 v158, v5, v177
	v_fmac_f32_e32 v158, v4, v176
	v_fmac_f32_e32 v158, v6, v178
	v_fmac_f32_e32 v158, v7, v179
	ds_read_b128 v[176:179], v9 offset:272
	v_add_f32_e32 v158, v157, v158
	s_waitcnt lgkmcnt(0)
	v_mul_f32_e32 v159, v154, v177
	v_fmac_f32_e32 v159, v228, v176
	v_fmac_f32_e32 v159, v155, v178
	v_fmac_f32_e32 v159, v156, v179
	ds_read_b128 v[176:179], v9 offset:288
	v_add_f32_e32 v158, v158, v159
	s_waitcnt lgkmcnt(0)
	v_mul_f32_e32 v159, v252, v177
	v_fmac_f32_e32 v159, v146, v176
	v_fmac_f32_e32 v159, v253, v178
	v_fmac_f32_e32 v159, v227, v179
	ds_read_b128 v[176:179], v9 offset:304
	v_add_f32_e32 v158, v158, v159
	s_waitcnt lgkmcnt(0)
	v_mul_f32_e32 v159, v147, v177
	v_fmac_f32_e32 v159, v145, v176
	v_fmac_f32_e32 v159, v230, v178
	v_fmac_f32_e32 v159, v231, v179
	v_add_f32_e32 v158, v158, v159
	v_min_f32_e32 v159, 0, v158
	v_mul_f32_e64 v158, |v158|, s18
	v_exp_f32_e32 v158, v158
	ds_read_b128 v[176:179], v9 offset:384
	v_add_f32_e32 v158, 1.0, v158
	v_cmp_gt_f32_e32 vcc, s71, v158
	s_nop 1
	v_cndmask_b32_e64 v160, 0, 32, vcc
	v_ldexp_f32 v158, v158, v160
	v_log_f32_e32 v158, v158
	s_nop 0
	v_mul_f32_e32 v160, 0x3f317217, v158
	v_fma_f32 v160, v158, s48, -v160
	v_fmac_f32_e32 v160, 0x3377d1cf, v158
	v_fmac_f32_e32 v160, 0x3f317217, v158
	v_cmp_lt_f32_e64 s[0:1], |v158|, s49
	s_nop 1
	v_cndmask_b32_e64 v158, v158, v160, s[0:1]
	v_cndmask_b32_e32 v160, 0, v233, vcc
	v_sub_f32_e32 v158, v158, v160
	v_sub_f32_e32 v158, v159, v158
	v_mul_f32_e32 v175, 0x3d800000, v158
	v_fmac_f32_e32 v141, 0x3d800000, v158
	s_waitcnt lgkmcnt(0)
	v_mul_f32_e32 v158, v5, v177
	v_fmac_f32_e32 v158, v4, v176
	v_fmac_f32_e32 v158, v6, v178
	v_fmac_f32_e32 v158, v7, v179
	ds_read_b128 v[176:179], v9 offset:400
	v_add_f32_e32 v158, v157, v158
	s_waitcnt lgkmcnt(0)
	v_mul_f32_e32 v159, v154, v177
	v_fmac_f32_e32 v159, v228, v176
	v_fmac_f32_e32 v159, v155, v178
	v_fmac_f32_e32 v159, v156, v179
	ds_read_b128 v[176:179], v9 offset:416
	v_add_f32_e32 v158, v158, v159
	s_waitcnt lgkmcnt(0)
	v_mul_f32_e32 v159, v252, v177
	v_fmac_f32_e32 v159, v146, v176
	v_fmac_f32_e32 v159, v253, v178
	v_fmac_f32_e32 v159, v227, v179
	ds_read_b128 v[176:179], v9 offset:432
	v_add_f32_e32 v158, v158, v159
	s_waitcnt lgkmcnt(0)
	v_mul_f32_e32 v159, v147, v177
	v_fmac_f32_e32 v159, v145, v176
	v_fmac_f32_e32 v159, v230, v178
	v_fmac_f32_e32 v159, v231, v179
	v_add_f32_e32 v158, v158, v159
	v_min_f32_e32 v159, 0, v158
	v_mul_f32_e64 v158, |v158|, s18
	v_exp_f32_e32 v158, v158
	ds_read_b128 v[178:181], v9 offset:512
	v_add_f32_e32 v158, 1.0, v158
	v_cmp_gt_f32_e32 vcc, s71, v158
	s_nop 1
	v_cndmask_b32_e64 v160, 0, 32, vcc
	v_ldexp_f32 v158, v158, v160
	v_log_f32_e32 v158, v158
	s_nop 0
	v_mul_f32_e32 v160, 0x3f317217, v158
	v_fma_f32 v160, v158, s48, -v160
	v_fmac_f32_e32 v160, 0x3377d1cf, v158
	v_fmac_f32_e32 v160, 0x3f317217, v158
	v_cmp_lt_f32_e64 s[0:1], |v158|, s49
	s_nop 1
	v_cndmask_b32_e64 v158, v158, v160, s[0:1]
	v_cndmask_b32_e32 v160, 0, v233, vcc
	v_sub_f32_e32 v158, v158, v160
	v_sub_f32_e32 v158, v159, v158
	v_mul_f32_e32 v176, 0x3d800000, v158
	v_fmac_f32_e32 v141, 0x3d800000, v158
	s_waitcnt lgkmcnt(0)
	v_mul_f32_e32 v158, v5, v179
	v_fmac_f32_e32 v158, v4, v178
	v_fmac_f32_e32 v158, v6, v180
	v_fmac_f32_e32 v158, v7, v181
	ds_read_b128 v[178:181], v9 offset:528
	v_add_f32_e32 v158, v157, v158
	s_waitcnt lgkmcnt(0)
	v_mul_f32_e32 v159, v154, v179
	v_fmac_f32_e32 v159, v228, v178
	v_fmac_f32_e32 v159, v155, v180
	v_fmac_f32_e32 v159, v156, v181
	ds_read_b128 v[178:181], v9 offset:544
	v_add_f32_e32 v158, v158, v159
	s_waitcnt lgkmcnt(0)
	v_mul_f32_e32 v159, v252, v179
	v_fmac_f32_e32 v159, v146, v178
	v_fmac_f32_e32 v159, v253, v180
	v_fmac_f32_e32 v159, v227, v181
	ds_read_b128 v[178:181], v9 offset:560
	v_add_f32_e32 v158, v158, v159
	s_waitcnt lgkmcnt(0)
	v_mul_f32_e32 v159, v147, v179
	v_fmac_f32_e32 v159, v145, v178
	v_fmac_f32_e32 v159, v230, v180
	v_fmac_f32_e32 v159, v231, v181
	v_add_f32_e32 v158, v158, v159
	v_min_f32_e32 v159, 0, v158
	v_mul_f32_e64 v158, |v158|, s18
	v_exp_f32_e32 v158, v158
	ds_read_b128 v[178:181], v9 offset:640
	v_add_f32_e32 v158, 1.0, v158
	v_cmp_gt_f32_e32 vcc, s71, v158
	s_nop 1
	v_cndmask_b32_e64 v160, 0, 32, vcc
	v_ldexp_f32 v158, v158, v160
	v_log_f32_e32 v158, v158
	s_nop 0
	v_mul_f32_e32 v160, 0x3f317217, v158
	v_fma_f32 v160, v158, s48, -v160
	v_fmac_f32_e32 v160, 0x3377d1cf, v158
	v_fmac_f32_e32 v160, 0x3f317217, v158
	v_cmp_lt_f32_e64 s[0:1], |v158|, s49
	s_nop 1
	v_cndmask_b32_e64 v158, v158, v160, s[0:1]
	v_cndmask_b32_e32 v160, 0, v233, vcc
	v_sub_f32_e32 v158, v158, v160
	v_sub_f32_e32 v158, v159, v158
	v_mul_f32_e32 v177, 0x3d800000, v158
	v_fmac_f32_e32 v141, 0x3d800000, v158
	s_waitcnt lgkmcnt(0)
	v_mul_f32_e32 v158, v5, v179
	v_fmac_f32_e32 v158, v4, v178
	v_fmac_f32_e32 v158, v6, v180
	v_fmac_f32_e32 v158, v7, v181
	ds_read_b128 v[178:181], v9 offset:656
	v_add_f32_e32 v158, v157, v158
	s_waitcnt lgkmcnt(0)
	v_mul_f32_e32 v159, v154, v179
	v_fmac_f32_e32 v159, v228, v178
	v_fmac_f32_e32 v159, v155, v180
	v_fmac_f32_e32 v159, v156, v181
	ds_read_b128 v[178:181], v9 offset:672
	v_add_f32_e32 v158, v158, v159
	s_waitcnt lgkmcnt(0)
	v_mul_f32_e32 v159, v252, v179
	v_fmac_f32_e32 v159, v146, v178
	v_fmac_f32_e32 v159, v253, v180
	v_fmac_f32_e32 v159, v227, v181
	ds_read_b128 v[178:181], v9 offset:688
	v_add_f32_e32 v158, v158, v159
	s_waitcnt lgkmcnt(0)
	v_mul_f32_e32 v159, v147, v179
	v_fmac_f32_e32 v159, v145, v178
	v_fmac_f32_e32 v159, v230, v180
	v_fmac_f32_e32 v159, v231, v181
	v_add_f32_e32 v158, v158, v159
	v_min_f32_e32 v159, 0, v158
	v_mul_f32_e64 v158, |v158|, s18
	v_exp_f32_e32 v158, v158
	ds_read_b128 v[180:183], v9 offset:768
	v_add_f32_e32 v158, 1.0, v158
	v_cmp_gt_f32_e32 vcc, s71, v158
	s_nop 1
	v_cndmask_b32_e64 v160, 0, 32, vcc
	v_ldexp_f32 v158, v158, v160
	v_log_f32_e32 v158, v158
	s_nop 0
	v_mul_f32_e32 v160, 0x3f317217, v158
	v_fma_f32 v160, v158, s48, -v160
	v_fmac_f32_e32 v160, 0x3377d1cf, v158
	v_fmac_f32_e32 v160, 0x3f317217, v158
	v_cmp_lt_f32_e64 s[0:1], |v158|, s49
	s_nop 1
	v_cndmask_b32_e64 v158, v158, v160, s[0:1]
	v_cndmask_b32_e32 v160, 0, v233, vcc
	v_sub_f32_e32 v158, v158, v160
	v_sub_f32_e32 v158, v159, v158
	v_mul_f32_e32 v178, 0x3d800000, v158
	v_fmac_f32_e32 v141, 0x3d800000, v158
	s_waitcnt lgkmcnt(0)
	v_mul_f32_e32 v158, v5, v181
	v_fmac_f32_e32 v158, v4, v180
	v_fmac_f32_e32 v158, v6, v182
	v_fmac_f32_e32 v158, v7, v183
	ds_read_b128 v[180:183], v9 offset:784
	v_add_f32_e32 v158, v157, v158
	s_waitcnt lgkmcnt(0)
	v_mul_f32_e32 v159, v154, v181
	v_fmac_f32_e32 v159, v228, v180
	v_fmac_f32_e32 v159, v155, v182
	v_fmac_f32_e32 v159, v156, v183
	ds_read_b128 v[180:183], v9 offset:800
	v_add_f32_e32 v158, v158, v159
	s_waitcnt lgkmcnt(0)
	v_mul_f32_e32 v159, v252, v181
	v_fmac_f32_e32 v159, v146, v180
	v_fmac_f32_e32 v159, v253, v182
	v_fmac_f32_e32 v159, v227, v183
	ds_read_b128 v[180:183], v9 offset:816
	v_add_f32_e32 v158, v158, v159
	s_waitcnt lgkmcnt(0)
	v_mul_f32_e32 v159, v147, v181
	v_fmac_f32_e32 v159, v145, v180
	v_fmac_f32_e32 v159, v230, v182
	v_fmac_f32_e32 v159, v231, v183
	v_add_f32_e32 v158, v158, v159
	v_min_f32_e32 v159, 0, v158
	v_mul_f32_e64 v158, |v158|, s18
	v_exp_f32_e32 v158, v158
	ds_read_b128 v[180:183], v9 offset:896
	v_add_f32_e32 v158, 1.0, v158
	v_cmp_gt_f32_e32 vcc, s71, v158
	s_nop 1
	v_cndmask_b32_e64 v160, 0, 32, vcc
	v_ldexp_f32 v158, v158, v160
	v_log_f32_e32 v158, v158
	s_nop 0
	v_mul_f32_e32 v160, 0x3f317217, v158
	v_fma_f32 v160, v158, s48, -v160
	v_fmac_f32_e32 v160, 0x3377d1cf, v158
	v_fmac_f32_e32 v160, 0x3f317217, v158
	v_cmp_lt_f32_e64 s[0:1], |v158|, s49
	s_nop 1
	v_cndmask_b32_e64 v158, v158, v160, s[0:1]
	v_cndmask_b32_e32 v160, 0, v233, vcc
	v_sub_f32_e32 v158, v158, v160
	v_sub_f32_e32 v158, v159, v158
	v_mul_f32_e32 v179, 0x3d800000, v158
	v_fmac_f32_e32 v141, 0x3d800000, v158
	s_waitcnt lgkmcnt(0)
	v_mul_f32_e32 v158, v5, v181
	v_fmac_f32_e32 v158, v4, v180
	v_fmac_f32_e32 v158, v6, v182
	v_fmac_f32_e32 v158, v7, v183
	ds_read_b128 v[180:183], v9 offset:912
	v_add_f32_e32 v158, v157, v158
	s_waitcnt lgkmcnt(0)
	v_mul_f32_e32 v159, v154, v181
	v_fmac_f32_e32 v159, v228, v180
	v_fmac_f32_e32 v159, v155, v182
	v_fmac_f32_e32 v159, v156, v183
	ds_read_b128 v[180:183], v9 offset:928
	v_add_f32_e32 v158, v158, v159
	s_waitcnt lgkmcnt(0)
	v_mul_f32_e32 v159, v252, v181
	v_fmac_f32_e32 v159, v146, v180
	v_fmac_f32_e32 v159, v253, v182
	v_fmac_f32_e32 v159, v227, v183
	ds_read_b128 v[180:183], v9 offset:944
	v_add_f32_e32 v158, v158, v159
	s_waitcnt lgkmcnt(0)
	v_mul_f32_e32 v159, v147, v181
	v_fmac_f32_e32 v159, v145, v180
	v_fmac_f32_e32 v159, v230, v182
	v_fmac_f32_e32 v159, v231, v183
	v_add_f32_e32 v158, v158, v159
	v_min_f32_e32 v159, 0, v158
	v_mul_f32_e64 v158, |v158|, s18
	v_exp_f32_e32 v158, v158
	ds_read_b128 v[182:185], v9 offset:1024
	v_add_f32_e32 v158, 1.0, v158
	v_cmp_gt_f32_e32 vcc, s71, v158
	s_nop 1
	v_cndmask_b32_e64 v160, 0, 32, vcc
	v_ldexp_f32 v158, v158, v160
	v_log_f32_e32 v158, v158
	s_nop 0
	v_mul_f32_e32 v160, 0x3f317217, v158
	v_fma_f32 v160, v158, s48, -v160
	v_fmac_f32_e32 v160, 0x3377d1cf, v158
	v_fmac_f32_e32 v160, 0x3f317217, v158
	v_cmp_lt_f32_e64 s[0:1], |v158|, s49
	s_nop 1
	v_cndmask_b32_e64 v158, v158, v160, s[0:1]
	v_cndmask_b32_e32 v160, 0, v233, vcc
	v_sub_f32_e32 v158, v158, v160
	v_sub_f32_e32 v158, v159, v158
	v_mul_f32_e32 v180, 0x3d800000, v158
	v_fmac_f32_e32 v141, 0x3d800000, v158
	s_waitcnt lgkmcnt(0)
	v_mul_f32_e32 v158, v5, v183
	v_fmac_f32_e32 v158, v4, v182
	v_fmac_f32_e32 v158, v6, v184
	v_fmac_f32_e32 v158, v7, v185
	ds_read_b128 v[182:185], v9 offset:1040
	v_add_f32_e32 v158, v157, v158
	s_waitcnt lgkmcnt(0)
	v_mul_f32_e32 v159, v154, v183
	v_fmac_f32_e32 v159, v228, v182
	v_fmac_f32_e32 v159, v155, v184
	v_fmac_f32_e32 v159, v156, v185
	ds_read_b128 v[182:185], v9 offset:1056
	v_add_f32_e32 v158, v158, v159
	s_waitcnt lgkmcnt(0)
	v_mul_f32_e32 v159, v252, v183
	v_fmac_f32_e32 v159, v146, v182
	v_fmac_f32_e32 v159, v253, v184
	v_fmac_f32_e32 v159, v227, v185
	ds_read_b128 v[182:185], v9 offset:1072
	v_add_f32_e32 v158, v158, v159
	s_waitcnt lgkmcnt(0)
	v_mul_f32_e32 v159, v147, v183
	v_fmac_f32_e32 v159, v145, v182
	v_fmac_f32_e32 v159, v230, v184
	v_fmac_f32_e32 v159, v231, v185
	v_add_f32_e32 v158, v158, v159
	v_min_f32_e32 v159, 0, v158
	v_mul_f32_e64 v158, |v158|, s18
	v_exp_f32_e32 v158, v158
	ds_read_b128 v[182:185], v9 offset:1152
	v_add_f32_e32 v158, 1.0, v158
	v_cmp_gt_f32_e32 vcc, s71, v158
	s_nop 1
	v_cndmask_b32_e64 v160, 0, 32, vcc
	v_ldexp_f32 v158, v158, v160
	v_log_f32_e32 v158, v158
	s_nop 0
	v_mul_f32_e32 v160, 0x3f317217, v158
	v_fma_f32 v160, v158, s48, -v160
	v_fmac_f32_e32 v160, 0x3377d1cf, v158
	v_fmac_f32_e32 v160, 0x3f317217, v158
	v_cmp_lt_f32_e64 s[0:1], |v158|, s49
	s_nop 1
	v_cndmask_b32_e64 v158, v158, v160, s[0:1]
	v_cndmask_b32_e32 v160, 0, v233, vcc
	v_sub_f32_e32 v158, v158, v160
	v_sub_f32_e32 v158, v159, v158
	v_mul_f32_e32 v181, 0x3d800000, v158
	v_fmac_f32_e32 v141, 0x3d800000, v158
	s_waitcnt lgkmcnt(0)
	v_mul_f32_e32 v158, v5, v183
	v_fmac_f32_e32 v158, v4, v182
	v_fmac_f32_e32 v158, v6, v184
	v_fmac_f32_e32 v158, v7, v185
	ds_read_b128 v[182:185], v9 offset:1168
	v_add_f32_e32 v158, v157, v158
	s_waitcnt lgkmcnt(0)
	v_mul_f32_e32 v159, v154, v183
	v_fmac_f32_e32 v159, v228, v182
	v_fmac_f32_e32 v159, v155, v184
	v_fmac_f32_e32 v159, v156, v185
	ds_read_b128 v[182:185], v9 offset:1184
	v_add_f32_e32 v158, v158, v159
	s_waitcnt lgkmcnt(0)
	v_mul_f32_e32 v159, v252, v183
	v_fmac_f32_e32 v159, v146, v182
	v_fmac_f32_e32 v159, v253, v184
	v_fmac_f32_e32 v159, v227, v185
	ds_read_b128 v[182:185], v9 offset:1200
	v_add_f32_e32 v158, v158, v159
	s_waitcnt lgkmcnt(0)
	v_mul_f32_e32 v159, v147, v183
	v_fmac_f32_e32 v159, v145, v182
	v_fmac_f32_e32 v159, v230, v184
	v_fmac_f32_e32 v159, v231, v185
	v_add_f32_e32 v158, v158, v159
	v_min_f32_e32 v159, 0, v158
	v_mul_f32_e64 v158, |v158|, s18
	v_exp_f32_e32 v158, v158
	ds_read_b128 v[184:187], v9 offset:1280
	v_add_f32_e32 v158, 1.0, v158
	v_cmp_gt_f32_e32 vcc, s71, v158
	s_nop 1
	v_cndmask_b32_e64 v160, 0, 32, vcc
	v_ldexp_f32 v158, v158, v160
	v_log_f32_e32 v158, v158
	s_nop 0
	v_mul_f32_e32 v160, 0x3f317217, v158
	v_fma_f32 v160, v158, s48, -v160
	v_fmac_f32_e32 v160, 0x3377d1cf, v158
	v_fmac_f32_e32 v160, 0x3f317217, v158
	v_cmp_lt_f32_e64 s[0:1], |v158|, s49
	s_nop 1
	v_cndmask_b32_e64 v158, v158, v160, s[0:1]
	v_cndmask_b32_e32 v160, 0, v233, vcc
	v_sub_f32_e32 v158, v158, v160
	v_sub_f32_e32 v158, v159, v158
	v_mul_f32_e32 v182, 0x3d800000, v158
	v_fmac_f32_e32 v141, 0x3d800000, v158
	s_waitcnt lgkmcnt(0)
	v_mul_f32_e32 v158, v5, v185
	v_fmac_f32_e32 v158, v4, v184
	v_fmac_f32_e32 v158, v6, v186
	v_fmac_f32_e32 v158, v7, v187
	ds_read_b128 v[184:187], v9 offset:1296
	v_add_f32_e32 v158, v157, v158
	s_waitcnt lgkmcnt(0)
	v_mul_f32_e32 v159, v154, v185
	v_fmac_f32_e32 v159, v228, v184
	v_fmac_f32_e32 v159, v155, v186
	v_fmac_f32_e32 v159, v156, v187
	ds_read_b128 v[184:187], v9 offset:1312
	v_add_f32_e32 v158, v158, v159
	s_waitcnt lgkmcnt(0)
	v_mul_f32_e32 v159, v252, v185
	v_fmac_f32_e32 v159, v146, v184
	v_fmac_f32_e32 v159, v253, v186
	v_fmac_f32_e32 v159, v227, v187
	ds_read_b128 v[184:187], v9 offset:1328
	v_add_f32_e32 v158, v158, v159
	s_waitcnt lgkmcnt(0)
	v_mul_f32_e32 v159, v147, v185
	v_fmac_f32_e32 v159, v145, v184
	v_fmac_f32_e32 v159, v230, v186
	v_fmac_f32_e32 v159, v231, v187
	v_add_f32_e32 v158, v158, v159
	v_min_f32_e32 v159, 0, v158
	v_mul_f32_e64 v158, |v158|, s18
	v_exp_f32_e32 v158, v158
	ds_read_b128 v[184:187], v9 offset:1408
	v_add_f32_e32 v158, 1.0, v158
	v_cmp_gt_f32_e32 vcc, s71, v158
	s_nop 1
	v_cndmask_b32_e64 v160, 0, 32, vcc
	v_ldexp_f32 v158, v158, v160
	v_log_f32_e32 v158, v158
	s_nop 0
	v_mul_f32_e32 v160, 0x3f317217, v158
	v_fma_f32 v160, v158, s48, -v160
	v_fmac_f32_e32 v160, 0x3377d1cf, v158
	v_fmac_f32_e32 v160, 0x3f317217, v158
	v_cmp_lt_f32_e64 s[0:1], |v158|, s49
	s_nop 1
	v_cndmask_b32_e64 v158, v158, v160, s[0:1]
	v_cndmask_b32_e32 v160, 0, v233, vcc
	v_sub_f32_e32 v158, v158, v160
	v_sub_f32_e32 v158, v159, v158
	v_mul_f32_e32 v183, 0x3d800000, v158
	v_fmac_f32_e32 v141, 0x3d800000, v158
	s_waitcnt lgkmcnt(0)
	v_mul_f32_e32 v158, v5, v185
	v_fmac_f32_e32 v158, v4, v184
	v_fmac_f32_e32 v158, v6, v186
	v_fmac_f32_e32 v158, v7, v187
	ds_read_b128 v[184:187], v9 offset:1424
	v_add_f32_e32 v158, v157, v158
	s_waitcnt lgkmcnt(0)
	v_mul_f32_e32 v159, v154, v185
	v_fmac_f32_e32 v159, v228, v184
	v_fmac_f32_e32 v159, v155, v186
	v_fmac_f32_e32 v159, v156, v187
	ds_read_b128 v[184:187], v9 offset:1440
	v_add_f32_e32 v158, v158, v159
	s_waitcnt lgkmcnt(0)
	v_mul_f32_e32 v159, v252, v185
	v_fmac_f32_e32 v159, v146, v184
	v_fmac_f32_e32 v159, v253, v186
	v_fmac_f32_e32 v159, v227, v187
	ds_read_b128 v[184:187], v9 offset:1456
	v_add_f32_e32 v158, v158, v159
	s_waitcnt lgkmcnt(0)
	v_mul_f32_e32 v159, v147, v185
	v_fmac_f32_e32 v159, v145, v184
	v_fmac_f32_e32 v159, v230, v186
	v_fmac_f32_e32 v159, v231, v187
	v_add_f32_e32 v158, v158, v159
	v_min_f32_e32 v159, 0, v158
	v_mul_f32_e64 v158, |v158|, s18
	v_exp_f32_e32 v158, v158
	ds_read_b128 v[186:189], v9 offset:1536
	v_add_f32_e32 v158, 1.0, v158
	v_cmp_gt_f32_e32 vcc, s71, v158
	s_nop 1
	v_cndmask_b32_e64 v160, 0, 32, vcc
	v_ldexp_f32 v158, v158, v160
	v_log_f32_e32 v158, v158
	s_nop 0
	v_mul_f32_e32 v160, 0x3f317217, v158
	v_fma_f32 v160, v158, s48, -v160
	v_fmac_f32_e32 v160, 0x3377d1cf, v158
	v_fmac_f32_e32 v160, 0x3f317217, v158
	v_cmp_lt_f32_e64 s[0:1], |v158|, s49
	s_nop 1
	v_cndmask_b32_e64 v158, v158, v160, s[0:1]
	v_cndmask_b32_e32 v160, 0, v233, vcc
	v_sub_f32_e32 v158, v158, v160
	v_sub_f32_e32 v158, v159, v158
	v_mul_f32_e32 v184, 0x3d800000, v158
	v_fmac_f32_e32 v141, 0x3d800000, v158
	s_waitcnt lgkmcnt(0)
	v_mul_f32_e32 v158, v5, v187
	v_fmac_f32_e32 v158, v4, v186
	v_fmac_f32_e32 v158, v6, v188
	v_fmac_f32_e32 v158, v7, v189
	ds_read_b128 v[186:189], v9 offset:1552
	v_add_f32_e32 v158, v157, v158
	s_waitcnt lgkmcnt(0)
	v_mul_f32_e32 v159, v154, v187
	v_fmac_f32_e32 v159, v228, v186
	v_fmac_f32_e32 v159, v155, v188
	v_fmac_f32_e32 v159, v156, v189
	ds_read_b128 v[186:189], v9 offset:1568
	v_add_f32_e32 v158, v158, v159
	s_waitcnt lgkmcnt(0)
	v_mul_f32_e32 v159, v252, v187
	v_fmac_f32_e32 v159, v146, v186
	v_fmac_f32_e32 v159, v253, v188
	v_fmac_f32_e32 v159, v227, v189
	ds_read_b128 v[186:189], v9 offset:1584
	v_add_f32_e32 v158, v158, v159
	s_waitcnt lgkmcnt(0)
	v_mul_f32_e32 v159, v147, v187
	v_fmac_f32_e32 v159, v145, v186
	v_fmac_f32_e32 v159, v230, v188
	v_fmac_f32_e32 v159, v231, v189
	v_add_f32_e32 v158, v158, v159
	v_min_f32_e32 v159, 0, v158
	v_mul_f32_e64 v158, |v158|, s18
	v_exp_f32_e32 v158, v158
	ds_read_b128 v[186:189], v9 offset:1664
	v_add_f32_e32 v158, 1.0, v158
	v_cmp_gt_f32_e32 vcc, s71, v158
	s_nop 1
	v_cndmask_b32_e64 v160, 0, 32, vcc
	v_ldexp_f32 v158, v158, v160
	v_log_f32_e32 v158, v158
	s_nop 0
	v_mul_f32_e32 v160, 0x3f317217, v158
	v_fma_f32 v160, v158, s48, -v160
	v_fmac_f32_e32 v160, 0x3377d1cf, v158
	v_fmac_f32_e32 v160, 0x3f317217, v158
	v_cmp_lt_f32_e64 s[0:1], |v158|, s49
	s_nop 1
	v_cndmask_b32_e64 v158, v158, v160, s[0:1]
	v_cndmask_b32_e32 v160, 0, v233, vcc
	v_sub_f32_e32 v158, v158, v160
	v_sub_f32_e32 v158, v159, v158
	v_mul_f32_e32 v185, 0x3d800000, v158
	v_fmac_f32_e32 v141, 0x3d800000, v158
	s_waitcnt lgkmcnt(0)
	v_mul_f32_e32 v158, v5, v187
	v_fmac_f32_e32 v158, v4, v186
	v_fmac_f32_e32 v158, v6, v188
	v_fmac_f32_e32 v158, v7, v189
	ds_read_b128 v[186:189], v9 offset:1680
	v_add_f32_e32 v158, v157, v158
	s_waitcnt lgkmcnt(0)
	v_mul_f32_e32 v159, v154, v187
	v_fmac_f32_e32 v159, v228, v186
	v_fmac_f32_e32 v159, v155, v188
	v_fmac_f32_e32 v159, v156, v189
	ds_read_b128 v[186:189], v9 offset:1696
	v_add_f32_e32 v158, v158, v159
	s_waitcnt lgkmcnt(0)
	v_mul_f32_e32 v159, v252, v187
	v_fmac_f32_e32 v159, v146, v186
	v_fmac_f32_e32 v159, v253, v188
	v_fmac_f32_e32 v159, v227, v189
	ds_read_b128 v[186:189], v9 offset:1712
	v_add_f32_e32 v158, v158, v159
	s_waitcnt lgkmcnt(0)
	v_mul_f32_e32 v159, v147, v187
	v_fmac_f32_e32 v159, v145, v186
	v_fmac_f32_e32 v159, v230, v188
	v_fmac_f32_e32 v159, v231, v189
	v_add_f32_e32 v158, v158, v159
	v_min_f32_e32 v159, 0, v158
	v_mul_f32_e64 v158, |v158|, s18
	v_exp_f32_e32 v158, v158
	ds_read_b128 v[188:191], v9 offset:1792
	v_add_f32_e32 v158, 1.0, v158
	v_cmp_gt_f32_e32 vcc, s71, v158
	s_nop 1
	v_cndmask_b32_e64 v160, 0, 32, vcc
	v_ldexp_f32 v158, v158, v160
	v_log_f32_e32 v158, v158
	s_nop 0
	v_mul_f32_e32 v160, 0x3f317217, v158
	v_fma_f32 v160, v158, s48, -v160
	v_fmac_f32_e32 v160, 0x3377d1cf, v158
	v_fmac_f32_e32 v160, 0x3f317217, v158
	v_cmp_lt_f32_e64 s[0:1], |v158|, s49
	s_nop 1
	v_cndmask_b32_e64 v158, v158, v160, s[0:1]
	v_cndmask_b32_e32 v160, 0, v233, vcc
	v_sub_f32_e32 v158, v158, v160
	v_sub_f32_e32 v158, v159, v158
	v_mul_f32_e32 v186, 0x3d800000, v158
	v_fmac_f32_e32 v141, 0x3d800000, v158
	s_waitcnt lgkmcnt(0)
	v_mul_f32_e32 v158, v5, v189
	v_fmac_f32_e32 v158, v4, v188
	v_fmac_f32_e32 v158, v6, v190
	v_fmac_f32_e32 v158, v7, v191
	ds_read_b128 v[188:191], v9 offset:1808
	v_add_f32_e32 v158, v157, v158
	s_waitcnt lgkmcnt(0)
	v_mul_f32_e32 v159, v154, v189
	v_fmac_f32_e32 v159, v228, v188
	v_fmac_f32_e32 v159, v155, v190
	v_fmac_f32_e32 v159, v156, v191
	ds_read_b128 v[188:191], v9 offset:1824
	v_add_f32_e32 v158, v158, v159
	s_waitcnt lgkmcnt(0)
	v_mul_f32_e32 v159, v252, v189
	v_fmac_f32_e32 v159, v146, v188
	v_fmac_f32_e32 v159, v253, v190
	v_fmac_f32_e32 v159, v227, v191
	ds_read_b128 v[188:191], v9 offset:1840
	v_add_f32_e32 v158, v158, v159
	s_waitcnt lgkmcnt(0)
	v_mul_f32_e32 v159, v147, v189
	v_fmac_f32_e32 v159, v145, v188
	v_fmac_f32_e32 v159, v230, v190
	v_fmac_f32_e32 v159, v231, v191
	v_add_f32_e32 v158, v158, v159
	v_min_f32_e32 v159, 0, v158
	v_mul_f32_e64 v158, |v158|, s18
	v_exp_f32_e32 v158, v158
	ds_read_b128 v[188:191], v9 offset:1920
	v_add_f32_e32 v158, 1.0, v158
	v_cmp_gt_f32_e32 vcc, s71, v158
	s_nop 1
	v_cndmask_b32_e64 v160, 0, 32, vcc
	v_ldexp_f32 v158, v158, v160
	v_log_f32_e32 v158, v158
	s_nop 0
	v_mul_f32_e32 v160, 0x3f317217, v158
	v_fma_f32 v160, v158, s48, -v160
	v_fmac_f32_e32 v160, 0x3377d1cf, v158
	v_fmac_f32_e32 v160, 0x3f317217, v158
	v_cmp_lt_f32_e64 s[0:1], |v158|, s49
	s_nop 1
	v_cndmask_b32_e64 v158, v158, v160, s[0:1]
	v_cndmask_b32_e32 v160, 0, v233, vcc
	v_sub_f32_e32 v158, v158, v160
	v_sub_f32_e32 v158, v159, v158
	v_mul_f32_e32 v187, 0x3d800000, v158
	v_fmac_f32_e32 v141, 0x3d800000, v158
	s_waitcnt lgkmcnt(0)
	v_mul_f32_e32 v158, v5, v189
	v_fmac_f32_e32 v158, v4, v188
	v_fmac_f32_e32 v158, v6, v190
	v_fmac_f32_e32 v158, v7, v191
	ds_read_b128 v[188:191], v9 offset:1936
	v_add_f32_e32 v158, v157, v158
	s_waitcnt lgkmcnt(0)
	v_mul_f32_e32 v159, v154, v189
	v_fmac_f32_e32 v159, v228, v188
	v_fmac_f32_e32 v159, v155, v190
	v_fmac_f32_e32 v159, v156, v191
	ds_read_b128 v[188:191], v9 offset:1952
	v_add_f32_e32 v158, v158, v159
	s_waitcnt lgkmcnt(0)
	v_mul_f32_e32 v159, v252, v189
	v_fmac_f32_e32 v159, v146, v188
	v_fmac_f32_e32 v159, v253, v190
	v_fmac_f32_e32 v159, v227, v191
	ds_read_b128 v[188:191], v9 offset:1968
	v_add_f32_e32 v158, v158, v159
	s_waitcnt lgkmcnt(0)
	v_mul_f32_e32 v159, v147, v189
	v_fmac_f32_e32 v159, v145, v188
	v_fmac_f32_e32 v159, v230, v190
	v_fmac_f32_e32 v159, v231, v191
	v_add_f32_e32 v158, v158, v159
	v_min_f32_e32 v159, 0, v158
	v_mul_f32_e64 v158, |v158|, s18
	v_exp_f32_e32 v158, v158
	ds_read_b128 v[190:193], v9 offset:2048
	v_add_f32_e32 v158, 1.0, v158
	v_cmp_gt_f32_e32 vcc, s71, v158
	s_nop 1
	v_cndmask_b32_e64 v160, 0, 32, vcc
	v_ldexp_f32 v158, v158, v160
	v_log_f32_e32 v158, v158
	s_nop 0
	v_mul_f32_e32 v160, 0x3f317217, v158
	v_fma_f32 v160, v158, s48, -v160
	v_fmac_f32_e32 v160, 0x3377d1cf, v158
	v_fmac_f32_e32 v160, 0x3f317217, v158
	v_cmp_lt_f32_e64 s[0:1], |v158|, s49
	s_nop 1
	v_cndmask_b32_e64 v158, v158, v160, s[0:1]
	v_cndmask_b32_e32 v160, 0, v233, vcc
	v_sub_f32_e32 v158, v158, v160
	v_sub_f32_e32 v158, v159, v158
	v_mul_f32_e32 v188, 0x3d800000, v158
	v_fmac_f32_e32 v141, 0x3d800000, v158
	s_waitcnt lgkmcnt(0)
	v_mul_f32_e32 v158, v5, v191
	v_fmac_f32_e32 v158, v4, v190
	v_fmac_f32_e32 v158, v6, v192
	v_fmac_f32_e32 v158, v7, v193
	ds_read_b128 v[190:193], v9 offset:2064
	v_add_f32_e32 v158, v157, v158
	s_waitcnt lgkmcnt(0)
	v_mul_f32_e32 v159, v154, v191
	v_fmac_f32_e32 v159, v228, v190
	v_fmac_f32_e32 v159, v155, v192
	v_fmac_f32_e32 v159, v156, v193
	ds_read_b128 v[190:193], v9 offset:2080
	v_add_f32_e32 v158, v158, v159
	s_waitcnt lgkmcnt(0)
	v_mul_f32_e32 v159, v252, v191
	v_fmac_f32_e32 v159, v146, v190
	v_fmac_f32_e32 v159, v253, v192
	v_fmac_f32_e32 v159, v227, v193
	ds_read_b128 v[190:193], v9 offset:2096
	v_add_f32_e32 v158, v158, v159
	s_waitcnt lgkmcnt(0)
	v_mul_f32_e32 v159, v147, v191
	v_fmac_f32_e32 v159, v145, v190
	v_fmac_f32_e32 v159, v230, v192
	v_fmac_f32_e32 v159, v231, v193
	v_add_f32_e32 v158, v158, v159
	v_min_f32_e32 v159, 0, v158
	v_mul_f32_e64 v158, |v158|, s18
	v_exp_f32_e32 v158, v158
	ds_read_b128 v[190:193], v9 offset:2176
	v_add_f32_e32 v158, 1.0, v158
	v_cmp_gt_f32_e32 vcc, s71, v158
	s_nop 1
	v_cndmask_b32_e64 v160, 0, 32, vcc
	v_ldexp_f32 v158, v158, v160
	v_log_f32_e32 v158, v158
	s_nop 0
	v_mul_f32_e32 v160, 0x3f317217, v158
	v_fma_f32 v160, v158, s48, -v160
	v_fmac_f32_e32 v160, 0x3377d1cf, v158
	v_fmac_f32_e32 v160, 0x3f317217, v158
	v_cmp_lt_f32_e64 s[0:1], |v158|, s49
	s_nop 1
	v_cndmask_b32_e64 v158, v158, v160, s[0:1]
	v_cndmask_b32_e32 v160, 0, v233, vcc
	v_sub_f32_e32 v158, v158, v160
	v_sub_f32_e32 v158, v159, v158
	v_mul_f32_e32 v189, 0x3d800000, v158
	v_fmac_f32_e32 v141, 0x3d800000, v158
	s_waitcnt lgkmcnt(0)
	v_mul_f32_e32 v158, v5, v191
	v_fmac_f32_e32 v158, v4, v190
	v_fmac_f32_e32 v158, v6, v192
	v_fmac_f32_e32 v158, v7, v193
	ds_read_b128 v[190:193], v9 offset:2192
	v_add_f32_e32 v158, v157, v158
	s_waitcnt lgkmcnt(0)
	v_mul_f32_e32 v159, v154, v191
	v_fmac_f32_e32 v159, v228, v190
	v_fmac_f32_e32 v159, v155, v192
	v_fmac_f32_e32 v159, v156, v193
	ds_read_b128 v[190:193], v9 offset:2208
	v_add_f32_e32 v158, v158, v159
	s_waitcnt lgkmcnt(0)
	v_mul_f32_e32 v159, v252, v191
	v_fmac_f32_e32 v159, v146, v190
	v_fmac_f32_e32 v159, v253, v192
	v_fmac_f32_e32 v159, v227, v193
	ds_read_b128 v[190:193], v9 offset:2224
	v_add_f32_e32 v158, v158, v159
	s_waitcnt lgkmcnt(0)
	v_mul_f32_e32 v159, v147, v191
	v_fmac_f32_e32 v159, v145, v190
	v_fmac_f32_e32 v159, v230, v192
	v_fmac_f32_e32 v159, v231, v193
	v_add_f32_e32 v158, v158, v159
	v_min_f32_e32 v159, 0, v158
	v_mul_f32_e64 v158, |v158|, s18
	v_exp_f32_e32 v158, v158
	ds_read_b128 v[192:195], v9 offset:2304
	v_add_f32_e32 v158, 1.0, v158
	v_cmp_gt_f32_e32 vcc, s71, v158
	s_nop 1
	v_cndmask_b32_e64 v160, 0, 32, vcc
	v_ldexp_f32 v158, v158, v160
	v_log_f32_e32 v158, v158
	s_nop 0
	v_mul_f32_e32 v160, 0x3f317217, v158
	v_fma_f32 v160, v158, s48, -v160
	v_fmac_f32_e32 v160, 0x3377d1cf, v158
	v_fmac_f32_e32 v160, 0x3f317217, v158
	v_cmp_lt_f32_e64 s[0:1], |v158|, s49
	s_nop 1
	v_cndmask_b32_e64 v158, v158, v160, s[0:1]
	v_cndmask_b32_e32 v160, 0, v233, vcc
	v_sub_f32_e32 v158, v158, v160
	v_sub_f32_e32 v158, v159, v158
	v_mul_f32_e32 v190, 0x3d800000, v158
	v_fmac_f32_e32 v141, 0x3d800000, v158
	s_waitcnt lgkmcnt(0)
	v_mul_f32_e32 v158, v5, v193
	v_fmac_f32_e32 v158, v4, v192
	v_fmac_f32_e32 v158, v6, v194
	v_fmac_f32_e32 v158, v7, v195
	ds_read_b128 v[192:195], v9 offset:2320
	v_add_f32_e32 v158, v157, v158
	s_waitcnt lgkmcnt(0)
	v_mul_f32_e32 v159, v154, v193
	v_fmac_f32_e32 v159, v228, v192
	v_fmac_f32_e32 v159, v155, v194
	v_fmac_f32_e32 v159, v156, v195
	ds_read_b128 v[192:195], v9 offset:2336
	v_add_f32_e32 v158, v158, v159
	s_waitcnt lgkmcnt(0)
	v_mul_f32_e32 v159, v252, v193
	v_fmac_f32_e32 v159, v146, v192
	v_fmac_f32_e32 v159, v253, v194
	v_fmac_f32_e32 v159, v227, v195
	ds_read_b128 v[192:195], v9 offset:2352
	v_add_f32_e32 v158, v158, v159
	s_waitcnt lgkmcnt(0)
	v_mul_f32_e32 v159, v147, v193
	v_fmac_f32_e32 v159, v145, v192
	v_fmac_f32_e32 v159, v230, v194
	v_fmac_f32_e32 v159, v231, v195
	v_add_f32_e32 v158, v158, v159
	v_min_f32_e32 v159, 0, v158
	v_mul_f32_e64 v158, |v158|, s18
	v_exp_f32_e32 v158, v158
	ds_read_b128 v[192:195], v9 offset:2432
	v_add_f32_e32 v158, 1.0, v158
	v_cmp_gt_f32_e32 vcc, s71, v158
	s_nop 1
	v_cndmask_b32_e64 v160, 0, 32, vcc
	v_ldexp_f32 v158, v158, v160
	v_log_f32_e32 v158, v158
	s_nop 0
	v_mul_f32_e32 v160, 0x3f317217, v158
	v_fma_f32 v160, v158, s48, -v160
	v_fmac_f32_e32 v160, 0x3377d1cf, v158
	v_fmac_f32_e32 v160, 0x3f317217, v158
	v_cmp_lt_f32_e64 s[0:1], |v158|, s49
	s_nop 1
	v_cndmask_b32_e64 v158, v158, v160, s[0:1]
	v_cndmask_b32_e32 v160, 0, v233, vcc
	v_sub_f32_e32 v158, v158, v160
	v_sub_f32_e32 v158, v159, v158
	v_mul_f32_e32 v191, 0x3d800000, v158
	v_fmac_f32_e32 v141, 0x3d800000, v158
	s_waitcnt lgkmcnt(0)
	v_mul_f32_e32 v158, v5, v193
	v_fmac_f32_e32 v158, v4, v192
	v_fmac_f32_e32 v158, v6, v194
	v_fmac_f32_e32 v158, v7, v195
	ds_read_b128 v[192:195], v9 offset:2448
	v_add_f32_e32 v158, v157, v158
	s_waitcnt lgkmcnt(0)
	v_mul_f32_e32 v159, v154, v193
	v_fmac_f32_e32 v159, v228, v192
	v_fmac_f32_e32 v159, v155, v194
	v_fmac_f32_e32 v159, v156, v195
	ds_read_b128 v[192:195], v9 offset:2464
	v_add_f32_e32 v158, v158, v159
	s_waitcnt lgkmcnt(0)
	v_mul_f32_e32 v159, v252, v193
	v_fmac_f32_e32 v159, v146, v192
	v_fmac_f32_e32 v159, v253, v194
	v_fmac_f32_e32 v159, v227, v195
	ds_read_b128 v[192:195], v9 offset:2480
	v_add_f32_e32 v158, v158, v159
	s_waitcnt lgkmcnt(0)
	v_mul_f32_e32 v159, v147, v193
	v_fmac_f32_e32 v159, v145, v192
	v_fmac_f32_e32 v159, v230, v194
	v_fmac_f32_e32 v159, v231, v195
	v_add_f32_e32 v158, v158, v159
	v_min_f32_e32 v159, 0, v158
	v_mul_f32_e64 v158, |v158|, s18
	v_exp_f32_e32 v158, v158
	ds_read_b128 v[194:197], v9 offset:2560
	v_add_f32_e32 v158, 1.0, v158
	v_cmp_gt_f32_e32 vcc, s71, v158
	s_nop 1
	v_cndmask_b32_e64 v160, 0, 32, vcc
	v_ldexp_f32 v158, v158, v160
	v_log_f32_e32 v158, v158
	s_nop 0
	v_mul_f32_e32 v160, 0x3f317217, v158
	v_fma_f32 v160, v158, s48, -v160
	v_fmac_f32_e32 v160, 0x3377d1cf, v158
	v_fmac_f32_e32 v160, 0x3f317217, v158
	v_cmp_lt_f32_e64 s[0:1], |v158|, s49
	s_nop 1
	v_cndmask_b32_e64 v158, v158, v160, s[0:1]
	v_cndmask_b32_e32 v160, 0, v233, vcc
	v_sub_f32_e32 v158, v158, v160
	v_sub_f32_e32 v158, v159, v158
	v_mul_f32_e32 v192, 0x3d800000, v158
	v_fmac_f32_e32 v141, 0x3d800000, v158
	s_waitcnt lgkmcnt(0)
	v_mul_f32_e32 v158, v5, v195
	v_fmac_f32_e32 v158, v4, v194
	v_fmac_f32_e32 v158, v6, v196
	v_fmac_f32_e32 v158, v7, v197
	ds_read_b128 v[194:197], v9 offset:2576
	v_add_f32_e32 v158, v157, v158
	s_waitcnt lgkmcnt(0)
	v_mul_f32_e32 v159, v154, v195
	v_fmac_f32_e32 v159, v228, v194
	v_fmac_f32_e32 v159, v155, v196
	v_fmac_f32_e32 v159, v156, v197
	ds_read_b128 v[194:197], v9 offset:2592
	v_add_f32_e32 v158, v158, v159
	s_waitcnt lgkmcnt(0)
	v_mul_f32_e32 v159, v252, v195
	v_fmac_f32_e32 v159, v146, v194
	v_fmac_f32_e32 v159, v253, v196
	v_fmac_f32_e32 v159, v227, v197
	ds_read_b128 v[194:197], v9 offset:2608
	v_add_f32_e32 v158, v158, v159
	s_waitcnt lgkmcnt(0)
	v_mul_f32_e32 v159, v147, v195
	v_fmac_f32_e32 v159, v145, v194
	v_fmac_f32_e32 v159, v230, v196
	v_fmac_f32_e32 v159, v231, v197
	v_add_f32_e32 v158, v158, v159
	v_min_f32_e32 v159, 0, v158
	v_mul_f32_e64 v158, |v158|, s18
	v_exp_f32_e32 v158, v158
	ds_read_b128 v[194:197], v9 offset:2688
	v_add_f32_e32 v158, 1.0, v158
	v_cmp_gt_f32_e32 vcc, s71, v158
	s_nop 1
	v_cndmask_b32_e64 v160, 0, 32, vcc
	v_ldexp_f32 v158, v158, v160
	v_log_f32_e32 v158, v158
	s_nop 0
	v_mul_f32_e32 v160, 0x3f317217, v158
	v_fma_f32 v160, v158, s48, -v160
	v_fmac_f32_e32 v160, 0x3377d1cf, v158
	v_fmac_f32_e32 v160, 0x3f317217, v158
	v_cmp_lt_f32_e64 s[0:1], |v158|, s49
	s_nop 1
	v_cndmask_b32_e64 v158, v158, v160, s[0:1]
	v_cndmask_b32_e32 v160, 0, v233, vcc
	v_sub_f32_e32 v158, v158, v160
	v_sub_f32_e32 v158, v159, v158
	v_mul_f32_e32 v193, 0x3d800000, v158
	v_fmac_f32_e32 v141, 0x3d800000, v158
	s_waitcnt lgkmcnt(0)
	v_mul_f32_e32 v158, v5, v195
	v_fmac_f32_e32 v158, v4, v194
	v_fmac_f32_e32 v158, v6, v196
	v_fmac_f32_e32 v158, v7, v197
	ds_read_b128 v[194:197], v9 offset:2704
	v_add_f32_e32 v158, v157, v158
	s_waitcnt lgkmcnt(0)
	v_mul_f32_e32 v159, v154, v195
	v_fmac_f32_e32 v159, v228, v194
	v_fmac_f32_e32 v159, v155, v196
	v_fmac_f32_e32 v159, v156, v197
	ds_read_b128 v[194:197], v9 offset:2720
	v_add_f32_e32 v158, v158, v159
	s_waitcnt lgkmcnt(0)
	v_mul_f32_e32 v159, v252, v195
	v_fmac_f32_e32 v159, v146, v194
	v_fmac_f32_e32 v159, v253, v196
	v_fmac_f32_e32 v159, v227, v197
	ds_read_b128 v[194:197], v9 offset:2736
	v_add_f32_e32 v158, v158, v159
	s_waitcnt lgkmcnt(0)
	v_mul_f32_e32 v159, v147, v195
	v_fmac_f32_e32 v159, v145, v194
	v_fmac_f32_e32 v159, v230, v196
	v_fmac_f32_e32 v159, v231, v197
	v_add_f32_e32 v158, v158, v159
	v_min_f32_e32 v159, 0, v158
	v_mul_f32_e64 v158, |v158|, s18
	v_exp_f32_e32 v158, v158
	ds_read_b128 v[196:199], v9 offset:2816
	v_add_f32_e32 v158, 1.0, v158
	v_cmp_gt_f32_e32 vcc, s71, v158
	s_nop 1
	v_cndmask_b32_e64 v160, 0, 32, vcc
	v_ldexp_f32 v158, v158, v160
	v_log_f32_e32 v158, v158
	s_nop 0
	v_mul_f32_e32 v160, 0x3f317217, v158
	v_fma_f32 v160, v158, s48, -v160
	v_fmac_f32_e32 v160, 0x3377d1cf, v158
	v_fmac_f32_e32 v160, 0x3f317217, v158
	v_cmp_lt_f32_e64 s[0:1], |v158|, s49
	s_nop 1
	v_cndmask_b32_e64 v158, v158, v160, s[0:1]
	v_cndmask_b32_e32 v160, 0, v233, vcc
	v_sub_f32_e32 v158, v158, v160
	v_sub_f32_e32 v158, v159, v158
	v_mul_f32_e32 v194, 0x3d800000, v158
	v_fmac_f32_e32 v141, 0x3d800000, v158
	s_waitcnt lgkmcnt(0)
	v_mul_f32_e32 v158, v5, v197
	v_fmac_f32_e32 v158, v4, v196
	v_fmac_f32_e32 v158, v6, v198
	v_fmac_f32_e32 v158, v7, v199
	ds_read_b128 v[196:199], v9 offset:2832
	v_add_f32_e32 v158, v157, v158
	s_waitcnt lgkmcnt(0)
	v_mul_f32_e32 v159, v154, v197
	v_fmac_f32_e32 v159, v228, v196
	v_fmac_f32_e32 v159, v155, v198
	v_fmac_f32_e32 v159, v156, v199
	ds_read_b128 v[196:199], v9 offset:2848
	v_add_f32_e32 v158, v158, v159
	s_waitcnt lgkmcnt(0)
	v_mul_f32_e32 v159, v252, v197
	v_fmac_f32_e32 v159, v146, v196
	v_fmac_f32_e32 v159, v253, v198
	v_fmac_f32_e32 v159, v227, v199
	ds_read_b128 v[196:199], v9 offset:2864
	v_add_f32_e32 v158, v158, v159
	s_waitcnt lgkmcnt(0)
	v_mul_f32_e32 v159, v147, v197
	v_fmac_f32_e32 v159, v145, v196
	v_fmac_f32_e32 v159, v230, v198
	v_fmac_f32_e32 v159, v231, v199
	v_add_f32_e32 v158, v158, v159
	v_min_f32_e32 v159, 0, v158
	v_mul_f32_e64 v158, |v158|, s18
	v_exp_f32_e32 v158, v158
	ds_read_b128 v[196:199], v9 offset:2944
	v_add_f32_e32 v158, 1.0, v158
	v_cmp_gt_f32_e32 vcc, s71, v158
	s_nop 1
	v_cndmask_b32_e64 v160, 0, 32, vcc
	v_ldexp_f32 v158, v158, v160
	v_log_f32_e32 v158, v158
	s_nop 0
	v_mul_f32_e32 v160, 0x3f317217, v158
	v_fma_f32 v160, v158, s48, -v160
	v_fmac_f32_e32 v160, 0x3377d1cf, v158
	v_fmac_f32_e32 v160, 0x3f317217, v158
	v_cmp_lt_f32_e64 s[0:1], |v158|, s49
	s_nop 1
	v_cndmask_b32_e64 v158, v158, v160, s[0:1]
	v_cndmask_b32_e32 v160, 0, v233, vcc
	v_sub_f32_e32 v158, v158, v160
	v_sub_f32_e32 v158, v159, v158
	v_mul_f32_e32 v195, 0x3d800000, v158
	v_fmac_f32_e32 v141, 0x3d800000, v158
	s_waitcnt lgkmcnt(0)
	v_mul_f32_e32 v158, v5, v197
	v_fmac_f32_e32 v158, v4, v196
	v_fmac_f32_e32 v158, v6, v198
	v_fmac_f32_e32 v158, v7, v199
	ds_read_b128 v[196:199], v9 offset:2960
	v_add_f32_e32 v158, v157, v158
	s_waitcnt lgkmcnt(0)
	v_mul_f32_e32 v159, v154, v197
	v_fmac_f32_e32 v159, v228, v196
	v_fmac_f32_e32 v159, v155, v198
	v_fmac_f32_e32 v159, v156, v199
	ds_read_b128 v[196:199], v9 offset:2976
	v_add_f32_e32 v158, v158, v159
	s_waitcnt lgkmcnt(0)
	v_mul_f32_e32 v159, v252, v197
	v_fmac_f32_e32 v159, v146, v196
	v_fmac_f32_e32 v159, v253, v198
	v_fmac_f32_e32 v159, v227, v199
	ds_read_b128 v[196:199], v9 offset:2992
	v_add_f32_e32 v158, v158, v159
	s_waitcnt lgkmcnt(0)
	v_mul_f32_e32 v159, v147, v197
	v_fmac_f32_e32 v159, v145, v196
	v_fmac_f32_e32 v159, v230, v198
	v_fmac_f32_e32 v159, v231, v199
	v_add_f32_e32 v158, v158, v159
	v_min_f32_e32 v159, 0, v158
	v_mul_f32_e64 v158, |v158|, s18
	v_exp_f32_e32 v158, v158
	ds_read_b128 v[198:201], v9 offset:3072
	v_add_f32_e32 v158, 1.0, v158
	v_cmp_gt_f32_e32 vcc, s71, v158
	s_nop 1
	v_cndmask_b32_e64 v160, 0, 32, vcc
	v_ldexp_f32 v158, v158, v160
	v_log_f32_e32 v158, v158
	s_nop 0
	v_mul_f32_e32 v160, 0x3f317217, v158
	v_fma_f32 v160, v158, s48, -v160
	v_fmac_f32_e32 v160, 0x3377d1cf, v158
	v_fmac_f32_e32 v160, 0x3f317217, v158
	v_cmp_lt_f32_e64 s[0:1], |v158|, s49
	s_nop 1
	v_cndmask_b32_e64 v158, v158, v160, s[0:1]
	v_cndmask_b32_e32 v160, 0, v233, vcc
	v_sub_f32_e32 v158, v158, v160
	v_sub_f32_e32 v158, v159, v158
	v_mul_f32_e32 v196, 0x3d800000, v158
	v_fmac_f32_e32 v141, 0x3d800000, v158
	s_waitcnt lgkmcnt(0)
	v_mul_f32_e32 v158, v5, v199
	v_fmac_f32_e32 v158, v4, v198
	v_fmac_f32_e32 v158, v6, v200
	v_fmac_f32_e32 v158, v7, v201
	ds_read_b128 v[198:201], v9 offset:3088
	v_add_f32_e32 v158, v157, v158
	s_waitcnt lgkmcnt(0)
	v_mul_f32_e32 v159, v154, v199
	v_fmac_f32_e32 v159, v228, v198
	v_fmac_f32_e32 v159, v155, v200
	v_fmac_f32_e32 v159, v156, v201
	ds_read_b128 v[198:201], v9 offset:3104
	v_add_f32_e32 v158, v158, v159
	s_waitcnt lgkmcnt(0)
	v_mul_f32_e32 v159, v252, v199
	v_fmac_f32_e32 v159, v146, v198
	v_fmac_f32_e32 v159, v253, v200
	v_fmac_f32_e32 v159, v227, v201
	ds_read_b128 v[198:201], v9 offset:3120
	v_add_f32_e32 v158, v158, v159
	s_waitcnt lgkmcnt(0)
	v_mul_f32_e32 v159, v147, v199
	v_fmac_f32_e32 v159, v145, v198
	v_fmac_f32_e32 v159, v230, v200
	v_fmac_f32_e32 v159, v231, v201
	v_add_f32_e32 v158, v158, v159
	v_min_f32_e32 v159, 0, v158
	v_mul_f32_e64 v158, |v158|, s18
	v_exp_f32_e32 v158, v158
	ds_read_b128 v[198:201], v9 offset:3200
	v_add_f32_e32 v158, 1.0, v158
	v_cmp_gt_f32_e32 vcc, s71, v158
	s_nop 1
	v_cndmask_b32_e64 v160, 0, 32, vcc
	v_ldexp_f32 v158, v158, v160
	v_log_f32_e32 v158, v158
	s_nop 0
	v_mul_f32_e32 v160, 0x3f317217, v158
	v_fma_f32 v160, v158, s48, -v160
	v_fmac_f32_e32 v160, 0x3377d1cf, v158
	v_fmac_f32_e32 v160, 0x3f317217, v158
	v_cmp_lt_f32_e64 s[0:1], |v158|, s49
	s_nop 1
	v_cndmask_b32_e64 v158, v158, v160, s[0:1]
	v_cndmask_b32_e32 v160, 0, v233, vcc
	v_sub_f32_e32 v158, v158, v160
	v_sub_f32_e32 v158, v159, v158
	v_mul_f32_e32 v197, 0x3d800000, v158
	v_fmac_f32_e32 v141, 0x3d800000, v158
	s_waitcnt lgkmcnt(0)
	v_mul_f32_e32 v158, v5, v199
	v_fmac_f32_e32 v158, v4, v198
	v_fmac_f32_e32 v158, v6, v200
	v_fmac_f32_e32 v158, v7, v201
	ds_read_b128 v[198:201], v9 offset:3216
	v_add_f32_e32 v158, v157, v158
	s_waitcnt lgkmcnt(0)
	v_mul_f32_e32 v159, v154, v199
	v_fmac_f32_e32 v159, v228, v198
	v_fmac_f32_e32 v159, v155, v200
	v_fmac_f32_e32 v159, v156, v201
	ds_read_b128 v[198:201], v9 offset:3232
	v_add_f32_e32 v158, v158, v159
	s_waitcnt lgkmcnt(0)
	v_mul_f32_e32 v159, v252, v199
	v_fmac_f32_e32 v159, v146, v198
	v_fmac_f32_e32 v159, v253, v200
	v_fmac_f32_e32 v159, v227, v201
	ds_read_b128 v[198:201], v9 offset:3248
	v_add_f32_e32 v158, v158, v159
	s_waitcnt lgkmcnt(0)
	v_mul_f32_e32 v159, v147, v199
	v_fmac_f32_e32 v159, v145, v198
	v_fmac_f32_e32 v159, v230, v200
	v_fmac_f32_e32 v159, v231, v201
	v_add_f32_e32 v158, v158, v159
	v_min_f32_e32 v159, 0, v158
	v_mul_f32_e64 v158, |v158|, s18
	v_exp_f32_e32 v158, v158
	ds_read_b128 v[200:203], v9 offset:3328
	v_add_f32_e32 v158, 1.0, v158
	v_cmp_gt_f32_e32 vcc, s71, v158
	s_nop 1
	v_cndmask_b32_e64 v160, 0, 32, vcc
	v_ldexp_f32 v158, v158, v160
	v_log_f32_e32 v158, v158
	s_nop 0
	v_mul_f32_e32 v160, 0x3f317217, v158
	v_fma_f32 v160, v158, s48, -v160
	v_fmac_f32_e32 v160, 0x3377d1cf, v158
	v_fmac_f32_e32 v160, 0x3f317217, v158
	v_cmp_lt_f32_e64 s[0:1], |v158|, s49
	s_nop 1
	v_cndmask_b32_e64 v158, v158, v160, s[0:1]
	v_cndmask_b32_e32 v160, 0, v233, vcc
	v_sub_f32_e32 v158, v158, v160
	v_sub_f32_e32 v158, v159, v158
	v_mul_f32_e32 v198, 0x3d800000, v158
	v_fmac_f32_e32 v141, 0x3d800000, v158
	s_waitcnt lgkmcnt(0)
	v_mul_f32_e32 v158, v5, v201
	v_fmac_f32_e32 v158, v4, v200
	v_fmac_f32_e32 v158, v6, v202
	v_fmac_f32_e32 v158, v7, v203
	ds_read_b128 v[200:203], v9 offset:3344
	v_add_f32_e32 v158, v157, v158
	s_waitcnt lgkmcnt(0)
	v_mul_f32_e32 v159, v154, v201
	v_fmac_f32_e32 v159, v228, v200
	v_fmac_f32_e32 v159, v155, v202
	v_fmac_f32_e32 v159, v156, v203
	ds_read_b128 v[200:203], v9 offset:3360
	v_add_f32_e32 v158, v158, v159
	s_waitcnt lgkmcnt(0)
	v_mul_f32_e32 v159, v252, v201
	v_fmac_f32_e32 v159, v146, v200
	v_fmac_f32_e32 v159, v253, v202
	v_fmac_f32_e32 v159, v227, v203
	ds_read_b128 v[200:203], v9 offset:3376
	v_add_f32_e32 v158, v158, v159
	s_waitcnt lgkmcnt(0)
	v_mul_f32_e32 v159, v147, v201
	v_fmac_f32_e32 v159, v145, v200
	v_fmac_f32_e32 v159, v230, v202
	v_fmac_f32_e32 v159, v231, v203
	v_add_f32_e32 v158, v158, v159
	v_min_f32_e32 v159, 0, v158
	v_mul_f32_e64 v158, |v158|, s18
	v_exp_f32_e32 v158, v158
	ds_read_b128 v[200:203], v9 offset:3456
	v_add_f32_e32 v158, 1.0, v158
	v_cmp_gt_f32_e32 vcc, s71, v158
	s_nop 1
	v_cndmask_b32_e64 v160, 0, 32, vcc
	v_ldexp_f32 v158, v158, v160
	v_log_f32_e32 v158, v158
	s_nop 0
	v_mul_f32_e32 v160, 0x3f317217, v158
	v_fma_f32 v160, v158, s48, -v160
	v_fmac_f32_e32 v160, 0x3377d1cf, v158
	v_fmac_f32_e32 v160, 0x3f317217, v158
	v_cmp_lt_f32_e64 s[0:1], |v158|, s49
	s_nop 1
	v_cndmask_b32_e64 v158, v158, v160, s[0:1]
	v_cndmask_b32_e32 v160, 0, v233, vcc
	v_sub_f32_e32 v158, v158, v160
	v_sub_f32_e32 v158, v159, v158
	v_mul_f32_e32 v199, 0x3d800000, v158
	v_fmac_f32_e32 v141, 0x3d800000, v158
	s_waitcnt lgkmcnt(0)
	v_mul_f32_e32 v158, v5, v201
	v_fmac_f32_e32 v158, v4, v200
	v_fmac_f32_e32 v158, v6, v202
	v_fmac_f32_e32 v158, v7, v203
	ds_read_b128 v[200:203], v9 offset:3472
	v_add_f32_e32 v158, v157, v158
	s_waitcnt lgkmcnt(0)
	v_mul_f32_e32 v159, v154, v201
	v_fmac_f32_e32 v159, v228, v200
	v_fmac_f32_e32 v159, v155, v202
	v_fmac_f32_e32 v159, v156, v203
	ds_read_b128 v[200:203], v9 offset:3488
	v_add_f32_e32 v158, v158, v159
	s_waitcnt lgkmcnt(0)
	v_mul_f32_e32 v159, v252, v201
	v_fmac_f32_e32 v159, v146, v200
	v_fmac_f32_e32 v159, v253, v202
	v_fmac_f32_e32 v159, v227, v203
	ds_read_b128 v[200:203], v9 offset:3504
	v_add_f32_e32 v158, v158, v159
	s_waitcnt lgkmcnt(0)
	v_mul_f32_e32 v159, v147, v201
	v_fmac_f32_e32 v159, v145, v200
	v_fmac_f32_e32 v159, v230, v202
	v_fmac_f32_e32 v159, v231, v203
	v_add_f32_e32 v158, v158, v159
	v_min_f32_e32 v159, 0, v158
	v_mul_f32_e64 v158, |v158|, s18
	v_exp_f32_e32 v158, v158
	ds_read_b128 v[202:205], v9 offset:3584
	v_add_f32_e32 v158, 1.0, v158
	v_cmp_gt_f32_e32 vcc, s71, v158
	s_nop 1
	v_cndmask_b32_e64 v160, 0, 32, vcc
	v_ldexp_f32 v158, v158, v160
	v_log_f32_e32 v158, v158
	s_nop 0
	v_mul_f32_e32 v160, 0x3f317217, v158
	v_fma_f32 v160, v158, s48, -v160
	v_fmac_f32_e32 v160, 0x3377d1cf, v158
	v_fmac_f32_e32 v160, 0x3f317217, v158
	v_cmp_lt_f32_e64 s[0:1], |v158|, s49
	s_nop 1
	v_cndmask_b32_e64 v158, v158, v160, s[0:1]
	v_cndmask_b32_e32 v160, 0, v233, vcc
	v_sub_f32_e32 v158, v158, v160
	v_sub_f32_e32 v158, v159, v158
	v_mul_f32_e32 v200, 0x3d800000, v158
	v_fmac_f32_e32 v141, 0x3d800000, v158
	s_waitcnt lgkmcnt(0)
	v_mul_f32_e32 v158, v5, v203
	v_fmac_f32_e32 v158, v4, v202
	v_fmac_f32_e32 v158, v6, v204
	v_fmac_f32_e32 v158, v7, v205
	ds_read_b128 v[202:205], v9 offset:3600
	v_add_f32_e32 v158, v157, v158
	s_waitcnt lgkmcnt(0)
	v_mul_f32_e32 v159, v154, v203
	v_fmac_f32_e32 v159, v228, v202
	v_fmac_f32_e32 v159, v155, v204
	v_fmac_f32_e32 v159, v156, v205
	ds_read_b128 v[202:205], v9 offset:3616
	v_add_f32_e32 v158, v158, v159
	s_waitcnt lgkmcnt(0)
	v_mul_f32_e32 v159, v252, v203
	v_fmac_f32_e32 v159, v146, v202
	v_fmac_f32_e32 v159, v253, v204
	v_fmac_f32_e32 v159, v227, v205
	ds_read_b128 v[202:205], v9 offset:3632
	v_add_f32_e32 v158, v158, v159
	s_waitcnt lgkmcnt(0)
	v_mul_f32_e32 v159, v147, v203
	v_fmac_f32_e32 v159, v145, v202
	v_fmac_f32_e32 v159, v230, v204
	v_fmac_f32_e32 v159, v231, v205
	v_add_f32_e32 v158, v158, v159
	v_min_f32_e32 v159, 0, v158
	v_mul_f32_e64 v158, |v158|, s18
	v_exp_f32_e32 v158, v158
	ds_read_b128 v[202:205], v9 offset:3712
	v_add_f32_e32 v158, 1.0, v158
	v_cmp_gt_f32_e32 vcc, s71, v158
	s_nop 1
	v_cndmask_b32_e64 v160, 0, 32, vcc
	v_ldexp_f32 v158, v158, v160
	v_log_f32_e32 v158, v158
	s_nop 0
	v_mul_f32_e32 v160, 0x3f317217, v158
	v_fma_f32 v160, v158, s48, -v160
	v_fmac_f32_e32 v160, 0x3377d1cf, v158
	v_fmac_f32_e32 v160, 0x3f317217, v158
	v_cmp_lt_f32_e64 s[0:1], |v158|, s49
	s_nop 1
	v_cndmask_b32_e64 v158, v158, v160, s[0:1]
	v_cndmask_b32_e32 v160, 0, v233, vcc
	v_sub_f32_e32 v158, v158, v160
	v_sub_f32_e32 v158, v159, v158
	v_mul_f32_e32 v201, 0x3d800000, v158
	v_fmac_f32_e32 v141, 0x3d800000, v158
	s_waitcnt lgkmcnt(0)
	v_mul_f32_e32 v158, v5, v203
	v_fmac_f32_e32 v158, v4, v202
	v_fmac_f32_e32 v158, v6, v204
	v_fmac_f32_e32 v158, v7, v205
	ds_read_b128 v[202:205], v9 offset:3728
	v_add_f32_e32 v158, v157, v158
	s_waitcnt lgkmcnt(0)
	v_mul_f32_e32 v159, v154, v203
	v_fmac_f32_e32 v159, v228, v202
	v_fmac_f32_e32 v159, v155, v204
	v_fmac_f32_e32 v159, v156, v205
	ds_read_b128 v[202:205], v9 offset:3744
	v_add_f32_e32 v158, v158, v159
	s_waitcnt lgkmcnt(0)
	v_mul_f32_e32 v159, v252, v203
	v_fmac_f32_e32 v159, v146, v202
	v_fmac_f32_e32 v159, v253, v204
	v_fmac_f32_e32 v159, v227, v205
	ds_read_b128 v[202:205], v9 offset:3760
	v_add_f32_e32 v158, v158, v159
	s_waitcnt lgkmcnt(0)
	v_mul_f32_e32 v159, v147, v203
	v_fmac_f32_e32 v159, v145, v202
	v_fmac_f32_e32 v159, v230, v204
	v_fmac_f32_e32 v159, v231, v205
	v_add_f32_e32 v158, v158, v159
	v_min_f32_e32 v159, 0, v158
	v_mul_f32_e64 v158, |v158|, s18
	v_exp_f32_e32 v158, v158
	ds_read_b128 v[204:207], v9 offset:3840
	v_add_f32_e32 v158, 1.0, v158
	v_cmp_gt_f32_e32 vcc, s71, v158
	s_nop 1
	v_cndmask_b32_e64 v160, 0, 32, vcc
	v_ldexp_f32 v158, v158, v160
	v_log_f32_e32 v158, v158
	s_nop 0
	v_mul_f32_e32 v160, 0x3f317217, v158
	v_fma_f32 v160, v158, s48, -v160
	v_fmac_f32_e32 v160, 0x3377d1cf, v158
	v_fmac_f32_e32 v160, 0x3f317217, v158
	v_cmp_lt_f32_e64 s[0:1], |v158|, s49
	s_nop 1
	v_cndmask_b32_e64 v158, v158, v160, s[0:1]
	v_cndmask_b32_e32 v160, 0, v233, vcc
	v_sub_f32_e32 v158, v158, v160
	v_sub_f32_e32 v158, v159, v158
	v_mul_f32_e32 v202, 0x3d800000, v158
	v_fmac_f32_e32 v141, 0x3d800000, v158
	s_waitcnt lgkmcnt(0)
	v_mul_f32_e32 v158, v5, v205
	v_fmac_f32_e32 v158, v4, v204
	v_fmac_f32_e32 v158, v6, v206
	v_fmac_f32_e32 v158, v7, v207
	ds_read_b128 v[204:207], v9 offset:3856
	v_add_f32_e32 v158, v157, v158
	s_waitcnt lgkmcnt(0)
	v_mul_f32_e32 v159, v154, v205
	v_fmac_f32_e32 v159, v228, v204
	v_fmac_f32_e32 v159, v155, v206
	v_fmac_f32_e32 v159, v156, v207
	ds_read_b128 v[204:207], v9 offset:3872
	v_add_f32_e32 v158, v158, v159
	s_waitcnt lgkmcnt(0)
	v_mul_f32_e32 v159, v252, v205
	v_fmac_f32_e32 v159, v146, v204
	v_fmac_f32_e32 v159, v253, v206
	v_fmac_f32_e32 v159, v227, v207
	ds_read_b128 v[204:207], v9 offset:3888
	v_add_f32_e32 v158, v158, v159
	s_waitcnt lgkmcnt(0)
	v_mul_f32_e32 v159, v147, v205
	v_fmac_f32_e32 v159, v145, v204
	v_fmac_f32_e32 v159, v230, v206
	v_fmac_f32_e32 v159, v231, v207
	v_add_f32_e32 v158, v158, v159
	v_min_f32_e32 v159, 0, v158
	v_mul_f32_e64 v158, |v158|, s18
	v_exp_f32_e32 v158, v158
	ds_read_b128 v[204:207], v9 offset:3968
	v_add_f32_e32 v158, 1.0, v158
	v_cmp_gt_f32_e32 vcc, s71, v158
	s_nop 1
	v_cndmask_b32_e64 v160, 0, 32, vcc
	v_ldexp_f32 v158, v158, v160
	v_log_f32_e32 v158, v158
	s_nop 0
	v_mul_f32_e32 v160, 0x3f317217, v158
	v_fma_f32 v160, v158, s48, -v160
	v_fmac_f32_e32 v160, 0x3377d1cf, v158
	v_fmac_f32_e32 v160, 0x3f317217, v158
	v_cmp_lt_f32_e64 s[0:1], |v158|, s49
	s_nop 1
	v_cndmask_b32_e64 v158, v158, v160, s[0:1]
	v_cndmask_b32_e32 v160, 0, v233, vcc
	v_sub_f32_e32 v158, v158, v160
	v_sub_f32_e32 v158, v159, v158
	v_mul_f32_e32 v203, 0x3d800000, v158
	v_fmac_f32_e32 v141, 0x3d800000, v158
	s_waitcnt lgkmcnt(0)
	v_mul_f32_e32 v158, v5, v205
	v_fmac_f32_e32 v158, v4, v204
	v_fmac_f32_e32 v158, v6, v206
	v_fmac_f32_e32 v158, v7, v207
	ds_read_b128 v[204:207], v9 offset:3984
	v_add_f32_e32 v158, v157, v158
	s_waitcnt lgkmcnt(0)
	v_mul_f32_e32 v159, v154, v205
	v_fmac_f32_e32 v159, v228, v204
	v_fmac_f32_e32 v159, v155, v206
	v_fmac_f32_e32 v159, v156, v207
	ds_read_b128 v[204:207], v9 offset:4000
	v_add_f32_e32 v158, v158, v159
	s_waitcnt lgkmcnt(0)
	v_mul_f32_e32 v159, v252, v205
	v_fmac_f32_e32 v159, v146, v204
	v_fmac_f32_e32 v159, v253, v206
	v_fmac_f32_e32 v159, v227, v207
	ds_read_b128 v[204:207], v9 offset:4016
	v_add_f32_e32 v158, v158, v159
	s_waitcnt lgkmcnt(0)
	v_mul_f32_e32 v159, v147, v205
	v_fmac_f32_e32 v159, v145, v204
	v_fmac_f32_e32 v159, v230, v206
	v_fmac_f32_e32 v159, v231, v207
	v_add_f32_e32 v158, v158, v159
	v_min_f32_e32 v159, 0, v158
	v_mul_f32_e64 v158, |v158|, s18
	v_exp_f32_e32 v158, v158
	ds_read_b128 v[206:209], v9 offset:4096
	v_add_f32_e32 v158, 1.0, v158
	v_cmp_gt_f32_e32 vcc, s71, v158
	s_nop 1
	v_cndmask_b32_e64 v160, 0, 32, vcc
	v_ldexp_f32 v158, v158, v160
	v_log_f32_e32 v158, v158
	s_nop 0
	v_mul_f32_e32 v160, 0x3f317217, v158
	v_fma_f32 v160, v158, s48, -v160
	v_fmac_f32_e32 v160, 0x3377d1cf, v158
	v_fmac_f32_e32 v160, 0x3f317217, v158
	v_cmp_lt_f32_e64 s[0:1], |v158|, s49
	s_nop 1
	v_cndmask_b32_e64 v158, v158, v160, s[0:1]
	v_cndmask_b32_e32 v160, 0, v233, vcc
	v_sub_f32_e32 v158, v158, v160
	v_sub_f32_e32 v158, v159, v158
	v_mul_f32_e32 v204, 0x3d800000, v158
	v_fmac_f32_e32 v141, 0x3d800000, v158
	s_waitcnt lgkmcnt(0)
	v_mul_f32_e32 v158, v5, v207
	v_fmac_f32_e32 v158, v4, v206
	v_fmac_f32_e32 v158, v6, v208
	v_fmac_f32_e32 v158, v7, v209
	ds_read_b128 v[206:209], v9 offset:4112
	v_add_f32_e32 v158, v157, v158
	s_waitcnt lgkmcnt(0)
	v_mul_f32_e32 v159, v154, v207
	v_fmac_f32_e32 v159, v228, v206
	v_fmac_f32_e32 v159, v155, v208
	v_fmac_f32_e32 v159, v156, v209
	ds_read_b128 v[206:209], v9 offset:4128
	v_add_f32_e32 v158, v158, v159
	s_waitcnt lgkmcnt(0)
	v_mul_f32_e32 v159, v252, v207
	v_fmac_f32_e32 v159, v146, v206
	v_fmac_f32_e32 v159, v253, v208
	v_fmac_f32_e32 v159, v227, v209
	ds_read_b128 v[206:209], v9 offset:4144
	v_add_f32_e32 v158, v158, v159
	s_waitcnt lgkmcnt(0)
	v_mul_f32_e32 v159, v147, v207
	v_fmac_f32_e32 v159, v145, v206
	v_fmac_f32_e32 v159, v230, v208
	v_fmac_f32_e32 v159, v231, v209
	v_add_f32_e32 v158, v158, v159
	v_min_f32_e32 v159, 0, v158
	v_mul_f32_e64 v158, |v158|, s18
	v_exp_f32_e32 v158, v158
	ds_read_b128 v[206:209], v9 offset:4224
	v_add_f32_e32 v158, 1.0, v158
	v_cmp_gt_f32_e32 vcc, s71, v158
	s_nop 1
	v_cndmask_b32_e64 v160, 0, 32, vcc
	v_ldexp_f32 v158, v158, v160
	v_log_f32_e32 v158, v158
	s_nop 0
	v_mul_f32_e32 v160, 0x3f317217, v158
	v_fma_f32 v160, v158, s48, -v160
	v_fmac_f32_e32 v160, 0x3377d1cf, v158
	v_fmac_f32_e32 v160, 0x3f317217, v158
	v_cmp_lt_f32_e64 s[0:1], |v158|, s49
	s_nop 1
	v_cndmask_b32_e64 v158, v158, v160, s[0:1]
	v_cndmask_b32_e32 v160, 0, v233, vcc
	v_sub_f32_e32 v158, v158, v160
	v_sub_f32_e32 v158, v159, v158
	v_mul_f32_e32 v205, 0x3d800000, v158
	v_fmac_f32_e32 v141, 0x3d800000, v158
	s_waitcnt lgkmcnt(0)
	v_mul_f32_e32 v158, v5, v207
	v_fmac_f32_e32 v158, v4, v206
	v_fmac_f32_e32 v158, v6, v208
	v_fmac_f32_e32 v158, v7, v209
	ds_read_b128 v[206:209], v9 offset:4240
	v_add_f32_e32 v158, v157, v158
	s_waitcnt lgkmcnt(0)
	v_mul_f32_e32 v159, v154, v207
	v_fmac_f32_e32 v159, v228, v206
	v_fmac_f32_e32 v159, v155, v208
	v_fmac_f32_e32 v159, v156, v209
	ds_read_b128 v[206:209], v9 offset:4256
	v_add_f32_e32 v158, v158, v159
	s_waitcnt lgkmcnt(0)
	v_mul_f32_e32 v159, v252, v207
	v_fmac_f32_e32 v159, v146, v206
	v_fmac_f32_e32 v159, v253, v208
	v_fmac_f32_e32 v159, v227, v209
	ds_read_b128 v[206:209], v9 offset:4272
	v_add_f32_e32 v158, v158, v159
	s_waitcnt lgkmcnt(0)
	v_mul_f32_e32 v159, v147, v207
	v_fmac_f32_e32 v159, v145, v206
	v_fmac_f32_e32 v159, v230, v208
	v_fmac_f32_e32 v159, v231, v209
	v_add_f32_e32 v158, v158, v159
	v_min_f32_e32 v159, 0, v158
	v_mul_f32_e64 v158, |v158|, s18
	v_exp_f32_e32 v158, v158
	ds_read_b128 v[208:211], v9 offset:4352
	v_add_f32_e32 v158, 1.0, v158
	v_cmp_gt_f32_e32 vcc, s71, v158
	s_nop 1
	v_cndmask_b32_e64 v160, 0, 32, vcc
	v_ldexp_f32 v158, v158, v160
	v_log_f32_e32 v158, v158
	s_nop 0
	v_mul_f32_e32 v160, 0x3f317217, v158
	v_fma_f32 v160, v158, s48, -v160
	v_fmac_f32_e32 v160, 0x3377d1cf, v158
	v_fmac_f32_e32 v160, 0x3f317217, v158
	v_cmp_lt_f32_e64 s[0:1], |v158|, s49
	s_nop 1
	v_cndmask_b32_e64 v158, v158, v160, s[0:1]
	v_cndmask_b32_e32 v160, 0, v233, vcc
	v_sub_f32_e32 v158, v158, v160
	v_sub_f32_e32 v158, v159, v158
	v_mul_f32_e32 v207, 0x3d800000, v158
	v_fmac_f32_e32 v141, 0x3d800000, v158
	s_waitcnt lgkmcnt(0)
	v_mul_f32_e32 v158, v5, v209
	v_fmac_f32_e32 v158, v4, v208
	v_fmac_f32_e32 v158, v6, v210
	v_fmac_f32_e32 v158, v7, v211
	ds_read_b128 v[208:211], v9 offset:4368
	v_add_f32_e32 v158, v157, v158
	s_waitcnt lgkmcnt(0)
	v_mul_f32_e32 v159, v154, v209
	v_fmac_f32_e32 v159, v228, v208
	v_fmac_f32_e32 v159, v155, v210
	v_fmac_f32_e32 v159, v156, v211
	ds_read_b128 v[208:211], v9 offset:4384
	v_add_f32_e32 v158, v158, v159
	s_waitcnt lgkmcnt(0)
	v_mul_f32_e32 v159, v252, v209
	v_fmac_f32_e32 v159, v146, v208
	v_fmac_f32_e32 v159, v253, v210
	v_fmac_f32_e32 v159, v227, v211
	ds_read_b128 v[208:211], v9 offset:4400
	v_add_f32_e32 v158, v158, v159
	s_waitcnt lgkmcnt(0)
	v_mul_f32_e32 v159, v147, v209
	v_fmac_f32_e32 v159, v145, v208
	v_fmac_f32_e32 v159, v230, v210
	v_fmac_f32_e32 v159, v231, v211
	v_add_f32_e32 v158, v158, v159
	v_min_f32_e32 v159, 0, v158
	v_mul_f32_e64 v158, |v158|, s18
	v_exp_f32_e32 v158, v158
	s_nop 0
	v_add_f32_e32 v158, 1.0, v158
	v_cmp_gt_f32_e32 vcc, s71, v158
	s_nop 1
	v_cndmask_b32_e64 v160, 0, 32, vcc
	v_ldexp_f32 v158, v158, v160
	v_log_f32_e32 v158, v158
	s_nop 0
	v_mul_f32_e32 v160, 0x3f317217, v158
	v_fma_f32 v160, v158, s48, -v160
	v_fmac_f32_e32 v160, 0x3377d1cf, v158
	v_fmac_f32_e32 v160, 0x3f317217, v158
	v_cmp_lt_f32_e64 s[0:1], |v158|, s49
	s_nop 1
	v_cndmask_b32_e64 v158, v158, v160, s[0:1]
	v_cndmask_b32_e32 v160, 0, v233, vcc
	v_sub_f32_e32 v158, v158, v160
	v_sub_f32_e32 v158, v159, v158
	v_mul_f32_e32 v210, 0x3d800000, v158
	v_fmac_f32_e32 v141, 0x3d800000, v158
	v_mul_f32_e32 v158, v5, v213
	v_fmac_f32_e32 v158, v4, v212
	v_fmac_f32_e32 v158, v6, v214
	v_fmac_f32_e32 v158, v7, v215
	ds_read_b128 v[212:215], v9 offset:4496
	v_add_f32_e32 v158, v157, v158
	s_waitcnt lgkmcnt(0)
	v_mul_f32_e32 v159, v154, v213
	v_fmac_f32_e32 v159, v228, v212
	v_fmac_f32_e32 v159, v155, v214
	v_fmac_f32_e32 v159, v156, v215
	ds_read_b128 v[212:215], v9 offset:4512
	v_add_f32_e32 v158, v158, v159
	s_waitcnt lgkmcnt(0)
	v_mul_f32_e32 v159, v252, v213
	v_fmac_f32_e32 v159, v146, v212
	v_fmac_f32_e32 v159, v253, v214
	v_fmac_f32_e32 v159, v227, v215
	ds_read_b128 v[212:215], v9 offset:4528
	v_add_f32_e32 v158, v158, v159
	s_waitcnt lgkmcnt(0)
	v_mul_f32_e32 v159, v147, v213
	v_fmac_f32_e32 v159, v145, v212
	v_fmac_f32_e32 v159, v230, v214
	v_fmac_f32_e32 v159, v231, v215
	v_add_f32_e32 v158, v158, v159
	v_min_f32_e32 v159, 0, v158
	v_mul_f32_e64 v158, |v158|, s18
	v_exp_f32_e32 v158, v158
	ds_read_b128 v[214:217], v9 offset:4608
	v_add_f32_e32 v158, 1.0, v158
	v_cmp_gt_f32_e32 vcc, s71, v158
	s_nop 1
	v_cndmask_b32_e64 v160, 0, 32, vcc
	v_ldexp_f32 v158, v158, v160
	v_log_f32_e32 v158, v158
	s_nop 0
	v_mul_f32_e32 v160, 0x3f317217, v158
	v_fma_f32 v160, v158, s48, -v160
	v_fmac_f32_e32 v160, 0x3377d1cf, v158
	v_fmac_f32_e32 v160, 0x3f317217, v158
	v_cmp_lt_f32_e64 s[0:1], |v158|, s49
	s_nop 1
	v_cndmask_b32_e64 v158, v158, v160, s[0:1]
	v_cndmask_b32_e32 v160, 0, v233, vcc
	v_sub_f32_e32 v158, v158, v160
	v_sub_f32_e32 v158, v159, v158
	v_mul_f32_e32 v212, 0x3d800000, v158
	v_fmac_f32_e32 v141, 0x3d800000, v158
	s_waitcnt lgkmcnt(0)
	v_mul_f32_e32 v158, v5, v215
	v_fmac_f32_e32 v158, v4, v214
	v_fmac_f32_e32 v158, v6, v216
	v_fmac_f32_e32 v158, v7, v217
	ds_read_b128 v[214:217], v9 offset:4624
	v_add_f32_e32 v158, v157, v158
	s_waitcnt lgkmcnt(0)
	v_mul_f32_e32 v159, v154, v215
	v_fmac_f32_e32 v159, v228, v214
	v_fmac_f32_e32 v159, v155, v216
	v_fmac_f32_e32 v159, v156, v217
	ds_read_b128 v[214:217], v9 offset:4640
	v_add_f32_e32 v158, v158, v159
	s_waitcnt lgkmcnt(0)
	v_mul_f32_e32 v159, v252, v215
	v_fmac_f32_e32 v159, v146, v214
	v_fmac_f32_e32 v159, v253, v216
	v_fmac_f32_e32 v159, v227, v217
	ds_read_b128 v[214:217], v9 offset:4656
	v_add_f32_e32 v158, v158, v159
	s_waitcnt lgkmcnt(0)
	v_mul_f32_e32 v159, v147, v215
	v_fmac_f32_e32 v159, v145, v214
	v_fmac_f32_e32 v159, v230, v216
	v_fmac_f32_e32 v159, v231, v217
	v_add_f32_e32 v158, v158, v159
	v_min_f32_e32 v159, 0, v158
	v_mul_f32_e64 v158, |v158|, s18
	v_exp_f32_e32 v158, v158
	ds_read_b128 v[214:217], v9 offset:4736
	v_add_f32_e32 v158, 1.0, v158
	v_cmp_gt_f32_e32 vcc, s71, v158
	s_nop 1
	v_cndmask_b32_e64 v160, 0, 32, vcc
	v_ldexp_f32 v158, v158, v160
	v_log_f32_e32 v158, v158
	s_nop 0
	v_mul_f32_e32 v160, 0x3f317217, v158
	v_fma_f32 v160, v158, s48, -v160
	v_fmac_f32_e32 v160, 0x3377d1cf, v158
	v_fmac_f32_e32 v160, 0x3f317217, v158
	v_cmp_lt_f32_e64 s[0:1], |v158|, s49
	s_nop 1
	v_cndmask_b32_e64 v158, v158, v160, s[0:1]
	v_cndmask_b32_e32 v160, 0, v233, vcc
	v_sub_f32_e32 v158, v158, v160
	v_sub_f32_e32 v158, v159, v158
	v_mul_f32_e32 v206, 0x3d800000, v158
	v_fmac_f32_e32 v141, 0x3d800000, v158
	s_waitcnt lgkmcnt(0)
	v_mul_f32_e32 v158, v5, v215
	v_fmac_f32_e32 v158, v4, v214
	v_fmac_f32_e32 v158, v6, v216
	v_fmac_f32_e32 v158, v7, v217
	ds_read_b128 v[214:217], v9 offset:4752
	v_add_f32_e32 v158, v157, v158
	s_waitcnt lgkmcnt(0)
	v_mul_f32_e32 v159, v154, v215
	v_fmac_f32_e32 v159, v228, v214
	v_fmac_f32_e32 v159, v155, v216
	v_fmac_f32_e32 v159, v156, v217
	ds_read_b128 v[214:217], v9 offset:4768
	v_add_f32_e32 v158, v158, v159
	s_waitcnt lgkmcnt(0)
	v_mul_f32_e32 v159, v252, v215
	v_fmac_f32_e32 v159, v146, v214
	v_fmac_f32_e32 v159, v253, v216
	v_fmac_f32_e32 v159, v227, v217
	ds_read_b128 v[214:217], v9 offset:4784
	v_add_f32_e32 v158, v158, v159
	s_waitcnt lgkmcnt(0)
	v_mul_f32_e32 v159, v147, v215
	v_fmac_f32_e32 v159, v145, v214
	v_fmac_f32_e32 v159, v230, v216
	v_fmac_f32_e32 v159, v231, v217
	v_add_f32_e32 v158, v158, v159
	v_min_f32_e32 v159, 0, v158
	v_mul_f32_e64 v158, |v158|, s18
	v_exp_f32_e32 v158, v158
	ds_read_b128 v[214:217], v9 offset:4864
	v_add_f32_e32 v158, 1.0, v158
	v_cmp_gt_f32_e32 vcc, s71, v158
	s_nop 1
	v_cndmask_b32_e64 v160, 0, 32, vcc
	v_ldexp_f32 v158, v158, v160
	v_log_f32_e32 v158, v158
	s_nop 0
	v_mul_f32_e32 v160, 0x3f317217, v158
	v_fma_f32 v160, v158, s48, -v160
	v_fmac_f32_e32 v160, 0x3377d1cf, v158
	v_fmac_f32_e32 v160, 0x3f317217, v158
	v_cmp_lt_f32_e64 s[0:1], |v158|, s49
	s_nop 1
	v_cndmask_b32_e64 v158, v158, v160, s[0:1]
	v_cndmask_b32_e32 v160, 0, v233, vcc
	v_sub_f32_e32 v158, v158, v160
	v_sub_f32_e32 v158, v159, v158
	v_mul_f32_e32 v209, 0x3d800000, v158
	v_fmac_f32_e32 v141, 0x3d800000, v158
	s_waitcnt lgkmcnt(0)
	v_mul_f32_e32 v158, v5, v215
	v_fmac_f32_e32 v158, v4, v214
	v_fmac_f32_e32 v158, v6, v216
	v_fmac_f32_e32 v158, v7, v217
	ds_read_b128 v[214:217], v9 offset:4880
	v_add_f32_e32 v158, v157, v158
	s_waitcnt lgkmcnt(0)
	v_mul_f32_e32 v159, v154, v215
	v_fmac_f32_e32 v159, v228, v214
	v_fmac_f32_e32 v159, v155, v216
	v_fmac_f32_e32 v159, v156, v217
	ds_read_b128 v[214:217], v9 offset:4896
	v_add_f32_e32 v158, v158, v159
	s_waitcnt lgkmcnt(0)
	v_mul_f32_e32 v159, v252, v215
	v_fmac_f32_e32 v159, v146, v214
	v_fmac_f32_e32 v159, v253, v216
	v_fmac_f32_e32 v159, v227, v217
	ds_read_b128 v[214:217], v9 offset:4912
	v_add_f32_e32 v158, v158, v159
	s_waitcnt lgkmcnt(0)
	v_mul_f32_e32 v159, v147, v215
	v_fmac_f32_e32 v159, v145, v214
	v_fmac_f32_e32 v159, v230, v216
	v_fmac_f32_e32 v159, v231, v217
	v_add_f32_e32 v158, v158, v159
	v_min_f32_e32 v159, 0, v158
	v_mul_f32_e64 v158, |v158|, s18
	v_exp_f32_e32 v158, v158
	s_nop 0
	v_add_f32_e32 v158, 1.0, v158
	v_cmp_gt_f32_e32 vcc, s71, v158
	s_nop 1
	v_cndmask_b32_e64 v160, 0, 32, vcc
	v_ldexp_f32 v158, v158, v160
	v_log_f32_e32 v158, v158
	s_nop 0
	v_mul_f32_e32 v160, 0x3f317217, v158
	v_fma_f32 v160, v158, s48, -v160
	v_fmac_f32_e32 v160, 0x3377d1cf, v158
	v_fmac_f32_e32 v160, 0x3f317217, v158
	v_cmp_lt_f32_e64 s[0:1], |v158|, s49
	s_nop 1
	v_cndmask_b32_e64 v158, v158, v160, s[0:1]
	v_cndmask_b32_e32 v160, 0, v233, vcc
	v_sub_f32_e32 v158, v158, v160
	v_sub_f32_e32 v158, v159, v158
	v_mul_f32_e32 v214, 0x3d800000, v158
	v_fmac_f32_e32 v141, 0x3d800000, v158
	v_mul_f32_e32 v158, v5, v235
	v_fmac_f32_e32 v158, v4, v234
	v_fmac_f32_e32 v158, v6, v236
	v_fmac_f32_e32 v158, v7, v237
	ds_read_b128 v[234:237], v9 offset:5008
	v_add_f32_e32 v158, v157, v158
	s_waitcnt lgkmcnt(0)
	v_mul_f32_e32 v159, v154, v235
	v_fmac_f32_e32 v159, v228, v234
	v_fmac_f32_e32 v159, v155, v236
	v_fmac_f32_e32 v159, v156, v237
	ds_read_b128 v[234:237], v9 offset:5024
	v_add_f32_e32 v158, v158, v159
	s_waitcnt lgkmcnt(0)
	v_mul_f32_e32 v159, v252, v235
	v_fmac_f32_e32 v159, v146, v234
	v_fmac_f32_e32 v159, v253, v236
	v_fmac_f32_e32 v159, v227, v237
	ds_read_b128 v[234:237], v9 offset:5040
	v_add_f32_e32 v158, v158, v159
	s_waitcnt lgkmcnt(0)
	v_mul_f32_e32 v159, v147, v235
	v_fmac_f32_e32 v159, v145, v234
	v_fmac_f32_e32 v159, v230, v236
	v_fmac_f32_e32 v159, v231, v237
	v_add_f32_e32 v158, v158, v159
	v_min_f32_e32 v159, 0, v158
	v_mul_f32_e64 v158, |v158|, s18
	v_exp_f32_e32 v158, v158
	ds_read_b128 v[234:237], v9 offset:5120
	v_add_f32_e32 v158, 1.0, v158
	v_cmp_gt_f32_e32 vcc, s71, v158
	s_nop 1
	v_cndmask_b32_e64 v160, 0, 32, vcc
	v_ldexp_f32 v158, v158, v160
	v_log_f32_e32 v158, v158
	s_nop 0
	v_mul_f32_e32 v160, 0x3f317217, v158
	v_fma_f32 v160, v158, s48, -v160
	v_fmac_f32_e32 v160, 0x3377d1cf, v158
	v_fmac_f32_e32 v160, 0x3f317217, v158
	v_cmp_lt_f32_e64 s[0:1], |v158|, s49
	s_nop 1
	v_cndmask_b32_e64 v158, v158, v160, s[0:1]
	v_cndmask_b32_e32 v160, 0, v233, vcc
	v_sub_f32_e32 v158, v158, v160
	v_sub_f32_e32 v158, v159, v158
	v_mul_f32_e32 v216, 0x3d800000, v158
	v_fmac_f32_e32 v141, 0x3d800000, v158
	s_waitcnt lgkmcnt(0)
	v_mul_f32_e32 v158, v5, v235
	v_fmac_f32_e32 v158, v4, v234
	v_fmac_f32_e32 v158, v6, v236
	v_fmac_f32_e32 v158, v7, v237
	ds_read_b128 v[234:237], v9 offset:5136
	v_add_f32_e32 v158, v157, v158
	s_waitcnt lgkmcnt(0)
	v_mul_f32_e32 v159, v154, v235
	v_fmac_f32_e32 v159, v228, v234
	v_fmac_f32_e32 v159, v155, v236
	v_fmac_f32_e32 v159, v156, v237
	ds_read_b128 v[234:237], v9 offset:5152
	v_add_f32_e32 v158, v158, v159
	s_waitcnt lgkmcnt(0)
	v_mul_f32_e32 v159, v252, v235
	v_fmac_f32_e32 v159, v146, v234
	v_fmac_f32_e32 v159, v253, v236
	v_fmac_f32_e32 v159, v227, v237
	ds_read_b128 v[234:237], v9 offset:5168
	v_add_f32_e32 v158, v158, v159
	s_waitcnt lgkmcnt(0)
	v_mul_f32_e32 v159, v147, v235
	v_fmac_f32_e32 v159, v145, v234
	v_fmac_f32_e32 v159, v230, v236
	v_fmac_f32_e32 v159, v231, v237
	v_add_f32_e32 v158, v158, v159
	v_min_f32_e32 v159, 0, v158
	v_mul_f32_e64 v158, |v158|, s18
	v_exp_f32_e32 v158, v158
	ds_read_b128 v[234:237], v9 offset:5248
	v_add_f32_e32 v158, 1.0, v158
	v_cmp_gt_f32_e32 vcc, s71, v158
	s_nop 1
	v_cndmask_b32_e64 v160, 0, 32, vcc
	v_ldexp_f32 v158, v158, v160
	v_log_f32_e32 v158, v158
	s_nop 0
	v_mul_f32_e32 v160, 0x3f317217, v158
	v_fma_f32 v160, v158, s48, -v160
	v_fmac_f32_e32 v160, 0x3377d1cf, v158
	v_fmac_f32_e32 v160, 0x3f317217, v158
	v_cmp_lt_f32_e64 s[0:1], |v158|, s49
	s_nop 1
	v_cndmask_b32_e64 v158, v158, v160, s[0:1]
	v_cndmask_b32_e32 v160, 0, v233, vcc
	v_sub_f32_e32 v158, v158, v160
	v_sub_f32_e32 v158, v159, v158
	v_mul_f32_e32 v208, 0x3d800000, v158
	v_fmac_f32_e32 v141, 0x3d800000, v158
	s_waitcnt lgkmcnt(0)
	v_mul_f32_e32 v158, v5, v235
	v_fmac_f32_e32 v158, v4, v234
	v_fmac_f32_e32 v158, v6, v236
	v_fmac_f32_e32 v158, v7, v237
	ds_read_b128 v[234:237], v9 offset:5264
	v_add_f32_e32 v158, v157, v158
	s_waitcnt lgkmcnt(0)
	v_mul_f32_e32 v159, v154, v235
	v_fmac_f32_e32 v159, v228, v234
	v_fmac_f32_e32 v159, v155, v236
	v_fmac_f32_e32 v159, v156, v237
	ds_read_b128 v[234:237], v9 offset:5280
	v_add_f32_e32 v158, v158, v159
	s_waitcnt lgkmcnt(0)
	v_mul_f32_e32 v159, v252, v235
	v_fmac_f32_e32 v159, v146, v234
	v_fmac_f32_e32 v159, v253, v236
	v_fmac_f32_e32 v159, v227, v237
	ds_read_b128 v[234:237], v9 offset:5296
	v_add_f32_e32 v158, v158, v159
	s_waitcnt lgkmcnt(0)
	v_mul_f32_e32 v159, v147, v235
	v_fmac_f32_e32 v159, v145, v234
	v_fmac_f32_e32 v159, v230, v236
	v_fmac_f32_e32 v159, v231, v237
	v_add_f32_e32 v158, v158, v159
	v_min_f32_e32 v159, 0, v158
	v_mul_f32_e64 v158, |v158|, s18
	v_exp_f32_e32 v158, v158
	ds_read_b128 v[234:237], v9 offset:5376
	v_add_f32_e32 v158, 1.0, v158
	v_cmp_gt_f32_e32 vcc, s71, v158
	s_nop 1
	v_cndmask_b32_e64 v160, 0, 32, vcc
	v_ldexp_f32 v158, v158, v160
	v_log_f32_e32 v158, v158
	s_nop 0
	v_mul_f32_e32 v160, 0x3f317217, v158
	v_fma_f32 v160, v158, s48, -v160
	v_fmac_f32_e32 v160, 0x3377d1cf, v158
	v_fmac_f32_e32 v160, 0x3f317217, v158
	v_cmp_lt_f32_e64 s[0:1], |v158|, s49
	s_nop 1
	v_cndmask_b32_e64 v158, v158, v160, s[0:1]
	v_cndmask_b32_e32 v160, 0, v233, vcc
	v_sub_f32_e32 v158, v158, v160
	v_sub_f32_e32 v158, v159, v158
	v_mul_f32_e32 v213, 0x3d800000, v158
	v_fmac_f32_e32 v141, 0x3d800000, v158
	s_waitcnt lgkmcnt(0)
	v_mul_f32_e32 v158, v5, v235
	v_fmac_f32_e32 v158, v4, v234
	v_fmac_f32_e32 v158, v6, v236
	v_fmac_f32_e32 v158, v7, v237
	ds_read_b128 v[234:237], v9 offset:5392
	v_add_f32_e32 v158, v157, v158
	s_waitcnt lgkmcnt(0)
	v_mul_f32_e32 v159, v154, v235
	v_fmac_f32_e32 v159, v228, v234
	v_fmac_f32_e32 v159, v155, v236
	v_fmac_f32_e32 v159, v156, v237
	ds_read_b128 v[234:237], v9 offset:5408
	v_add_f32_e32 v158, v158, v159
	s_waitcnt lgkmcnt(0)
	v_mul_f32_e32 v159, v252, v235
	v_fmac_f32_e32 v159, v146, v234
	v_fmac_f32_e32 v159, v253, v236
	v_fmac_f32_e32 v159, v227, v237
	ds_read_b128 v[234:237], v9 offset:5424
	v_add_f32_e32 v158, v158, v159
	s_waitcnt lgkmcnt(0)
	v_mul_f32_e32 v159, v147, v235
	v_fmac_f32_e32 v159, v145, v234
	v_fmac_f32_e32 v159, v230, v236
	v_fmac_f32_e32 v159, v231, v237
	v_add_f32_e32 v158, v158, v159
	v_min_f32_e32 v159, 0, v158
	v_mul_f32_e64 v158, |v158|, s18
	v_exp_f32_e32 v158, v158
	ds_read_b128 v[236:239], v9 offset:5504
	v_add_f32_e32 v158, 1.0, v158
	v_cmp_gt_f32_e32 vcc, s71, v158
	s_nop 1
	v_cndmask_b32_e64 v160, 0, 32, vcc
	v_ldexp_f32 v158, v158, v160
	v_log_f32_e32 v158, v158
	s_nop 0
	v_mul_f32_e32 v160, 0x3f317217, v158
	v_fma_f32 v160, v158, s48, -v160
	v_fmac_f32_e32 v160, 0x3377d1cf, v158
	v_fmac_f32_e32 v160, 0x3f317217, v158
	v_cmp_lt_f32_e64 s[0:1], |v158|, s49
	s_nop 1
	v_cndmask_b32_e64 v158, v158, v160, s[0:1]
	v_cndmask_b32_e32 v160, 0, v233, vcc
	v_sub_f32_e32 v158, v158, v160
	v_sub_f32_e32 v158, v159, v158
	v_mul_f32_e32 v234, 0x3d800000, v158
	v_fmac_f32_e32 v141, 0x3d800000, v158
	s_waitcnt lgkmcnt(0)
	v_mul_f32_e32 v158, v5, v237
	v_fmac_f32_e32 v158, v4, v236
	v_fmac_f32_e32 v158, v6, v238
	v_fmac_f32_e32 v158, v7, v239
	ds_read_b128 v[236:239], v9 offset:5520
	v_add_f32_e32 v158, v157, v158
	s_waitcnt lgkmcnt(0)
	v_mul_f32_e32 v159, v154, v237
	v_fmac_f32_e32 v159, v228, v236
	v_fmac_f32_e32 v159, v155, v238
	v_fmac_f32_e32 v159, v156, v239
	ds_read_b128 v[236:239], v9 offset:5536
	v_add_f32_e32 v158, v158, v159
	s_waitcnt lgkmcnt(0)
	v_mul_f32_e32 v159, v252, v237
	v_fmac_f32_e32 v159, v146, v236
	v_fmac_f32_e32 v159, v253, v238
	v_fmac_f32_e32 v159, v227, v239
	ds_read_b128 v[236:239], v9 offset:5552
	v_add_f32_e32 v158, v158, v159
	s_waitcnt lgkmcnt(0)
	v_mul_f32_e32 v159, v147, v237
	v_fmac_f32_e32 v159, v145, v236
	v_fmac_f32_e32 v159, v230, v238
	v_fmac_f32_e32 v159, v231, v239
	v_add_f32_e32 v158, v158, v159
	v_min_f32_e32 v159, 0, v158
	v_mul_f32_e64 v158, |v158|, s18
	v_exp_f32_e32 v158, v158
	ds_read_b128 v[238:241], v9 offset:5632
	v_add_f32_e32 v158, 1.0, v158
	v_cmp_gt_f32_e32 vcc, s71, v158
	s_nop 1
	v_cndmask_b32_e64 v160, 0, 32, vcc
	v_ldexp_f32 v158, v158, v160
	v_log_f32_e32 v158, v158
	s_nop 0
	v_mul_f32_e32 v160, 0x3f317217, v158
	v_fma_f32 v160, v158, s48, -v160
	v_fmac_f32_e32 v160, 0x3377d1cf, v158
	v_fmac_f32_e32 v160, 0x3f317217, v158
	v_cmp_lt_f32_e64 s[0:1], |v158|, s49
	s_nop 1
	v_cndmask_b32_e64 v158, v158, v160, s[0:1]
	v_cndmask_b32_e32 v160, 0, v233, vcc
	v_sub_f32_e32 v158, v158, v160
	v_sub_f32_e32 v158, v159, v158
	v_mul_f32_e32 v236, 0x3d800000, v158
	v_fmac_f32_e32 v141, 0x3d800000, v158
	s_waitcnt lgkmcnt(0)
	v_mul_f32_e32 v158, v5, v239
	v_fmac_f32_e32 v158, v4, v238
	v_fmac_f32_e32 v158, v6, v240
	v_fmac_f32_e32 v158, v7, v241
	ds_read_b128 v[238:241], v9 offset:5648
	v_add_f32_e32 v158, v157, v158
	s_waitcnt lgkmcnt(0)
	v_mul_f32_e32 v159, v154, v239
	v_fmac_f32_e32 v159, v228, v238
	v_fmac_f32_e32 v159, v155, v240
	v_fmac_f32_e32 v159, v156, v241
	ds_read_b128 v[238:241], v9 offset:5664
	v_add_f32_e32 v158, v158, v159
	s_waitcnt lgkmcnt(0)
	v_mul_f32_e32 v159, v252, v239
	v_fmac_f32_e32 v159, v146, v238
	v_fmac_f32_e32 v159, v253, v240
	v_fmac_f32_e32 v159, v227, v241
	ds_read_b128 v[238:241], v9 offset:5680
	v_add_f32_e32 v158, v158, v159
	s_waitcnt lgkmcnt(0)
	v_mul_f32_e32 v159, v147, v239
	v_fmac_f32_e32 v159, v145, v238
	v_fmac_f32_e32 v159, v230, v240
	v_fmac_f32_e32 v159, v231, v241
	v_add_f32_e32 v158, v158, v159
	v_min_f32_e32 v159, 0, v158
	v_mul_f32_e64 v158, |v158|, s18
	v_exp_f32_e32 v158, v158
	ds_read_b128 v[238:241], v9 offset:5760
	v_add_f32_e32 v158, 1.0, v158
	v_cmp_gt_f32_e32 vcc, s71, v158
	s_nop 1
	v_cndmask_b32_e64 v160, 0, 32, vcc
	v_ldexp_f32 v158, v158, v160
	v_log_f32_e32 v158, v158
	s_nop 0
	v_mul_f32_e32 v160, 0x3f317217, v158
	v_fma_f32 v160, v158, s48, -v160
	v_fmac_f32_e32 v160, 0x3377d1cf, v158
	v_fmac_f32_e32 v160, 0x3f317217, v158
	v_cmp_lt_f32_e64 s[0:1], |v158|, s49
	s_nop 1
	v_cndmask_b32_e64 v158, v158, v160, s[0:1]
	v_cndmask_b32_e32 v160, 0, v233, vcc
	v_sub_f32_e32 v158, v158, v160
	v_sub_f32_e32 v158, v159, v158
	v_mul_f32_e32 v211, 0x3d800000, v158
	v_fmac_f32_e32 v141, 0x3d800000, v158
	s_waitcnt lgkmcnt(0)
	v_mul_f32_e32 v158, v5, v239
	v_fmac_f32_e32 v158, v4, v238
	v_fmac_f32_e32 v158, v6, v240
	v_fmac_f32_e32 v158, v7, v241
	ds_read_b128 v[238:241], v9 offset:5776
	v_add_f32_e32 v158, v157, v158
	s_waitcnt lgkmcnt(0)
	v_mul_f32_e32 v159, v154, v239
	v_fmac_f32_e32 v159, v228, v238
	v_fmac_f32_e32 v159, v155, v240
	v_fmac_f32_e32 v159, v156, v241
	ds_read_b128 v[238:241], v9 offset:5792
	v_add_f32_e32 v158, v158, v159
	s_waitcnt lgkmcnt(0)
	v_mul_f32_e32 v159, v252, v239
	v_fmac_f32_e32 v159, v146, v238
	v_fmac_f32_e32 v159, v253, v240
	v_fmac_f32_e32 v159, v227, v241
	ds_read_b128 v[238:241], v9 offset:5808
	v_add_f32_e32 v158, v158, v159
	s_waitcnt lgkmcnt(0)
	v_mul_f32_e32 v159, v147, v239
	v_fmac_f32_e32 v159, v145, v238
	v_fmac_f32_e32 v159, v230, v240
	v_fmac_f32_e32 v159, v231, v241
	v_add_f32_e32 v158, v158, v159
	v_min_f32_e32 v159, 0, v158
	v_mul_f32_e64 v158, |v158|, s18
	v_exp_f32_e32 v158, v158
	ds_read_b128 v[238:241], v9 offset:5888
	v_add_f32_e32 v158, 1.0, v158
	v_cmp_gt_f32_e32 vcc, s71, v158
	s_nop 1
	v_cndmask_b32_e64 v160, 0, 32, vcc
	v_ldexp_f32 v158, v158, v160
	v_log_f32_e32 v158, v158
	s_nop 0
	v_mul_f32_e32 v160, 0x3f317217, v158
	v_fma_f32 v160, v158, s48, -v160
	v_fmac_f32_e32 v160, 0x3377d1cf, v158
	v_fmac_f32_e32 v160, 0x3f317217, v158
	v_cmp_lt_f32_e64 s[0:1], |v158|, s49
	s_nop 1
	v_cndmask_b32_e64 v158, v158, v160, s[0:1]
	v_cndmask_b32_e32 v160, 0, v233, vcc
	v_sub_f32_e32 v158, v158, v160
	v_sub_f32_e32 v158, v159, v158
	v_mul_f32_e32 v217, 0x3d800000, v158
	v_fmac_f32_e32 v141, 0x3d800000, v158
	s_waitcnt lgkmcnt(0)
	v_mul_f32_e32 v158, v5, v239
	v_fmac_f32_e32 v158, v4, v238
	v_fmac_f32_e32 v158, v6, v240
	v_fmac_f32_e32 v158, v7, v241
	ds_read_b128 v[238:241], v9 offset:5904
	v_add_f32_e32 v158, v157, v158
	s_waitcnt lgkmcnt(0)
	v_mul_f32_e32 v159, v154, v239
	v_fmac_f32_e32 v159, v228, v238
	v_fmac_f32_e32 v159, v155, v240
	v_fmac_f32_e32 v159, v156, v241
	ds_read_b128 v[238:241], v9 offset:5920
	v_add_f32_e32 v158, v158, v159
	s_waitcnt lgkmcnt(0)
	v_mul_f32_e32 v159, v252, v239
	v_fmac_f32_e32 v159, v146, v238
	v_fmac_f32_e32 v159, v253, v240
	v_fmac_f32_e32 v159, v227, v241
	ds_read_b128 v[238:241], v9 offset:5936
	v_add_f32_e32 v158, v158, v159
	s_waitcnt lgkmcnt(0)
	v_mul_f32_e32 v159, v147, v239
	v_fmac_f32_e32 v159, v145, v238
	v_fmac_f32_e32 v159, v230, v240
	v_fmac_f32_e32 v159, v231, v241
	v_add_f32_e32 v158, v158, v159
	v_min_f32_e32 v159, 0, v158
	v_mul_f32_e64 v158, |v158|, s18
	v_exp_f32_e32 v158, v158
	ds_read_b128 v[240:243], v9 offset:6016
	v_add_f32_e32 v158, 1.0, v158
	v_cmp_gt_f32_e32 vcc, s71, v158
	s_nop 1
	v_cndmask_b32_e64 v160, 0, 32, vcc
	v_ldexp_f32 v158, v158, v160
	v_log_f32_e32 v158, v158
	s_nop 0
	v_mul_f32_e32 v160, 0x3f317217, v158
	v_fma_f32 v160, v158, s48, -v160
	v_fmac_f32_e32 v160, 0x3377d1cf, v158
	v_fmac_f32_e32 v160, 0x3f317217, v158
	v_cmp_lt_f32_e64 s[0:1], |v158|, s49
	s_nop 1
	v_cndmask_b32_e64 v158, v158, v160, s[0:1]
	v_cndmask_b32_e32 v160, 0, v233, vcc
	v_sub_f32_e32 v158, v158, v160
	v_sub_f32_e32 v158, v159, v158
	v_mul_f32_e32 v238, 0x3d800000, v158
	v_fmac_f32_e32 v141, 0x3d800000, v158
	s_waitcnt lgkmcnt(0)
	v_mul_f32_e32 v158, v5, v241
	v_fmac_f32_e32 v158, v4, v240
	v_fmac_f32_e32 v158, v6, v242
	v_fmac_f32_e32 v158, v7, v243
	ds_read_b128 v[240:243], v9 offset:6032
	v_add_f32_e32 v158, v157, v158
	s_waitcnt lgkmcnt(0)
	v_mul_f32_e32 v159, v154, v241
	v_fmac_f32_e32 v159, v228, v240
	v_fmac_f32_e32 v159, v155, v242
	v_fmac_f32_e32 v159, v156, v243
	ds_read_b128 v[240:243], v9 offset:6048
	v_add_f32_e32 v158, v158, v159
	s_waitcnt lgkmcnt(0)
	v_mul_f32_e32 v159, v252, v241
	v_fmac_f32_e32 v159, v146, v240
	v_fmac_f32_e32 v159, v253, v242
	v_fmac_f32_e32 v159, v227, v243
	ds_read_b128 v[240:243], v9 offset:6064
	v_add_f32_e32 v158, v158, v159
	s_waitcnt lgkmcnt(0)
	v_mul_f32_e32 v159, v147, v241
	v_fmac_f32_e32 v159, v145, v240
	v_fmac_f32_e32 v159, v230, v242
	v_fmac_f32_e32 v159, v231, v243
	v_add_f32_e32 v158, v158, v159
	v_min_f32_e32 v159, 0, v158
	v_mul_f32_e64 v158, |v158|, s18
	v_exp_f32_e32 v158, v158
	ds_read_b128 v[242:245], v9 offset:6144
	v_add_f32_e32 v158, 1.0, v158
	v_cmp_gt_f32_e32 vcc, s71, v158
	s_nop 1
	v_cndmask_b32_e64 v160, 0, 32, vcc
	v_ldexp_f32 v158, v158, v160
	v_log_f32_e32 v158, v158
	s_nop 0
	v_mul_f32_e32 v160, 0x3f317217, v158
	v_fma_f32 v160, v158, s48, -v160
	v_fmac_f32_e32 v160, 0x3377d1cf, v158
	v_fmac_f32_e32 v160, 0x3f317217, v158
	v_cmp_lt_f32_e64 s[0:1], |v158|, s49
	s_nop 1
	v_cndmask_b32_e64 v158, v158, v160, s[0:1]
	v_cndmask_b32_e32 v160, 0, v233, vcc
	v_sub_f32_e32 v158, v158, v160
	v_sub_f32_e32 v158, v159, v158
	v_mul_f32_e32 v240, 0x3d800000, v158
	v_fmac_f32_e32 v141, 0x3d800000, v158
	s_waitcnt lgkmcnt(0)
	v_mul_f32_e32 v158, v5, v243
	v_fmac_f32_e32 v158, v4, v242
	v_fmac_f32_e32 v158, v6, v244
	v_fmac_f32_e32 v158, v7, v245
	ds_read_b128 v[242:245], v9 offset:6160
	v_add_f32_e32 v158, v157, v158
	s_waitcnt lgkmcnt(0)
	v_mul_f32_e32 v159, v154, v243
	v_fmac_f32_e32 v159, v228, v242
	v_fmac_f32_e32 v159, v155, v244
	v_fmac_f32_e32 v159, v156, v245
	ds_read_b128 v[242:245], v9 offset:6176
	v_add_f32_e32 v158, v158, v159
	s_waitcnt lgkmcnt(0)
	v_mul_f32_e32 v159, v252, v243
	v_fmac_f32_e32 v159, v146, v242
	v_fmac_f32_e32 v159, v253, v244
	v_fmac_f32_e32 v159, v227, v245
	ds_read_b128 v[242:245], v9 offset:6192
	v_add_f32_e32 v158, v158, v159
	s_waitcnt lgkmcnt(0)
	v_mul_f32_e32 v159, v147, v243
	v_fmac_f32_e32 v159, v145, v242
	v_fmac_f32_e32 v159, v230, v244
	v_fmac_f32_e32 v159, v231, v245
	v_add_f32_e32 v158, v158, v159
	v_min_f32_e32 v159, 0, v158
	v_mul_f32_e64 v158, |v158|, s18
	v_exp_f32_e32 v158, v158
	ds_read_b128 v[242:245], v9 offset:6272
	v_add_f32_e32 v158, 1.0, v158
	v_cmp_gt_f32_e32 vcc, s71, v158
	s_nop 1
	v_cndmask_b32_e64 v160, 0, 32, vcc
	v_ldexp_f32 v158, v158, v160
	v_log_f32_e32 v158, v158
	s_nop 0
	v_mul_f32_e32 v160, 0x3f317217, v158
	v_fma_f32 v160, v158, s48, -v160
	v_fmac_f32_e32 v160, 0x3377d1cf, v158
	v_fmac_f32_e32 v160, 0x3f317217, v158
	v_cmp_lt_f32_e64 s[0:1], |v158|, s49
	s_nop 1
	v_cndmask_b32_e64 v158, v158, v160, s[0:1]
	v_cndmask_b32_e32 v160, 0, v233, vcc
	v_sub_f32_e32 v158, v158, v160
	v_sub_f32_e32 v158, v159, v158
	v_mul_f32_e32 v215, 0x3d800000, v158
	v_fmac_f32_e32 v141, 0x3d800000, v158
	s_waitcnt lgkmcnt(0)
	v_mul_f32_e32 v158, v5, v243
	v_fmac_f32_e32 v158, v4, v242
	v_fmac_f32_e32 v158, v6, v244
	v_fmac_f32_e32 v158, v7, v245
	ds_read_b128 v[242:245], v9 offset:6288
	v_add_f32_e32 v158, v157, v158
	s_waitcnt lgkmcnt(0)
	v_mul_f32_e32 v159, v154, v243
	v_fmac_f32_e32 v159, v228, v242
	v_fmac_f32_e32 v159, v155, v244
	v_fmac_f32_e32 v159, v156, v245
	ds_read_b128 v[242:245], v9 offset:6304
	v_add_f32_e32 v158, v158, v159
	s_waitcnt lgkmcnt(0)
	v_mul_f32_e32 v159, v252, v243
	v_fmac_f32_e32 v159, v146, v242
	v_fmac_f32_e32 v159, v253, v244
	v_fmac_f32_e32 v159, v227, v245
	ds_read_b128 v[242:245], v9 offset:6320
	v_add_f32_e32 v158, v158, v159
	s_waitcnt lgkmcnt(0)
	v_mul_f32_e32 v159, v147, v243
	v_fmac_f32_e32 v159, v145, v242
	v_fmac_f32_e32 v159, v230, v244
	v_fmac_f32_e32 v159, v231, v245
	v_add_f32_e32 v158, v158, v159
	v_min_f32_e32 v159, 0, v158
	v_mul_f32_e64 v158, |v158|, s18
	v_exp_f32_e32 v158, v158
	ds_read_b128 v[242:245], v9 offset:6400
	v_add_f32_e32 v158, 1.0, v158
	v_cmp_gt_f32_e32 vcc, s71, v158
	s_nop 1
	v_cndmask_b32_e64 v160, 0, 32, vcc
	v_ldexp_f32 v158, v158, v160
	v_log_f32_e32 v158, v158
	s_nop 0
	v_mul_f32_e32 v160, 0x3f317217, v158
	v_fma_f32 v160, v158, s48, -v160
	v_fmac_f32_e32 v160, 0x3377d1cf, v158
	v_fmac_f32_e32 v160, 0x3f317217, v158
	v_cmp_lt_f32_e64 s[0:1], |v158|, s49
	s_nop 1
	v_cndmask_b32_e64 v158, v158, v160, s[0:1]
	v_cndmask_b32_e32 v160, 0, v233, vcc
	v_sub_f32_e32 v158, v158, v160
	v_sub_f32_e32 v158, v159, v158
	v_mul_f32_e32 v237, 0x3d800000, v158
	v_fmac_f32_e32 v141, 0x3d800000, v158
	s_waitcnt lgkmcnt(0)
	v_mul_f32_e32 v158, v5, v243
	v_fmac_f32_e32 v158, v4, v242
	v_fmac_f32_e32 v158, v6, v244
	v_fmac_f32_e32 v158, v7, v245
	ds_read_b128 v[242:245], v9 offset:6416
	v_add_f32_e32 v158, v157, v158
	s_waitcnt lgkmcnt(0)
	v_mul_f32_e32 v159, v154, v243
	v_fmac_f32_e32 v159, v228, v242
	v_fmac_f32_e32 v159, v155, v244
	v_fmac_f32_e32 v159, v156, v245
	ds_read_b128 v[242:245], v9 offset:6432
	v_add_f32_e32 v158, v158, v159
	s_waitcnt lgkmcnt(0)
	v_mul_f32_e32 v159, v252, v243
	v_fmac_f32_e32 v159, v146, v242
	v_fmac_f32_e32 v159, v253, v244
	v_fmac_f32_e32 v159, v227, v245
	ds_read_b128 v[242:245], v9 offset:6448
	v_add_f32_e32 v158, v158, v159
	s_waitcnt lgkmcnt(0)
	v_mul_f32_e32 v159, v147, v243
	v_fmac_f32_e32 v159, v145, v242
	v_fmac_f32_e32 v159, v230, v244
	v_fmac_f32_e32 v159, v231, v245
	v_add_f32_e32 v158, v158, v159
	v_min_f32_e32 v159, 0, v158
	v_mul_f32_e64 v158, |v158|, s18
	v_exp_f32_e32 v158, v158
	ds_read_b128 v[244:247], v9 offset:6528
	v_add_f32_e32 v158, 1.0, v158
	v_cmp_gt_f32_e32 vcc, s71, v158
	s_nop 1
	v_cndmask_b32_e64 v160, 0, 32, vcc
	v_ldexp_f32 v158, v158, v160
	v_log_f32_e32 v158, v158
	s_nop 0
	v_mul_f32_e32 v160, 0x3f317217, v158
	v_fma_f32 v160, v158, s48, -v160
	v_fmac_f32_e32 v160, 0x3377d1cf, v158
	v_fmac_f32_e32 v160, 0x3f317217, v158
	v_cmp_lt_f32_e64 s[0:1], |v158|, s49
	s_nop 1
	v_cndmask_b32_e64 v158, v158, v160, s[0:1]
	v_cndmask_b32_e32 v160, 0, v233, vcc
	v_sub_f32_e32 v158, v158, v160
	v_sub_f32_e32 v158, v159, v158
	v_mul_f32_e32 v242, 0x3d800000, v158
	v_fmac_f32_e32 v141, 0x3d800000, v158
	s_waitcnt lgkmcnt(0)
	v_mul_f32_e32 v158, v5, v245
	v_fmac_f32_e32 v158, v4, v244
	v_fmac_f32_e32 v158, v6, v246
	v_fmac_f32_e32 v158, v7, v247
	ds_read_b128 v[244:247], v9 offset:6544
	v_add_f32_e32 v158, v157, v158
	s_waitcnt lgkmcnt(0)
	v_mul_f32_e32 v159, v154, v245
	v_fmac_f32_e32 v159, v228, v244
	v_fmac_f32_e32 v159, v155, v246
	v_fmac_f32_e32 v159, v156, v247
	ds_read_b128 v[244:247], v9 offset:6560
	v_add_f32_e32 v158, v158, v159
	s_waitcnt lgkmcnt(0)
	v_mul_f32_e32 v159, v252, v245
	v_fmac_f32_e32 v159, v146, v244
	v_fmac_f32_e32 v159, v253, v246
	v_fmac_f32_e32 v159, v227, v247
	ds_read_b128 v[244:247], v9 offset:6576
	v_add_f32_e32 v158, v158, v159
	s_waitcnt lgkmcnt(0)
	v_mul_f32_e32 v159, v147, v245
	v_fmac_f32_e32 v159, v145, v244
	v_fmac_f32_e32 v159, v230, v246
	v_fmac_f32_e32 v159, v231, v247
	v_add_f32_e32 v158, v158, v159
	v_min_f32_e32 v159, 0, v158
	v_mul_f32_e64 v158, |v158|, s18
	v_exp_f32_e32 v158, v158
	ds_read_b128 v[246:249], v9 offset:6656
	v_add_f32_e32 v158, 1.0, v158
	v_cmp_gt_f32_e32 vcc, s71, v158
	s_nop 1
	v_cndmask_b32_e64 v160, 0, 32, vcc
	v_ldexp_f32 v158, v158, v160
	v_log_f32_e32 v158, v158
	s_nop 0
	v_mul_f32_e32 v160, 0x3f317217, v158
	v_fma_f32 v160, v158, s48, -v160
	v_fmac_f32_e32 v160, 0x3377d1cf, v158
	v_fmac_f32_e32 v160, 0x3f317217, v158
	v_cmp_lt_f32_e64 s[0:1], |v158|, s49
	s_nop 1
	v_cndmask_b32_e64 v158, v158, v160, s[0:1]
	v_cndmask_b32_e32 v160, 0, v233, vcc
	v_sub_f32_e32 v158, v158, v160
	v_sub_f32_e32 v158, v159, v158
	v_mul_f32_e32 v244, 0x3d800000, v158
	v_fmac_f32_e32 v141, 0x3d800000, v158
	s_waitcnt lgkmcnt(0)
	v_mul_f32_e32 v158, v5, v247
	v_fmac_f32_e32 v158, v4, v246
	v_fmac_f32_e32 v158, v6, v248
	v_fmac_f32_e32 v158, v7, v249
	ds_read_b128 v[246:249], v9 offset:6672
	v_add_f32_e32 v158, v157, v158
	s_waitcnt lgkmcnt(0)
	v_mul_f32_e32 v159, v154, v247
	v_fmac_f32_e32 v159, v228, v246
	v_fmac_f32_e32 v159, v155, v248
	v_fmac_f32_e32 v159, v156, v249
	ds_read_b128 v[246:249], v9 offset:6688
	v_add_f32_e32 v158, v158, v159
	s_waitcnt lgkmcnt(0)
	v_mul_f32_e32 v159, v252, v247
	v_fmac_f32_e32 v159, v146, v246
	v_fmac_f32_e32 v159, v253, v248
	v_fmac_f32_e32 v159, v227, v249
	ds_read_b128 v[246:249], v9 offset:6704
	v_add_f32_e32 v158, v158, v159
	s_waitcnt lgkmcnt(0)
	v_mul_f32_e32 v159, v147, v247
	v_fmac_f32_e32 v159, v145, v246
	v_fmac_f32_e32 v159, v230, v248
	v_fmac_f32_e32 v159, v231, v249
	v_add_f32_e32 v158, v158, v159
	v_min_f32_e32 v159, 0, v158
	v_mul_f32_e64 v158, |v158|, s18
	v_exp_f32_e32 v158, v158
	ds_read_b128 v[246:249], v9 offset:6784
	v_add_f32_e32 v158, 1.0, v158
	v_cmp_gt_f32_e32 vcc, s71, v158
	s_nop 1
	v_cndmask_b32_e64 v160, 0, 32, vcc
	v_ldexp_f32 v158, v158, v160
	v_log_f32_e32 v158, v158
	s_nop 0
	v_mul_f32_e32 v160, 0x3f317217, v158
	v_fma_f32 v160, v158, s48, -v160
	v_fmac_f32_e32 v160, 0x3377d1cf, v158
	v_fmac_f32_e32 v160, 0x3f317217, v158
	v_cmp_lt_f32_e64 s[0:1], |v158|, s49
	s_nop 1
	v_cndmask_b32_e64 v158, v158, v160, s[0:1]
	v_cndmask_b32_e32 v160, 0, v233, vcc
	v_sub_f32_e32 v158, v158, v160
	v_sub_f32_e32 v158, v159, v158
	v_mul_f32_e32 v235, 0x3d800000, v158
	v_fmac_f32_e32 v141, 0x3d800000, v158
	s_waitcnt lgkmcnt(0)
	v_mul_f32_e32 v158, v5, v247
	v_fmac_f32_e32 v158, v4, v246
	v_fmac_f32_e32 v158, v6, v248
	v_fmac_f32_e32 v158, v7, v249
	ds_read_b128 v[246:249], v9 offset:6800
	v_add_f32_e32 v158, v157, v158
	s_waitcnt lgkmcnt(0)
	v_mul_f32_e32 v159, v154, v247
	v_fmac_f32_e32 v159, v228, v246
	v_fmac_f32_e32 v159, v155, v248
	v_fmac_f32_e32 v159, v156, v249
	ds_read_b128 v[246:249], v9 offset:6816
	v_add_f32_e32 v158, v158, v159
	s_waitcnt lgkmcnt(0)
	v_mul_f32_e32 v159, v252, v247
	v_fmac_f32_e32 v159, v146, v246
	v_fmac_f32_e32 v159, v253, v248
	v_fmac_f32_e32 v159, v227, v249
	ds_read_b128 v[246:249], v9 offset:6832
	v_add_f32_e32 v158, v158, v159
	s_waitcnt lgkmcnt(0)
	v_mul_f32_e32 v159, v147, v247
	v_fmac_f32_e32 v159, v145, v246
	v_fmac_f32_e32 v159, v230, v248
	v_fmac_f32_e32 v159, v231, v249
	v_add_f32_e32 v158, v158, v159
	v_min_f32_e32 v159, 0, v158
	v_mul_f32_e64 v158, |v158|, s18
	v_exp_f32_e32 v158, v158
	ds_read_b128 v[246:249], v9 offset:6912
	v_add_f32_e32 v158, 1.0, v158
	v_cmp_gt_f32_e32 vcc, s71, v158
	s_nop 1
	v_cndmask_b32_e64 v160, 0, 32, vcc
	v_ldexp_f32 v158, v158, v160
	v_log_f32_e32 v158, v158
	s_nop 0
	v_mul_f32_e32 v160, 0x3f317217, v158
	v_fma_f32 v160, v158, s48, -v160
	v_fmac_f32_e32 v160, 0x3377d1cf, v158
	v_fmac_f32_e32 v160, 0x3f317217, v158
	v_cmp_lt_f32_e64 s[0:1], |v158|, s49
	s_nop 1
	v_cndmask_b32_e64 v158, v158, v160, s[0:1]
	v_cndmask_b32_e32 v160, 0, v233, vcc
	v_sub_f32_e32 v158, v158, v160
	v_sub_f32_e32 v158, v159, v158
	v_mul_f32_e32 v241, 0x3d800000, v158
	v_fmac_f32_e32 v141, 0x3d800000, v158
	s_waitcnt lgkmcnt(0)
	v_mul_f32_e32 v158, v5, v247
	v_fmac_f32_e32 v158, v4, v246
	v_fmac_f32_e32 v158, v6, v248
	v_fmac_f32_e32 v158, v7, v249
	ds_read_b128 v[246:249], v9 offset:6928
	v_add_f32_e32 v158, v157, v158
	s_waitcnt lgkmcnt(0)
	v_mul_f32_e32 v159, v154, v247
	v_fmac_f32_e32 v159, v228, v246
	v_fmac_f32_e32 v159, v155, v248
	v_fmac_f32_e32 v159, v156, v249
	ds_read_b128 v[246:249], v9 offset:6944
	v_add_f32_e32 v158, v158, v159
	s_waitcnt lgkmcnt(0)
	v_mul_f32_e32 v159, v252, v247
	v_fmac_f32_e32 v159, v146, v246
	v_fmac_f32_e32 v159, v253, v248
	v_fmac_f32_e32 v159, v227, v249
	ds_read_b128 v[246:249], v9 offset:6960
	v_add_f32_e32 v158, v158, v159
	s_waitcnt lgkmcnt(0)
	v_mul_f32_e32 v159, v147, v247
	v_fmac_f32_e32 v159, v145, v246
	v_fmac_f32_e32 v159, v230, v248
	v_fmac_f32_e32 v159, v231, v249
	v_add_f32_e32 v158, v158, v159
	v_min_f32_e32 v159, 0, v158
	v_mul_f32_e64 v158, |v158|, s18
	v_exp_f32_e32 v158, v158
	ds_read_b128 v[248:251], v9 offset:7040
	v_add_f32_e32 v158, 1.0, v158
	v_cmp_gt_f32_e32 vcc, s71, v158
	s_nop 1
	v_cndmask_b32_e64 v160, 0, 32, vcc
	v_ldexp_f32 v158, v158, v160
	v_log_f32_e32 v158, v158
	s_nop 0
	v_mul_f32_e32 v160, 0x3f317217, v158
	v_fma_f32 v160, v158, s48, -v160
	v_fmac_f32_e32 v160, 0x3377d1cf, v158
	v_fmac_f32_e32 v160, 0x3f317217, v158
	v_cmp_lt_f32_e64 s[0:1], |v158|, s49
	s_nop 1
	v_cndmask_b32_e64 v158, v158, v160, s[0:1]
	v_cndmask_b32_e32 v160, 0, v233, vcc
	v_sub_f32_e32 v158, v158, v160
	v_sub_f32_e32 v158, v159, v158
	v_mul_f32_e32 v246, 0x3d800000, v158
	v_fmac_f32_e32 v141, 0x3d800000, v158
	s_waitcnt lgkmcnt(0)
	v_mul_f32_e32 v158, v5, v249
	v_fmac_f32_e32 v158, v4, v248
	v_fmac_f32_e32 v158, v6, v250
	v_fmac_f32_e32 v158, v7, v251
	ds_read_b128 v[248:251], v9 offset:7056
	v_add_f32_e32 v158, v157, v158
	s_waitcnt lgkmcnt(0)
	v_mul_f32_e32 v159, v154, v249
	v_fmac_f32_e32 v159, v228, v248
	v_fmac_f32_e32 v159, v155, v250
	v_fmac_f32_e32 v159, v156, v251
	ds_read_b128 v[248:251], v9 offset:7072
	v_add_f32_e32 v158, v158, v159
	s_waitcnt lgkmcnt(0)
	v_mul_f32_e32 v159, v252, v249
	v_fmac_f32_e32 v159, v146, v248
	v_fmac_f32_e32 v159, v253, v250
	v_fmac_f32_e32 v159, v227, v251
	ds_read_b128 v[248:251], v9 offset:7088
	v_add_f32_e32 v158, v158, v159
	s_waitcnt lgkmcnt(0)
	v_mul_f32_e32 v159, v147, v249
	v_fmac_f32_e32 v159, v145, v248
	v_fmac_f32_e32 v159, v230, v250
	v_fmac_f32_e32 v159, v231, v251
	v_add_f32_e32 v158, v158, v159
	v_min_f32_e32 v159, 0, v158
	v_mul_f32_e64 v158, |v158|, s18
	v_exp_f32_e32 v158, v158
	ds_read_b128 v[248:251], v9 offset:7168
	v_add_f32_e32 v158, 1.0, v158
	v_cmp_gt_f32_e32 vcc, s71, v158
	s_nop 1
	v_cndmask_b32_e64 v160, 0, 32, vcc
	v_ldexp_f32 v158, v158, v160
	v_log_f32_e32 v158, v158
	s_nop 0
	v_mul_f32_e32 v160, 0x3f317217, v158
	v_fma_f32 v160, v158, s48, -v160
	v_fmac_f32_e32 v160, 0x3377d1cf, v158
	v_fmac_f32_e32 v160, 0x3f317217, v158
	v_cmp_lt_f32_e64 s[0:1], |v158|, s49
	s_nop 1
	v_cndmask_b32_e64 v158, v158, v160, s[0:1]
	v_cndmask_b32_e32 v160, 0, v233, vcc
	v_sub_f32_e32 v158, v158, v160
	v_sub_f32_e32 v158, v159, v158
	v_mul_f32_e32 v247, 0x3d800000, v158
	v_fmac_f32_e32 v141, 0x3d800000, v158
	s_waitcnt lgkmcnt(0)
	v_mul_f32_e32 v158, v5, v249
	v_fmac_f32_e32 v158, v4, v248
	v_fmac_f32_e32 v158, v6, v250
	v_fmac_f32_e32 v158, v7, v251
	ds_read_b128 v[248:251], v9 offset:7184
	v_add_f32_e32 v158, v157, v158
	s_waitcnt lgkmcnt(0)
	v_mul_f32_e32 v159, v154, v249
	v_fmac_f32_e32 v159, v228, v248
	v_fmac_f32_e32 v159, v155, v250
	v_fmac_f32_e32 v159, v156, v251
	ds_read_b128 v[248:251], v9 offset:7200
	v_add_f32_e32 v158, v158, v159
	s_waitcnt lgkmcnt(0)
	v_mul_f32_e32 v159, v252, v249
	v_fmac_f32_e32 v159, v146, v248
	v_fmac_f32_e32 v159, v253, v250
	v_fmac_f32_e32 v159, v227, v251
	ds_read_b128 v[248:251], v9 offset:7216
	v_add_f32_e32 v158, v158, v159
	s_waitcnt lgkmcnt(0)
	v_mul_f32_e32 v159, v147, v249
	v_fmac_f32_e32 v159, v145, v248
	v_fmac_f32_e32 v159, v230, v250
	v_fmac_f32_e32 v159, v231, v251
	v_add_f32_e32 v158, v158, v159
	v_min_f32_e32 v159, 0, v158
	v_mul_f32_e64 v158, |v158|, s18
	v_exp_f32_e32 v158, v158
	ds_read_b128 v[248:251], v9 offset:7296
	v_add_f32_e32 v158, 1.0, v158
	v_cmp_gt_f32_e32 vcc, s71, v158
	s_nop 1
	v_cndmask_b32_e64 v160, 0, 32, vcc
	v_ldexp_f32 v158, v158, v160
	v_log_f32_e32 v158, v158
	s_nop 0
	v_mul_f32_e32 v160, 0x3f317217, v158
	v_fma_f32 v160, v158, s48, -v160
	v_fmac_f32_e32 v160, 0x3377d1cf, v158
	v_fmac_f32_e32 v160, 0x3f317217, v158
	v_cmp_lt_f32_e64 s[0:1], |v158|, s49
	s_nop 1
	v_cndmask_b32_e64 v158, v158, v160, s[0:1]
	v_cndmask_b32_e32 v160, 0, v233, vcc
	v_sub_f32_e32 v158, v158, v160
	v_sub_f32_e32 v158, v159, v158
	v_mul_f32_e32 v239, 0x3d800000, v158
	v_fmac_f32_e32 v141, 0x3d800000, v158
	s_waitcnt lgkmcnt(0)
	v_mul_f32_e32 v158, v5, v249
	v_fmac_f32_e32 v158, v4, v248
	v_fmac_f32_e32 v158, v6, v250
	v_fmac_f32_e32 v158, v7, v251
	ds_read_b128 v[248:251], v9 offset:7312
	v_add_f32_e32 v158, v157, v158
	s_waitcnt lgkmcnt(0)
	v_mul_f32_e32 v159, v154, v249
	v_fmac_f32_e32 v159, v228, v248
	v_fmac_f32_e32 v159, v155, v250
	v_fmac_f32_e32 v159, v156, v251
	ds_read_b128 v[248:251], v9 offset:7328
	v_add_f32_e32 v158, v158, v159
	s_waitcnt lgkmcnt(0)
	v_mul_f32_e32 v159, v252, v249
	v_fmac_f32_e32 v159, v146, v248
	v_fmac_f32_e32 v159, v253, v250
	v_fmac_f32_e32 v159, v227, v251
	ds_read_b128 v[248:251], v9 offset:7344
	v_add_f32_e32 v158, v158, v159
	s_waitcnt lgkmcnt(0)
	v_mul_f32_e32 v159, v147, v249
	v_fmac_f32_e32 v159, v145, v248
	v_fmac_f32_e32 v159, v230, v250
	v_fmac_f32_e32 v159, v231, v251
	v_add_f32_e32 v158, v158, v159
	v_min_f32_e32 v159, 0, v158
	v_mul_f32_e64 v158, |v158|, s18
	v_exp_f32_e32 v158, v158
	ds_read_b128 v[248:251], v9 offset:7424
	v_add_f32_e32 v158, 1.0, v158
	v_cmp_gt_f32_e32 vcc, s71, v158
	s_nop 1
	v_cndmask_b32_e64 v160, 0, 32, vcc
	v_ldexp_f32 v158, v158, v160
	v_log_f32_e32 v158, v158
	s_nop 0
	v_mul_f32_e32 v160, 0x3f317217, v158
	v_fma_f32 v160, v158, s48, -v160
	v_fmac_f32_e32 v160, 0x3377d1cf, v158
	v_fmac_f32_e32 v160, 0x3f317217, v158
	v_cmp_lt_f32_e64 s[0:1], |v158|, s49
	s_nop 1
	v_cndmask_b32_e64 v158, v158, v160, s[0:1]
	v_cndmask_b32_e32 v160, 0, v233, vcc
	v_sub_f32_e32 v158, v158, v160
	v_sub_f32_e32 v158, v159, v158
	v_mul_f32_e32 v245, 0x3d800000, v158
	v_fmac_f32_e32 v141, 0x3d800000, v158
	s_waitcnt lgkmcnt(0)
	v_mul_f32_e32 v158, v5, v249
	v_fmac_f32_e32 v158, v4, v248
	v_fmac_f32_e32 v158, v6, v250
	v_fmac_f32_e32 v158, v7, v251
	ds_read_b128 v[248:251], v9 offset:7440
	v_add_f32_e32 v158, v157, v158
	s_waitcnt lgkmcnt(0)
	v_mul_f32_e32 v159, v154, v249
	v_fmac_f32_e32 v159, v228, v248
	v_fmac_f32_e32 v159, v155, v250
	v_fmac_f32_e32 v159, v156, v251
	ds_read_b128 v[248:251], v9 offset:7456
	v_add_f32_e32 v158, v158, v159
	s_waitcnt lgkmcnt(0)
	v_mul_f32_e32 v159, v252, v249
	v_fmac_f32_e32 v159, v146, v248
	v_fmac_f32_e32 v159, v253, v250
	v_fmac_f32_e32 v159, v227, v251
	ds_read_b128 v[248:251], v9 offset:7472
	v_add_f32_e32 v158, v158, v159
	s_waitcnt lgkmcnt(0)
	v_mul_f32_e32 v159, v147, v249
	v_fmac_f32_e32 v159, v145, v248
	v_fmac_f32_e32 v159, v230, v250
	v_fmac_f32_e32 v159, v231, v251
	v_add_f32_e32 v158, v158, v159
	v_min_f32_e32 v159, 0, v158
	v_mul_f32_e64 v158, |v158|, s18
	v_exp_f32_e32 v158, v158
	s_nop 0
	v_add_f32_e32 v158, 1.0, v158
	v_cmp_gt_f32_e32 vcc, s71, v158
	s_nop 1
	v_cndmask_b32_e64 v160, 0, 32, vcc
	v_ldexp_f32 v158, v158, v160
	v_log_f32_e32 v158, v158
	s_nop 0
	v_mul_f32_e32 v160, 0x3f317217, v158
	v_fma_f32 v160, v158, s48, -v160
	v_fmac_f32_e32 v160, 0x3377d1cf, v158
	v_fmac_f32_e32 v160, 0x3f317217, v158
	v_cmp_lt_f32_e64 s[0:1], |v158|, s49
	s_nop 1
	v_cndmask_b32_e64 v158, v158, v160, s[0:1]
	v_cndmask_b32_e32 v160, 0, v233, vcc
	v_sub_f32_e32 v158, v158, v160
	v_sub_f32_e32 v158, v159, v158
	v_mul_f32_e32 v249, 0x3d800000, v158
	v_fmac_f32_e32 v141, 0x3d800000, v158
	ds_read_b128 v[158:161], v9 offset:7552
	s_waitcnt lgkmcnt(0)
	v_mul_f32_e32 v159, v5, v159
	v_fmac_f32_e32 v159, v4, v158
	v_fmac_f32_e32 v159, v6, v160
	v_fmac_f32_e32 v159, v7, v161
	v_add_f32_e32 v243, v157, v159
	ds_read_b128 v[158:161], v9 offset:7568
	s_waitcnt lgkmcnt(0)
	v_mul_f32_e32 v159, v154, v159
	v_fmac_f32_e32 v159, v228, v158
	v_fmac_f32_e32 v159, v155, v160
	v_fmac_f32_e32 v159, v156, v161
	v_add_f32_e32 v243, v243, v159
	ds_read_b128 v[158:161], v9 offset:7584
	s_waitcnt lgkmcnt(0)
	v_mul_f32_e32 v159, v252, v159
	v_fmac_f32_e32 v159, v146, v158
	v_fmac_f32_e32 v159, v253, v160
	v_fmac_f32_e32 v159, v227, v161
	v_add_f32_e32 v243, v243, v159
	ds_read_b128 v[158:161], v9 offset:7600
	s_waitcnt lgkmcnt(0)
	v_mul_f32_e32 v159, v147, v159
	v_fmac_f32_e32 v159, v145, v158
	v_fmac_f32_e32 v159, v230, v160
	v_fmac_f32_e32 v159, v231, v161
	v_add_f32_e32 v158, v243, v159
	v_min_f32_e32 v159, 0, v158
	v_mul_f32_e64 v158, |v158|, s18
	v_exp_f32_e32 v158, v158
	s_nop 0
	v_add_f32_e32 v158, 1.0, v158
	v_cmp_gt_f32_e32 vcc, s71, v158
	s_nop 1
	v_cndmask_b32_e64 v160, 0, 32, vcc
	v_ldexp_f32 v158, v158, v160
	v_log_f32_e32 v158, v158
	s_nop 0
	v_mul_f32_e32 v160, 0x3f317217, v158
	v_fma_f32 v160, v158, s48, -v160
	v_fmac_f32_e32 v160, 0x3377d1cf, v158
	v_fmac_f32_e32 v160, 0x3f317217, v158
	v_cmp_lt_f32_e64 s[0:1], |v158|, s49
	s_nop 1
	v_cndmask_b32_e64 v158, v158, v160, s[0:1]
	v_cndmask_b32_e32 v160, 0, v233, vcc
	v_sub_f32_e32 v158, v158, v160
	v_sub_f32_e32 v158, v159, v158
	v_mul_f32_e32 v250, 0x3d800000, v158
	v_fmac_f32_e32 v141, 0x3d800000, v158
	ds_read_b128 v[158:161], v9 offset:7680
	s_waitcnt lgkmcnt(0)
	v_mul_f32_e32 v159, v5, v159
	v_fmac_f32_e32 v159, v4, v158
	v_fmac_f32_e32 v159, v6, v160
	v_fmac_f32_e32 v159, v7, v161
	v_add_f32_e32 v243, v157, v159
	ds_read_b128 v[158:161], v9 offset:7696
	s_waitcnt lgkmcnt(0)
	v_mul_f32_e32 v159, v154, v159
	v_fmac_f32_e32 v159, v228, v158
	v_fmac_f32_e32 v159, v155, v160
	v_fmac_f32_e32 v159, v156, v161
	v_add_f32_e32 v243, v243, v159
	ds_read_b128 v[158:161], v9 offset:7712
	s_waitcnt lgkmcnt(0)
	v_mul_f32_e32 v159, v252, v159
	v_fmac_f32_e32 v159, v146, v158
	v_fmac_f32_e32 v159, v253, v160
	v_fmac_f32_e32 v159, v227, v161
	v_add_f32_e32 v243, v243, v159
	ds_read_b128 v[158:161], v9 offset:7728
	s_waitcnt lgkmcnt(0)
	v_mul_f32_e32 v159, v147, v159
	v_fmac_f32_e32 v159, v145, v158
	v_fmac_f32_e32 v159, v230, v160
	v_fmac_f32_e32 v159, v231, v161
	v_add_f32_e32 v158, v243, v159
	v_min_f32_e32 v159, 0, v158
	v_mul_f32_e64 v158, |v158|, s18
	v_exp_f32_e32 v158, v158
	s_nop 0
	v_add_f32_e32 v158, 1.0, v158
	v_cmp_gt_f32_e32 vcc, s71, v158
	s_nop 1
	v_cndmask_b32_e64 v160, 0, 32, vcc
	v_ldexp_f32 v158, v158, v160
	v_log_f32_e32 v158, v158
	s_nop 0
	v_mul_f32_e32 v160, 0x3f317217, v158
	v_fma_f32 v160, v158, s48, -v160
	v_fmac_f32_e32 v160, 0x3377d1cf, v158
	v_fmac_f32_e32 v160, 0x3f317217, v158
	v_cmp_lt_f32_e64 s[0:1], |v158|, s49
	s_nop 1
	v_cndmask_b32_e64 v158, v158, v160, s[0:1]
	v_cndmask_b32_e32 v160, 0, v233, vcc
	v_sub_f32_e32 v158, v158, v160
	v_sub_f32_e32 v158, v159, v158
	v_mul_f32_e32 v243, 0x3d800000, v158
	v_fmac_f32_e32 v141, 0x3d800000, v158
	ds_read_b128 v[158:161], v9 offset:7808
	s_waitcnt lgkmcnt(0)
	v_mul_f32_e32 v159, v5, v159
	v_fmac_f32_e32 v159, v4, v158
	v_fmac_f32_e32 v159, v6, v160
	v_fmac_f32_e32 v159, v7, v161
	v_add_f32_e32 v248, v157, v159
	ds_read_b128 v[158:161], v9 offset:7824
	s_waitcnt lgkmcnt(0)
	v_mul_f32_e32 v159, v154, v159
	v_fmac_f32_e32 v159, v228, v158
	v_fmac_f32_e32 v159, v155, v160
	v_fmac_f32_e32 v159, v156, v161
	v_add_f32_e32 v248, v248, v159
	ds_read_b128 v[158:161], v9 offset:7840
	s_waitcnt lgkmcnt(0)
	v_mul_f32_e32 v159, v252, v159
	v_fmac_f32_e32 v159, v146, v158
	v_fmac_f32_e32 v159, v253, v160
	v_fmac_f32_e32 v159, v227, v161
	v_add_f32_e32 v248, v248, v159
	ds_read_b128 v[158:161], v9 offset:7856
	s_waitcnt lgkmcnt(0)
	v_mul_f32_e32 v159, v147, v159
	v_fmac_f32_e32 v159, v145, v158
	v_fmac_f32_e32 v159, v230, v160
	v_fmac_f32_e32 v159, v231, v161
	v_add_f32_e32 v158, v248, v159
	v_min_f32_e32 v159, 0, v158
	v_mul_f32_e64 v158, |v158|, s18
	v_exp_f32_e32 v158, v158
	s_nop 0
	v_add_f32_e32 v158, 1.0, v158
	v_cmp_gt_f32_e32 vcc, s71, v158
	s_nop 1
	v_cndmask_b32_e64 v160, 0, 32, vcc
	v_ldexp_f32 v158, v158, v160
	v_log_f32_e32 v158, v158
	s_nop 0
	v_mul_f32_e32 v160, 0x3f317217, v158
	v_fma_f32 v160, v158, s48, -v160
	v_fmac_f32_e32 v160, 0x3377d1cf, v158
	v_fmac_f32_e32 v160, 0x3f317217, v158
	v_cmp_lt_f32_e64 s[0:1], |v158|, s49
	s_nop 1
	v_cndmask_b32_e64 v158, v158, v160, s[0:1]
	v_cndmask_b32_e32 v160, 0, v233, vcc
	v_sub_f32_e32 v158, v158, v160
	v_sub_f32_e32 v158, v159, v158
	v_mul_f32_e32 v248, 0x3d800000, v158
	v_fmac_f32_e32 v141, 0x3d800000, v158
	ds_read_b128 v[158:161], v9 offset:7936
	s_waitcnt lgkmcnt(0)
	v_mul_f32_e32 v159, v5, v159
	v_fmac_f32_e32 v159, v4, v158
	v_fmac_f32_e32 v159, v6, v160
	v_fmac_f32_e32 v159, v7, v161
	v_add_f32_e32 v251, v157, v159
	ds_read_b128 v[158:161], v9 offset:7952
	s_waitcnt lgkmcnt(0)
	v_mul_f32_e32 v159, v154, v159
	v_fmac_f32_e32 v159, v228, v158
	v_fmac_f32_e32 v159, v155, v160
	v_fmac_f32_e32 v159, v156, v161
	v_add_f32_e32 v251, v251, v159
	ds_read_b128 v[158:161], v9 offset:7968
	s_waitcnt lgkmcnt(0)
	v_mul_f32_e32 v159, v252, v159
	v_fmac_f32_e32 v159, v146, v158
	v_fmac_f32_e32 v159, v253, v160
	v_fmac_f32_e32 v159, v227, v161
	v_add_f32_e32 v251, v251, v159
	ds_read_b128 v[158:161], v9 offset:7984
	s_waitcnt lgkmcnt(0)
	v_mul_f32_e32 v159, v147, v159
	v_fmac_f32_e32 v159, v145, v158
	v_fmac_f32_e32 v159, v230, v160
	v_fmac_f32_e32 v159, v231, v161
	v_add_f32_e32 v158, v251, v159
	v_min_f32_e32 v159, 0, v158
	v_mul_f32_e64 v158, |v158|, s18
	v_exp_f32_e32 v158, v158
	s_nop 0
	v_add_f32_e32 v158, 1.0, v158
	v_cmp_gt_f32_e32 vcc, s71, v158
	s_nop 1
	v_cndmask_b32_e64 v160, 0, 32, vcc
	v_ldexp_f32 v158, v158, v160
	v_log_f32_e32 v158, v158
	s_nop 0
	v_mul_f32_e32 v160, 0x3f317217, v158
	v_fma_f32 v160, v158, s48, -v160
	v_fmac_f32_e32 v160, 0x3377d1cf, v158
	v_fmac_f32_e32 v160, 0x3f317217, v158
	v_cmp_lt_f32_e64 s[0:1], |v158|, s49
	s_nop 1
	v_cndmask_b32_e64 v158, v158, v160, s[0:1]
	v_cndmask_b32_e32 v160, 0, v233, vcc
	v_sub_f32_e32 v158, v158, v160
	v_sub_f32_e32 v158, v159, v158
	v_mul_f32_e32 v251, 0x3d800000, v158
	v_fmac_f32_e32 v141, 0x3d800000, v158
	ds_read_b128 v[158:161], v9 offset:8064
	s_waitcnt lgkmcnt(0)
	v_mul_f32_e32 v5, v5, v159
	v_fmac_f32_e32 v5, v4, v158
	v_fmac_f32_e32 v5, v6, v160
	v_fmac_f32_e32 v5, v7, v161
	v_add_f32_e32 v157, v157, v5
	ds_read_b128 v[4:7], v9 offset:8080
	s_waitcnt lgkmcnt(0)
	v_mul_f32_e32 v5, v154, v5
	v_fmac_f32_e32 v5, v228, v4
	v_fmac_f32_e32 v5, v155, v6
	v_fmac_f32_e32 v5, v156, v7
	v_add_f32_e32 v4, v157, v5
	ds_read_b128 v[154:157], v9 offset:8096
	s_waitcnt lgkmcnt(0)
	v_mul_f32_e32 v5, v252, v155
	v_fmac_f32_e32 v5, v146, v154
	v_fmac_f32_e32 v5, v253, v156
	v_fmac_f32_e32 v5, v227, v157
	v_add_f32_e32 v146, v4, v5
	ds_read_b128 v[4:7], v9 offset:8112
	s_waitcnt lgkmcnt(0)
	v_mul_f32_e32 v5, v147, v5
	v_fmac_f32_e32 v5, v145, v4
	v_fmac_f32_e32 v5, v230, v6
	v_fmac_f32_e32 v5, v231, v7
	v_add_f32_e32 v4, v146, v5
	v_min_f32_e32 v5, 0, v4
	v_mul_f32_e64 v4, |v4|, s18
	v_exp_f32_e32 v4, v4
	v_ashrrev_i32_e32 v145, 31, v144
	v_mov_b32_e32 v147, v3
	v_add_f32_e32 v4, 1.0, v4
	v_cmp_gt_f32_e32 vcc, s71, v4
	s_nop 1
	v_cndmask_b32_e64 v6, 0, 32, vcc
	v_ldexp_f32 v4, v4, v6
	v_log_f32_e32 v4, v4
	s_nop 0
	v_mul_f32_e32 v6, 0x3f317217, v4
	v_fma_f32 v6, v4, s48, -v6
	v_fmac_f32_e32 v6, 0x3377d1cf, v4
	v_fmac_f32_e32 v6, 0x3f317217, v4
	v_cmp_lt_f32_e64 s[0:1], |v4|, s49
	s_nop 1
	v_cndmask_b32_e64 v4, v4, v6, s[0:1]
	v_cndmask_b32_e32 v6, 0, v233, vcc
	v_sub_f32_e32 v4, v4, v6
	v_sub_f32_e32 v4, v5, v4
	v_lshlrev_b64 v[6:7], 7, v[144:145]
	ds_read_u16 v145, v41 offset:24576
	v_mul_f32_e32 v252, 0x3d800000, v4
	v_cndmask_b32_e64 v144, v252, v173, s[4:5]
	v_add_f32_e32 v156, 0, v144
	ds_read_u16 v144, v41 offset:8192
	s_waitcnt lgkmcnt(1)
	v_lshlrev_b32_e32 v157, 16, v145
	v_mul_f32_e32 v145, 0x3fb8aa3b, v156
	v_exp_f32_e32 v145, v145
	v_fmac_f32_e32 v141, 0x3d800000, v4
	s_waitcnt lgkmcnt(0)
	v_lshlrev_b32_e32 v144, 16, v144
	v_or_b32_e32 v4, v143, v11
	v_mul_f32_e32 v144, 0x3db504f3, v144
	v_lshlrev_b32_e32 v146, 13, v4
	v_ashrrev_i32_e32 v143, 31, v142
	v_mul_f32_e32 v144, v144, v145
	v_lshl_add_u64 v[142:143], v[146:147], 0, v[142:143]
	v_bfe_u32 v145, v144, 16, 1
	v_add3_u32 v158, v144, v145, s73
	v_or_b32_e32 v144, v142, v10
	v_mov_b32_e32 v145, v143
	v_lshlrev_b64 v[146:147], 8, v[144:145]
	v_mul_f32_e32 v145, 0xbfb8aa3b, v156
	v_exp_f32_e32 v145, v145
	v_lshlrev_b32_e32 v144, 1, v8
	v_or_b32_e32 v146, v146, v144
	v_lshl_add_u64 v[154:155], s[36:37], 0, v[146:147]
	v_mul_f32_e32 v145, v145, v157
	v_and_b32_e32 v227, 0xff, v0
	v_lshrrev_b32_e32 v228, 8, v0
	v_lshlrev_b32_e32 v227, 2, v227
	v_lshl_add_u32 v227, v228, 16, v227
	ds_write_b32 v227, v218 offset:40960
	ds_write_b32 v227, v219 offset:41984
	ds_write_b32 v227, v220 offset:43008
	ds_write_b32 v227, v221 offset:44032
	ds_write_b32 v227, v222 offset:45056
	ds_write_b32 v227, v223 offset:46080
	ds_write_b32 v227, v224 offset:47104
	ds_write_b32 v227, v225 offset:48128
	ds_write_b32 v227, v226 offset:49152
	v_cndmask_b32_e64 v224, 0, -14, s[4:5]
	v_cndmask_b32_e64 v225, 0, -1, s[4:5]
	s_mov_b32 s98, 0xffff0000
	global_store_short_d16_hi v[154:155], v158, off
	v_bfe_u32 v154, v145, 16, 1
	v_add3_u32 v145, v145, v154, s73
	v_lshl_add_u64 v[146:147], s[38:39], 0, v[146:147]
	global_store_short_d16_hi v[146:147], v145, off
	v_sub_f32_e32 v145, v141, v156
	v_mul_f32_e32 v145, 0x3fb8aa3b, v145
	v_exp_f32_e32 v145, v145
	v_lshlrev_b32_e32 v4, 14, v4
	v_mov_b32_e32 v5, v3
	v_lshl_add_u64 v[4:5], v[4:5], 0, v[6:7]
	v_or_b32_e32 v4, v4, v8
	v_mul_f32_e32 v145, v145, v157
	v_lshlrev_b64 v[6:7], 7, v[4:5]
	v_bfe_u32 v146, v145, 16, 1
	v_lshl_add_u64 v[6:7], s[54:55], 0, v[6:7]
	v_add3_u32 v145, v145, v146, s73
	v_lshlrev_b32_e32 v146, 1, v10
	v_mov_b32_e32 v147, v3
	v_lshl_add_u64 v[146:147], v[6:7], 0, v[146:147]
	v_lshrrev_b32_e32 v220, 16, v145
	ds_read_u16 v146, v43 offset:8192
	ds_read_u16 v147, v43 offset:24576
	v_cndmask_b32_e64 v145, v251, v174, s[4:5]
	v_add_f32_e32 v145, v145, v156
	s_movk_i32 s0, 0x1ff
	s_waitcnt lgkmcnt(1)
	v_lshlrev_b32_e32 v146, 16, v146
	s_waitcnt lgkmcnt(0)
	v_lshlrev_b32_e32 v156, 16, v147
	v_mul_f32_e32 v147, 0x3fb8aa3b, v145
	v_exp_f32_e32 v147, v147
	v_mul_f32_e32 v146, 0x3db504f3, v146
	v_cmp_lt_i32_e32 vcc, s0, v1
	v_lshl_add_u64 v[4:5], v[4:5], 2, s[50:51]
	v_mul_f32_e32 v146, v146, v147
	v_bfe_u32 v147, v146, 16, 1
	v_add3_u32 v157, v146, v147, s73
	v_or_b32_e32 v146, v142, v12
	v_mov_b32_e32 v147, v143
	v_lshlrev_b64 v[146:147], 8, v[146:147]
	v_or_b32_e32 v146, v146, v144
	v_lshl_add_u64 v[154:155], s[36:37], 0, v[146:147]
	global_store_short_d16_hi v[154:155], v157, off
	v_mul_f32_e32 v154, 0xbfb8aa3b, v145
	v_exp_f32_e32 v154, v154
	v_lshl_add_u64 v[146:147], s[38:39], 0, v[146:147]
	s_or_b64 s[12:13], vcc, s[12:13]
	v_mul_f32_e32 v154, v154, v156
	v_bfe_u32 v155, v154, 16, 1
	v_add3_u32 v154, v154, v155, s73
	global_store_short_d16_hi v[146:147], v154, off
	v_sub_f32_e32 v146, v141, v145
	v_mul_f32_e32 v146, 0x3fb8aa3b, v146
	v_exp_f32_e32 v146, v146
	s_nop 0
	v_mul_f32_e32 v146, v146, v156
	v_bfe_u32 v147, v146, 16, 1
	v_add3_u32 v154, v146, v147, s73
	v_lshlrev_b32_e32 v146, 1, v12
	v_mov_b32_e32 v147, v3
	v_lshl_add_u64 v[146:147], v[6:7], 0, v[146:147]
	v_and_or_b32 v220, v154, s98, v220
	ds_read_u16 v147, v45 offset:24576
	v_cndmask_b32_e64 v146, v248, v175, s[4:5]
	v_add_f32_e32 v145, v146, v145
	ds_read_u16 v146, v45 offset:8192
	s_waitcnt lgkmcnt(1)
	v_lshlrev_b32_e32 v156, 16, v147
	v_mul_f32_e32 v147, 0x3fb8aa3b, v145
	v_exp_f32_e32 v147, v147
	s_waitcnt lgkmcnt(0)
	v_lshlrev_b32_e32 v146, 16, v146
	v_mul_f32_e32 v146, 0x3db504f3, v146
	v_mul_f32_e32 v146, v146, v147
	v_bfe_u32 v147, v146, 16, 1
	v_add3_u32 v157, v146, v147, s73
	v_or_b32_e32 v146, v142, v14
	v_mov_b32_e32 v147, v143
	v_lshlrev_b64 v[146:147], 8, v[146:147]
	v_or_b32_e32 v146, v146, v144
	v_lshl_add_u64 v[154:155], s[36:37], 0, v[146:147]
	global_store_short_d16_hi v[154:155], v157, off
	v_mul_f32_e32 v154, 0xbfb8aa3b, v145
	v_exp_f32_e32 v154, v154
	v_lshl_add_u64 v[146:147], s[38:39], 0, v[146:147]
	v_mul_f32_e32 v154, v154, v156
	v_bfe_u32 v155, v154, 16, 1
	v_add3_u32 v154, v154, v155, s73
	global_store_short_d16_hi v[146:147], v154, off
	v_sub_f32_e32 v146, v141, v145
	v_mul_f32_e32 v146, 0x3fb8aa3b, v146
	v_exp_f32_e32 v146, v146
	v_mov_b32_e32 v155, v143
	v_mul_f32_e32 v146, v146, v156
	v_bfe_u32 v147, v146, 16, 1
	v_add3_u32 v154, v146, v147, s73
	v_lshlrev_b32_e32 v146, 1, v14
	v_mov_b32_e32 v147, v3
	v_lshl_add_u64 v[146:147], v[6:7], 0, v[146:147]
	v_lshrrev_b32_e32 v221, 16, v154
	v_cndmask_b32_e64 v146, v243, v176, s[4:5]
	v_add_f32_e32 v145, v146, v145
	ds_read_u16 v146, v47 offset:8192
	v_mul_f32_e32 v154, 0x3fb8aa3b, v145
	v_exp_f32_e32 v154, v154
	s_waitcnt lgkmcnt(0)
	v_lshlrev_b32_e32 v147, 16, v146
	v_mul_f32_e32 v147, 0x3db504f3, v147
	v_mul_f32_e32 v147, v154, v147
	v_bfe_u32 v154, v147, 16, 1
	v_add3_u32 v147, v147, v154, s73
	v_or_b32_e32 v154, v142, v16
	v_lshlrev_b64 v[154:155], 8, v[154:155]
	v_or_b32_e32 v154, v154, v144
	ds_read_u16 v146, v47 offset:24576
	v_lshl_add_u64 v[156:157], s[36:37], 0, v[154:155]
	global_store_short_d16_hi v[156:157], v147, off
	v_mul_f32_e32 v147, 0xbfb8aa3b, v145
	v_exp_f32_e32 v147, v147
	s_waitcnt lgkmcnt(0)
	v_lshlrev_b32_e32 v146, 16, v146
	v_lshl_add_u64 v[154:155], s[38:39], 0, v[154:155]
	v_mul_f32_e32 v147, v147, v146
	v_bfe_u32 v156, v147, 16, 1
	v_add3_u32 v147, v147, v156, s73
	global_store_short_d16_hi v[154:155], v147, off
	v_sub_f32_e32 v147, v141, v145
	v_mul_f32_e32 v147, 0x3fb8aa3b, v147
	v_exp_f32_e32 v147, v147
	s_nop 0
	v_mul_f32_e32 v146, v147, v146
	v_bfe_u32 v147, v146, 16, 1
	v_add3_u32 v154, v146, v147, s73
	v_lshlrev_b32_e32 v146, 1, v16
	v_mov_b32_e32 v147, v3
	v_lshl_add_u64 v[146:147], v[6:7], 0, v[146:147]
	v_and_or_b32 v221, v154, s98, v221
	ds_read_u16 v147, v49 offset:24576
	v_cndmask_b32_e64 v146, v250, v177, s[4:5]
	v_add_f32_e32 v145, v146, v145
	ds_read_u16 v146, v49 offset:8192
	s_waitcnt lgkmcnt(1)
	v_lshlrev_b32_e32 v156, 16, v147
	v_mul_f32_e32 v147, 0x3fb8aa3b, v145
	v_exp_f32_e32 v147, v147
	s_waitcnt lgkmcnt(0)
	v_lshlrev_b32_e32 v146, 16, v146
	v_mul_f32_e32 v146, 0x3db504f3, v146
	v_mul_f32_e32 v146, v147, v146
	v_bfe_u32 v147, v146, 16, 1
	v_add3_u32 v157, v146, v147, s73
	v_or_b32_e32 v146, v142, v18
	v_mov_b32_e32 v147, v143
	v_lshlrev_b64 v[146:147], 8, v[146:147]
	v_or_b32_e32 v146, v146, v144
	v_lshl_add_u64 v[154:155], s[36:37], 0, v[146:147]
	global_store_short_d16_hi v[154:155], v157, off
	v_mul_f32_e32 v154, 0xbfb8aa3b, v145
	v_exp_f32_e32 v154, v154
	v_lshl_add_u64 v[146:147], s[38:39], 0, v[146:147]
	v_mul_f32_e32 v154, v154, v156
	v_bfe_u32 v155, v154, 16, 1
	v_add3_u32 v154, v154, v155, s73
	global_store_short_d16_hi v[146:147], v154, off
	v_sub_f32_e32 v146, v141, v145
	v_mul_f32_e32 v146, 0x3fb8aa3b, v146
	v_exp_f32_e32 v146, v146
	s_nop 0
	v_mul_f32_e32 v146, v146, v156
	v_bfe_u32 v147, v146, 16, 1
	v_add3_u32 v154, v146, v147, s73
	v_lshlrev_b32_e32 v146, 1, v18
	v_mov_b32_e32 v147, v3
	v_lshl_add_u64 v[146:147], v[6:7], 0, v[146:147]
	v_lshrrev_b32_e32 v222, 16, v154
	ds_read_u16 v147, v51 offset:24576
	v_cndmask_b32_e64 v146, v249, v178, s[4:5]
	v_add_f32_e32 v145, v146, v145
	ds_read_u16 v146, v51 offset:8192
	s_waitcnt lgkmcnt(1)
	v_lshlrev_b32_e32 v156, 16, v147
	v_mul_f32_e32 v147, 0x3fb8aa3b, v145
	v_exp_f32_e32 v147, v147
	s_waitcnt lgkmcnt(0)
	v_lshlrev_b32_e32 v146, 16, v146
	v_mul_f32_e32 v146, 0x3db504f3, v146
	v_mul_f32_e32 v146, v147, v146
	v_bfe_u32 v147, v146, 16, 1
	v_add3_u32 v157, v146, v147, s73
	v_or_b32_e32 v146, v142, v20
	v_mov_b32_e32 v147, v143
	v_lshlrev_b64 v[146:147], 8, v[146:147]
	v_or_b32_e32 v146, v146, v144
	v_lshl_add_u64 v[154:155], s[36:37], 0, v[146:147]
	global_store_short_d16_hi v[154:155], v157, off
	v_mul_f32_e32 v154, 0xbfb8aa3b, v145
	v_exp_f32_e32 v154, v154
	v_lshl_add_u64 v[146:147], s[38:39], 0, v[146:147]
	v_mul_f32_e32 v154, v154, v156
	v_bfe_u32 v155, v154, 16, 1
	v_add3_u32 v154, v154, v155, s73
	global_store_short_d16_hi v[146:147], v154, off
	v_sub_f32_e32 v146, v141, v145
	v_mul_f32_e32 v146, 0x3fb8aa3b, v146
	v_exp_f32_e32 v146, v146
	s_nop 0
	v_mul_f32_e32 v146, v146, v156
	v_bfe_u32 v147, v146, 16, 1
	v_add3_u32 v154, v146, v147, s73
	v_lshlrev_b32_e32 v146, 1, v20
	v_mov_b32_e32 v147, v3
	v_lshl_add_u64 v[146:147], v[6:7], 0, v[146:147]
	v_and_or_b32 v222, v154, s98, v222
	ds_read_u16 v147, v53 offset:24576
	v_cndmask_b32_e64 v146, v245, v179, s[4:5]
	v_add_f32_e32 v145, v146, v145
	ds_read_u16 v146, v53 offset:8192
	s_waitcnt lgkmcnt(1)
	v_lshlrev_b32_e32 v156, 16, v147
	v_mul_f32_e32 v147, 0x3fb8aa3b, v145
	v_exp_f32_e32 v147, v147
	s_waitcnt lgkmcnt(0)
	v_lshlrev_b32_e32 v146, 16, v146
	v_mul_f32_e32 v146, 0x3db504f3, v146
	v_mul_f32_e32 v146, v147, v146
	v_bfe_u32 v147, v146, 16, 1
	v_add3_u32 v157, v146, v147, s73
	v_or_b32_e32 v146, v142, v22
	v_mov_b32_e32 v147, v143
	v_lshlrev_b64 v[146:147], 8, v[146:147]
	v_or_b32_e32 v146, v146, v144
	v_lshl_add_u64 v[154:155], s[36:37], 0, v[146:147]
	global_store_short_d16_hi v[154:155], v157, off
	v_mul_f32_e32 v154, 0xbfb8aa3b, v145
	v_exp_f32_e32 v154, v154
	v_lshl_add_u64 v[146:147], s[38:39], 0, v[146:147]
	v_mul_f32_e32 v154, v154, v156
	v_bfe_u32 v155, v154, 16, 1
	v_add3_u32 v154, v154, v155, s73
	global_store_short_d16_hi v[146:147], v154, off
	v_sub_f32_e32 v146, v141, v145
	v_mul_f32_e32 v146, 0x3fb8aa3b, v146
	v_exp_f32_e32 v146, v146
	s_nop 0
	v_mul_f32_e32 v146, v146, v156
	v_bfe_u32 v147, v146, 16, 1
	v_add3_u32 v154, v146, v147, s73
	v_lshlrev_b32_e32 v146, 1, v22
	v_mov_b32_e32 v147, v3
	v_lshl_add_u64 v[146:147], v[6:7], 0, v[146:147]
	v_lshrrev_b32_e32 v223, 16, v154
	ds_read_u16 v147, v55 offset:24576
	v_cndmask_b32_e64 v146, v239, v180, s[4:5]
	v_add_f32_e32 v145, v146, v145
	ds_read_u16 v146, v55 offset:8192
	s_waitcnt lgkmcnt(1)
	v_lshlrev_b32_e32 v156, 16, v147
	v_mul_f32_e32 v147, 0x3fb8aa3b, v145
	v_exp_f32_e32 v147, v147
	s_waitcnt lgkmcnt(0)
	v_lshlrev_b32_e32 v146, 16, v146
	v_mul_f32_e32 v146, 0x3db504f3, v146
	v_mul_f32_e32 v146, v147, v146
	v_bfe_u32 v147, v146, 16, 1
	v_add3_u32 v157, v146, v147, s73
	v_or_b32_e32 v146, v142, v24
	v_mov_b32_e32 v147, v143
	v_lshlrev_b64 v[146:147], 8, v[146:147]
	v_or_b32_e32 v146, v146, v144
	v_lshl_add_u64 v[154:155], s[36:37], 0, v[146:147]
	global_store_short_d16_hi v[154:155], v157, off
	v_mul_f32_e32 v154, 0xbfb8aa3b, v145
	v_exp_f32_e32 v154, v154
	v_lshl_add_u64 v[146:147], s[38:39], 0, v[146:147]
	v_mul_f32_e32 v154, v154, v156
	v_bfe_u32 v155, v154, 16, 1
	v_add3_u32 v154, v154, v155, s73
	global_store_short_d16_hi v[146:147], v154, off
	v_sub_f32_e32 v146, v141, v145
	v_mul_f32_e32 v146, 0x3fb8aa3b, v146
	v_exp_f32_e32 v146, v146
	s_nop 0
	v_mul_f32_e32 v146, v146, v156
	v_bfe_u32 v147, v146, 16, 1
	v_add3_u32 v154, v146, v147, s73
	v_lshlrev_b32_e32 v146, 1, v24
	v_mov_b32_e32 v147, v3
	v_lshl_add_u64 v[146:147], v[6:7], 0, v[146:147]
	v_and_or_b32 v223, v154, s98, v223
	v_alignbit_b32 v226, v223, v223, 16
	v_alignbit_b32 v218, v220, v220, 16
	v_cndmask_b32_e64 v220, v226, v220, s[4:5]
	v_cndmask_b32_e64 v223, v218, v223, s[4:5]
	v_alignbit_b32 v226, v222, v222, 16
	v_alignbit_b32 v218, v221, v221, 16
	v_cndmask_b32_e64 v221, v226, v221, s[4:5]
	v_cndmask_b32_e64 v222, v218, v222, s[4:5]
	v_lshl_add_u64 v[218:219], v[146:147], 0, v[224:225]
	global_store_dwordx4 v[218:219], v[220:223], off
	s_nop 1
	ds_read_u16 v147, v57 offset:24576
	v_cndmask_b32_e64 v146, v247, v181, s[4:5]
	v_add_f32_e32 v145, v146, v145
	ds_read_u16 v146, v57 offset:8192
	s_waitcnt lgkmcnt(1)
	v_lshlrev_b32_e32 v156, 16, v147
	v_mul_f32_e32 v147, 0x3fb8aa3b, v145
	v_exp_f32_e32 v147, v147
	s_waitcnt lgkmcnt(0)
	v_lshlrev_b32_e32 v146, 16, v146
	v_mul_f32_e32 v146, 0x3db504f3, v146
	v_mul_f32_e32 v146, v147, v146
	v_bfe_u32 v147, v146, 16, 1
	v_add3_u32 v157, v146, v147, s73
	v_or_b32_e32 v146, v142, v26
	v_mov_b32_e32 v147, v143
	v_lshlrev_b64 v[146:147], 8, v[146:147]
	v_or_b32_e32 v146, v146, v144
	v_lshl_add_u64 v[154:155], s[36:37], 0, v[146:147]
	global_store_short_d16_hi v[154:155], v157, off
	v_mul_f32_e32 v154, 0xbfb8aa3b, v145
	v_exp_f32_e32 v154, v154
	v_lshl_add_u64 v[146:147], s[38:39], 0, v[146:147]
	v_mul_f32_e32 v154, v154, v156
	v_bfe_u32 v155, v154, 16, 1
	v_add3_u32 v154, v154, v155, s73
	global_store_short_d16_hi v[146:147], v154, off
	v_sub_f32_e32 v146, v141, v145
	v_mul_f32_e32 v146, 0x3fb8aa3b, v146
	v_exp_f32_e32 v146, v146
	s_nop 0
	v_mul_f32_e32 v146, v146, v156
	v_bfe_u32 v147, v146, 16, 1
	v_add3_u32 v154, v146, v147, s73
	v_lshlrev_b32_e32 v146, 1, v26
	v_mov_b32_e32 v147, v3
	v_lshl_add_u64 v[146:147], v[6:7], 0, v[146:147]
	v_lshrrev_b32_e32 v220, 16, v154
	ds_read_u16 v147, v59 offset:24576
	v_cndmask_b32_e64 v146, v246, v182, s[4:5]
	v_add_f32_e32 v145, v146, v145
	ds_read_u16 v146, v59 offset:8192
	s_waitcnt lgkmcnt(1)
	v_lshlrev_b32_e32 v156, 16, v147
	v_mul_f32_e32 v147, 0x3fb8aa3b, v145
	v_exp_f32_e32 v147, v147
	s_waitcnt lgkmcnt(0)
	v_lshlrev_b32_e32 v146, 16, v146
	v_mul_f32_e32 v146, 0x3db504f3, v146
	v_mul_f32_e32 v146, v147, v146
	v_bfe_u32 v147, v146, 16, 1
	v_add3_u32 v157, v146, v147, s73
	v_or_b32_e32 v146, v142, v28
	v_mov_b32_e32 v147, v143
	v_lshlrev_b64 v[146:147], 8, v[146:147]
	v_or_b32_e32 v146, v146, v144
	v_lshl_add_u64 v[154:155], s[36:37], 0, v[146:147]
	global_store_short_d16_hi v[154:155], v157, off
	v_mul_f32_e32 v154, 0xbfb8aa3b, v145
	v_exp_f32_e32 v154, v154
	v_lshl_add_u64 v[146:147], s[38:39], 0, v[146:147]
	v_mul_f32_e32 v154, v154, v156
	v_bfe_u32 v155, v154, 16, 1
	v_add3_u32 v154, v154, v155, s73
	global_store_short_d16_hi v[146:147], v154, off
	v_sub_f32_e32 v146, v141, v145
	v_mul_f32_e32 v146, 0x3fb8aa3b, v146
	v_exp_f32_e32 v146, v146
	s_nop 0
	v_mul_f32_e32 v146, v146, v156
	v_bfe_u32 v147, v146, 16, 1
	v_add3_u32 v154, v146, v147, s73
	v_lshlrev_b32_e32 v146, 1, v28
	v_mov_b32_e32 v147, v3
	v_lshl_add_u64 v[146:147], v[6:7], 0, v[146:147]
	v_and_or_b32 v220, v154, s98, v220
	ds_read_u16 v147, v61 offset:24576
	v_cndmask_b32_e64 v146, v241, v183, s[4:5]
	v_add_f32_e32 v145, v146, v145
	ds_read_u16 v146, v61 offset:8192
	s_waitcnt lgkmcnt(1)
	v_lshlrev_b32_e32 v156, 16, v147
	v_mul_f32_e32 v147, 0x3fb8aa3b, v145
	v_exp_f32_e32 v147, v147
	s_waitcnt lgkmcnt(0)
	v_lshlrev_b32_e32 v146, 16, v146
	v_mul_f32_e32 v146, 0x3db504f3, v146
	v_mul_f32_e32 v146, v147, v146
	v_bfe_u32 v147, v146, 16, 1
	v_add3_u32 v157, v146, v147, s73
	v_or_b32_e32 v146, v142, v30
	v_mov_b32_e32 v147, v143
	v_lshlrev_b64 v[146:147], 8, v[146:147]
	v_or_b32_e32 v146, v146, v144
	v_lshl_add_u64 v[154:155], s[36:37], 0, v[146:147]
	global_store_short_d16_hi v[154:155], v157, off
	v_mul_f32_e32 v154, 0xbfb8aa3b, v145
	v_exp_f32_e32 v154, v154
	v_lshl_add_u64 v[146:147], s[38:39], 0, v[146:147]
	v_mul_f32_e32 v154, v154, v156
	v_bfe_u32 v155, v154, 16, 1
	v_add3_u32 v154, v154, v155, s73
	global_store_short_d16_hi v[146:147], v154, off
	v_sub_f32_e32 v146, v141, v145
	v_mul_f32_e32 v146, 0x3fb8aa3b, v146
	v_exp_f32_e32 v146, v146
	s_nop 0
	v_mul_f32_e32 v146, v146, v156
	v_bfe_u32 v147, v146, 16, 1
	v_add3_u32 v154, v146, v147, s73
	v_lshlrev_b32_e32 v146, 1, v30
	v_mov_b32_e32 v147, v3
	v_lshl_add_u64 v[146:147], v[6:7], 0, v[146:147]
	v_lshrrev_b32_e32 v221, 16, v154
	ds_read_u16 v147, v63 offset:24576
	v_cndmask_b32_e64 v146, v235, v184, s[4:5]
	v_add_f32_e32 v145, v146, v145
	ds_read_u16 v146, v63 offset:8192
	s_waitcnt lgkmcnt(1)
	v_lshlrev_b32_e32 v156, 16, v147
	v_mul_f32_e32 v147, 0x3fb8aa3b, v145
	v_exp_f32_e32 v147, v147
	s_waitcnt lgkmcnt(0)
	v_lshlrev_b32_e32 v146, 16, v146
	v_mul_f32_e32 v146, 0x3db504f3, v146
	v_mul_f32_e32 v146, v147, v146
	v_bfe_u32 v147, v146, 16, 1
	v_add3_u32 v157, v146, v147, s73
	v_or_b32_e32 v146, v142, v32
	v_mov_b32_e32 v147, v143
	v_lshlrev_b64 v[146:147], 8, v[146:147]
	v_or_b32_e32 v146, v146, v144
	v_lshl_add_u64 v[154:155], s[36:37], 0, v[146:147]
	global_store_short_d16_hi v[154:155], v157, off
	v_mul_f32_e32 v154, 0xbfb8aa3b, v145
	v_exp_f32_e32 v154, v154
	v_lshl_add_u64 v[146:147], s[38:39], 0, v[146:147]
	v_mul_f32_e32 v154, v154, v156
	v_bfe_u32 v155, v154, 16, 1
	v_add3_u32 v154, v154, v155, s73
	global_store_short_d16_hi v[146:147], v154, off
	v_sub_f32_e32 v146, v141, v145
	v_mul_f32_e32 v146, 0x3fb8aa3b, v146
	v_exp_f32_e32 v146, v146
	s_nop 0
	v_mul_f32_e32 v146, v146, v156
	v_bfe_u32 v147, v146, 16, 1
	v_add3_u32 v154, v146, v147, s73
	v_lshlrev_b32_e32 v146, 1, v32
	v_mov_b32_e32 v147, v3
	v_lshl_add_u64 v[146:147], v[6:7], 0, v[146:147]
	v_and_or_b32 v221, v154, s98, v221
	ds_read_u16 v147, v65 offset:24576
	v_cndmask_b32_e64 v146, v244, v185, s[4:5]
	v_add_f32_e32 v145, v146, v145
	ds_read_u16 v146, v65 offset:8192
	s_waitcnt lgkmcnt(1)
	v_lshlrev_b32_e32 v156, 16, v147
	v_mul_f32_e32 v147, 0x3fb8aa3b, v145
	v_exp_f32_e32 v147, v147
	s_waitcnt lgkmcnt(0)
	v_lshlrev_b32_e32 v146, 16, v146
	v_mul_f32_e32 v146, 0x3db504f3, v146
	v_mul_f32_e32 v146, v147, v146
	v_bfe_u32 v147, v146, 16, 1
	v_add3_u32 v157, v146, v147, s73
	v_or_b32_e32 v146, v142, v34
	v_mov_b32_e32 v147, v143
	v_lshlrev_b64 v[146:147], 8, v[146:147]
	v_or_b32_e32 v146, v146, v144
	v_lshl_add_u64 v[154:155], s[36:37], 0, v[146:147]
	global_store_short_d16_hi v[154:155], v157, off
	v_mul_f32_e32 v154, 0xbfb8aa3b, v145
	v_exp_f32_e32 v154, v154
	v_lshl_add_u64 v[146:147], s[38:39], 0, v[146:147]
	v_mul_f32_e32 v154, v154, v156
	v_bfe_u32 v155, v154, 16, 1
	v_add3_u32 v154, v154, v155, s73
	global_store_short_d16_hi v[146:147], v154, off
	v_sub_f32_e32 v146, v141, v145
	v_mul_f32_e32 v146, 0x3fb8aa3b, v146
	v_exp_f32_e32 v146, v146
	s_nop 0
	v_mul_f32_e32 v146, v146, v156
	v_bfe_u32 v147, v146, 16, 1
	v_add3_u32 v154, v146, v147, s73
	v_lshlrev_b32_e32 v146, 1, v34
	v_mov_b32_e32 v147, v3
	v_lshl_add_u64 v[146:147], v[6:7], 0, v[146:147]
	v_lshrrev_b32_e32 v222, 16, v154
	ds_read_u16 v147, v67 offset:24576
	v_cndmask_b32_e64 v146, v242, v186, s[4:5]
	v_add_f32_e32 v145, v146, v145
	ds_read_u16 v146, v67 offset:8192
	s_waitcnt lgkmcnt(1)
	v_lshlrev_b32_e32 v156, 16, v147
	v_mul_f32_e32 v147, 0x3fb8aa3b, v145
	v_exp_f32_e32 v147, v147
	s_waitcnt lgkmcnt(0)
	v_lshlrev_b32_e32 v146, 16, v146
	v_mul_f32_e32 v146, 0x3db504f3, v146
	v_mul_f32_e32 v146, v147, v146
	v_bfe_u32 v147, v146, 16, 1
	v_add3_u32 v157, v146, v147, s73
	v_or_b32_e32 v146, v142, v38
	v_mov_b32_e32 v147, v143
	v_lshlrev_b64 v[146:147], 8, v[146:147]
	v_or_b32_e32 v146, v146, v144
	v_lshl_add_u64 v[154:155], s[36:37], 0, v[146:147]
	global_store_short_d16_hi v[154:155], v157, off
	v_mul_f32_e32 v154, 0xbfb8aa3b, v145
	v_exp_f32_e32 v154, v154
	v_lshl_add_u64 v[146:147], s[38:39], 0, v[146:147]
	v_mul_f32_e32 v154, v154, v156
	v_bfe_u32 v155, v154, 16, 1
	v_add3_u32 v154, v154, v155, s73
	global_store_short_d16_hi v[146:147], v154, off
	v_sub_f32_e32 v146, v141, v145
	v_mul_f32_e32 v146, 0x3fb8aa3b, v146
	v_exp_f32_e32 v146, v146
	s_nop 0
	v_mul_f32_e32 v146, v146, v156
	v_bfe_u32 v147, v146, 16, 1
	v_add3_u32 v154, v146, v147, s73
	v_lshlrev_b32_e32 v146, 1, v38
	v_mov_b32_e32 v147, v3
	v_lshl_add_u64 v[146:147], v[6:7], 0, v[146:147]
	v_and_or_b32 v222, v154, s98, v222
	ds_read_u16 v147, v69 offset:24576
	v_cndmask_b32_e64 v146, v237, v187, s[4:5]
	v_add_f32_e32 v145, v146, v145
	ds_read_u16 v146, v69 offset:8192
	s_waitcnt lgkmcnt(1)
	v_lshlrev_b32_e32 v156, 16, v147
	v_mul_f32_e32 v147, 0x3fb8aa3b, v145
	v_exp_f32_e32 v147, v147
	s_waitcnt lgkmcnt(0)
	v_lshlrev_b32_e32 v146, 16, v146
	v_mul_f32_e32 v146, 0x3db504f3, v146
	v_mul_f32_e32 v146, v147, v146
	v_bfe_u32 v147, v146, 16, 1
	v_add3_u32 v157, v146, v147, s73
	v_or_b32_e32 v146, v142, v40
	v_mov_b32_e32 v147, v143
	v_lshlrev_b64 v[146:147], 8, v[146:147]
	v_or_b32_e32 v146, v146, v144
	v_lshl_add_u64 v[154:155], s[36:37], 0, v[146:147]
	global_store_short_d16_hi v[154:155], v157, off
	v_mul_f32_e32 v154, 0xbfb8aa3b, v145
	v_exp_f32_e32 v154, v154
	v_lshl_add_u64 v[146:147], s[38:39], 0, v[146:147]
	v_mul_f32_e32 v154, v154, v156
	v_bfe_u32 v155, v154, 16, 1
	v_add3_u32 v154, v154, v155, s73
	global_store_short_d16_hi v[146:147], v154, off
	v_sub_f32_e32 v146, v141, v145
	v_mul_f32_e32 v146, 0x3fb8aa3b, v146
	v_exp_f32_e32 v146, v146
	s_nop 0
	v_mul_f32_e32 v146, v146, v156
	v_bfe_u32 v147, v146, 16, 1
	v_add3_u32 v154, v146, v147, s73
	v_lshlrev_b32_e32 v146, 1, v40
	v_mov_b32_e32 v147, v3
	v_lshl_add_u64 v[146:147], v[6:7], 0, v[146:147]
	v_lshrrev_b32_e32 v223, 16, v154
	ds_read_u16 v147, v71 offset:24576
	v_cndmask_b32_e64 v146, v215, v188, s[4:5]
	v_add_f32_e32 v145, v146, v145
	ds_read_u16 v146, v71 offset:8192
	s_waitcnt lgkmcnt(1)
	v_lshlrev_b32_e32 v156, 16, v147
	v_mul_f32_e32 v147, 0x3fb8aa3b, v145
	v_exp_f32_e32 v147, v147
	s_waitcnt lgkmcnt(0)
	v_lshlrev_b32_e32 v146, 16, v146
	v_mul_f32_e32 v146, 0x3db504f3, v146
	v_mul_f32_e32 v146, v147, v146
	v_bfe_u32 v147, v146, 16, 1
	v_add3_u32 v157, v146, v147, s73
	v_or_b32_e32 v146, v142, v42
	v_mov_b32_e32 v147, v143
	v_lshlrev_b64 v[146:147], 8, v[146:147]
	v_or_b32_e32 v146, v146, v144
	v_lshl_add_u64 v[154:155], s[36:37], 0, v[146:147]
	global_store_short_d16_hi v[154:155], v157, off
	v_mul_f32_e32 v154, 0xbfb8aa3b, v145
	v_exp_f32_e32 v154, v154
	v_lshl_add_u64 v[146:147], s[38:39], 0, v[146:147]
	v_mul_f32_e32 v154, v154, v156
	v_bfe_u32 v155, v154, 16, 1
	v_add3_u32 v154, v154, v155, s73
	global_store_short_d16_hi v[146:147], v154, off
	v_sub_f32_e32 v146, v141, v145
	v_mul_f32_e32 v146, 0x3fb8aa3b, v146
	v_exp_f32_e32 v146, v146
	s_nop 0
	v_mul_f32_e32 v146, v146, v156
	v_bfe_u32 v147, v146, 16, 1
	v_add3_u32 v154, v146, v147, s73
	v_lshlrev_b32_e32 v146, 1, v42
	v_mov_b32_e32 v147, v3
	v_lshl_add_u64 v[146:147], v[6:7], 0, v[146:147]
	v_and_or_b32 v223, v154, s98, v223
	v_alignbit_b32 v226, v223, v223, 16
	v_alignbit_b32 v218, v220, v220, 16
	v_cndmask_b32_e64 v220, v226, v220, s[4:5]
	v_cndmask_b32_e64 v223, v218, v223, s[4:5]
	v_alignbit_b32 v226, v222, v222, 16
	v_alignbit_b32 v218, v221, v221, 16
	v_cndmask_b32_e64 v221, v226, v221, s[4:5]
	v_cndmask_b32_e64 v222, v218, v222, s[4:5]
	v_lshl_add_u64 v[218:219], v[146:147], 0, v[224:225]
	global_store_dwordx4 v[218:219], v[220:223], off
	s_nop 1
	ds_read_u16 v147, v73 offset:24576
	v_cndmask_b32_e64 v146, v240, v189, s[4:5]
	v_add_f32_e32 v145, v146, v145
	ds_read_u16 v146, v73 offset:8192
	s_waitcnt lgkmcnt(1)
	v_lshlrev_b32_e32 v156, 16, v147
	v_mul_f32_e32 v147, 0x3fb8aa3b, v145
	v_exp_f32_e32 v147, v147
	s_waitcnt lgkmcnt(0)
	v_lshlrev_b32_e32 v146, 16, v146
	v_mul_f32_e32 v146, 0x3db504f3, v146
	v_mul_f32_e32 v146, v147, v146
	v_bfe_u32 v147, v146, 16, 1
	v_add3_u32 v157, v146, v147, s73
	v_or_b32_e32 v146, v142, v44
	v_mov_b32_e32 v147, v143
	v_lshlrev_b64 v[146:147], 8, v[146:147]
	v_or_b32_e32 v146, v146, v144
	v_lshl_add_u64 v[154:155], s[36:37], 0, v[146:147]
	global_store_short_d16_hi v[154:155], v157, off
	v_mul_f32_e32 v154, 0xbfb8aa3b, v145
	v_exp_f32_e32 v154, v154
	v_lshl_add_u64 v[146:147], s[38:39], 0, v[146:147]
	v_mul_f32_e32 v154, v154, v156
	v_bfe_u32 v155, v154, 16, 1
	v_add3_u32 v154, v154, v155, s73
	global_store_short_d16_hi v[146:147], v154, off
	v_sub_f32_e32 v146, v141, v145
	v_mul_f32_e32 v146, 0x3fb8aa3b, v146
	v_exp_f32_e32 v146, v146
	s_nop 0
	v_mul_f32_e32 v146, v146, v156
	v_bfe_u32 v147, v146, 16, 1
	v_add3_u32 v154, v146, v147, s73
	v_lshlrev_b32_e32 v146, 1, v44
	v_mov_b32_e32 v147, v3
	v_lshl_add_u64 v[146:147], v[6:7], 0, v[146:147]
	v_lshrrev_b32_e32 v220, 16, v154
	ds_read_u16 v147, v75 offset:24576
	v_cndmask_b32_e64 v146, v238, v190, s[4:5]
	v_add_f32_e32 v145, v146, v145
	ds_read_u16 v146, v75 offset:8192
	s_waitcnt lgkmcnt(1)
	v_lshlrev_b32_e32 v156, 16, v147
	v_mul_f32_e32 v147, 0x3fb8aa3b, v145
	v_exp_f32_e32 v147, v147
	s_waitcnt lgkmcnt(0)
	v_lshlrev_b32_e32 v146, 16, v146
	v_mul_f32_e32 v146, 0x3db504f3, v146
	v_mul_f32_e32 v146, v147, v146
	v_bfe_u32 v147, v146, 16, 1
	v_add3_u32 v157, v146, v147, s73
	v_or_b32_e32 v146, v142, v46
	v_mov_b32_e32 v147, v143
	v_lshlrev_b64 v[146:147], 8, v[146:147]
	v_or_b32_e32 v146, v146, v144
	v_lshl_add_u64 v[154:155], s[36:37], 0, v[146:147]
	global_store_short_d16_hi v[154:155], v157, off
	v_mul_f32_e32 v154, 0xbfb8aa3b, v145
	v_exp_f32_e32 v154, v154
	v_lshl_add_u64 v[146:147], s[38:39], 0, v[146:147]
	v_mul_f32_e32 v154, v154, v156
	v_bfe_u32 v155, v154, 16, 1
	v_add3_u32 v154, v154, v155, s73
	global_store_short_d16_hi v[146:147], v154, off
	v_sub_f32_e32 v146, v141, v145
	v_mul_f32_e32 v146, 0x3fb8aa3b, v146
	v_exp_f32_e32 v146, v146
	s_nop 0
	v_mul_f32_e32 v146, v146, v156
	v_bfe_u32 v147, v146, 16, 1
	v_add3_u32 v154, v146, v147, s73
	v_lshlrev_b32_e32 v146, 1, v46
	v_mov_b32_e32 v147, v3
	v_lshl_add_u64 v[146:147], v[6:7], 0, v[146:147]
	v_and_or_b32 v220, v154, s98, v220
	ds_read_u16 v147, v77 offset:24576
	v_cndmask_b32_e64 v146, v217, v191, s[4:5]
	v_add_f32_e32 v145, v146, v145
	ds_read_u16 v146, v77 offset:8192
	s_waitcnt lgkmcnt(1)
	v_lshlrev_b32_e32 v156, 16, v147
	v_mul_f32_e32 v147, 0x3fb8aa3b, v145
	v_exp_f32_e32 v147, v147
	s_waitcnt lgkmcnt(0)
	v_lshlrev_b32_e32 v146, 16, v146
	v_mul_f32_e32 v146, 0x3db504f3, v146
	v_mul_f32_e32 v146, v147, v146
	v_bfe_u32 v147, v146, 16, 1
	v_add3_u32 v157, v146, v147, s73
	v_or_b32_e32 v146, v142, v48
	v_mov_b32_e32 v147, v143
	v_lshlrev_b64 v[146:147], 8, v[146:147]
	v_or_b32_e32 v146, v146, v144
	v_lshl_add_u64 v[154:155], s[36:37], 0, v[146:147]
	global_store_short_d16_hi v[154:155], v157, off
	v_mul_f32_e32 v154, 0xbfb8aa3b, v145
	v_exp_f32_e32 v154, v154
	v_lshl_add_u64 v[146:147], s[38:39], 0, v[146:147]
	v_mul_f32_e32 v154, v154, v156
	v_bfe_u32 v155, v154, 16, 1
	v_add3_u32 v154, v154, v155, s73
	global_store_short_d16_hi v[146:147], v154, off
	v_sub_f32_e32 v146, v141, v145
	v_mul_f32_e32 v146, 0x3fb8aa3b, v146
	v_exp_f32_e32 v146, v146
	s_nop 0
	v_mul_f32_e32 v146, v146, v156
	v_bfe_u32 v147, v146, 16, 1
	v_add3_u32 v154, v146, v147, s73
	v_lshlrev_b32_e32 v146, 1, v48
	v_mov_b32_e32 v147, v3
	v_lshl_add_u64 v[146:147], v[6:7], 0, v[146:147]
	v_lshrrev_b32_e32 v221, 16, v154
	ds_read_u16 v147, v79 offset:24576
	v_cndmask_b32_e64 v146, v211, v192, s[4:5]
	v_add_f32_e32 v145, v146, v145
	ds_read_u16 v146, v79 offset:8192
	s_waitcnt lgkmcnt(1)
	v_lshlrev_b32_e32 v156, 16, v147
	v_mul_f32_e32 v147, 0x3fb8aa3b, v145
	v_exp_f32_e32 v147, v147
	s_waitcnt lgkmcnt(0)
	v_lshlrev_b32_e32 v146, 16, v146
	v_mul_f32_e32 v146, 0x3db504f3, v146
	v_mul_f32_e32 v146, v147, v146
	v_bfe_u32 v147, v146, 16, 1
	v_add3_u32 v157, v146, v147, s73
	v_or_b32_e32 v146, v142, v50
	v_mov_b32_e32 v147, v143
	v_lshlrev_b64 v[146:147], 8, v[146:147]
	v_or_b32_e32 v146, v146, v144
	v_lshl_add_u64 v[154:155], s[36:37], 0, v[146:147]
	global_store_short_d16_hi v[154:155], v157, off
	v_mul_f32_e32 v154, 0xbfb8aa3b, v145
	v_exp_f32_e32 v154, v154
	v_lshl_add_u64 v[146:147], s[38:39], 0, v[146:147]
	v_mul_f32_e32 v154, v154, v156
	v_bfe_u32 v155, v154, 16, 1
	v_add3_u32 v154, v154, v155, s73
	global_store_short_d16_hi v[146:147], v154, off
	v_sub_f32_e32 v146, v141, v145
	v_mul_f32_e32 v146, 0x3fb8aa3b, v146
	v_exp_f32_e32 v146, v146
	s_nop 0
	v_mul_f32_e32 v146, v146, v156
	v_bfe_u32 v147, v146, 16, 1
	v_add3_u32 v154, v146, v147, s73
	v_lshlrev_b32_e32 v146, 1, v50
	v_mov_b32_e32 v147, v3
	v_lshl_add_u64 v[146:147], v[6:7], 0, v[146:147]
	v_and_or_b32 v221, v154, s98, v221
	ds_read_u16 v147, v81 offset:24576
	v_cndmask_b32_e64 v146, v236, v193, s[4:5]
	v_add_f32_e32 v145, v146, v145
	ds_read_u16 v146, v81 offset:8192
	s_waitcnt lgkmcnt(1)
	v_lshlrev_b32_e32 v156, 16, v147
	v_mul_f32_e32 v147, 0x3fb8aa3b, v145
	v_exp_f32_e32 v147, v147
	s_waitcnt lgkmcnt(0)
	v_lshlrev_b32_e32 v146, 16, v146
	v_mul_f32_e32 v146, 0x3db504f3, v146
	v_mul_f32_e32 v146, v147, v146
	v_bfe_u32 v147, v146, 16, 1
	v_add3_u32 v157, v146, v147, s73
	v_or_b32_e32 v146, v142, v52
	v_mov_b32_e32 v147, v143
	v_lshlrev_b64 v[146:147], 8, v[146:147]
	v_or_b32_e32 v146, v146, v144
	v_lshl_add_u64 v[154:155], s[36:37], 0, v[146:147]
	global_store_short_d16_hi v[154:155], v157, off
	v_mul_f32_e32 v154, 0xbfb8aa3b, v145
	v_exp_f32_e32 v154, v154
	v_lshl_add_u64 v[146:147], s[38:39], 0, v[146:147]
	v_mul_f32_e32 v154, v154, v156
	v_bfe_u32 v155, v154, 16, 1
	v_add3_u32 v154, v154, v155, s73
	global_store_short_d16_hi v[146:147], v154, off
	v_sub_f32_e32 v146, v141, v145
	v_mul_f32_e32 v146, 0x3fb8aa3b, v146
	v_exp_f32_e32 v146, v146
	s_nop 0
	v_mul_f32_e32 v146, v146, v156
	v_bfe_u32 v147, v146, 16, 1
	v_add3_u32 v154, v146, v147, s73
	v_lshlrev_b32_e32 v146, 1, v52
	v_mov_b32_e32 v147, v3
	v_lshl_add_u64 v[146:147], v[6:7], 0, v[146:147]
	v_lshrrev_b32_e32 v222, 16, v154
	ds_read_u16 v147, v83 offset:24576
	v_cndmask_b32_e64 v146, v234, v194, s[4:5]
	v_add_f32_e32 v145, v146, v145
	ds_read_u16 v146, v83 offset:8192
	s_waitcnt lgkmcnt(1)
	v_lshlrev_b32_e32 v156, 16, v147
	v_mul_f32_e32 v147, 0x3fb8aa3b, v145
	v_exp_f32_e32 v147, v147
	s_waitcnt lgkmcnt(0)
	v_lshlrev_b32_e32 v146, 16, v146
	v_mul_f32_e32 v146, 0x3db504f3, v146
	v_mul_f32_e32 v146, v147, v146
	v_bfe_u32 v147, v146, 16, 1
	v_add3_u32 v157, v146, v147, s73
	v_or_b32_e32 v146, v142, v54
	v_mov_b32_e32 v147, v143
	v_lshlrev_b64 v[146:147], 8, v[146:147]
	v_or_b32_e32 v146, v146, v144
	v_lshl_add_u64 v[154:155], s[36:37], 0, v[146:147]
	global_store_short_d16_hi v[154:155], v157, off
	v_mul_f32_e32 v154, 0xbfb8aa3b, v145
	v_exp_f32_e32 v154, v154
	v_lshl_add_u64 v[146:147], s[38:39], 0, v[146:147]
	v_mul_f32_e32 v154, v154, v156
	v_bfe_u32 v155, v154, 16, 1
	v_add3_u32 v154, v154, v155, s73
	global_store_short_d16_hi v[146:147], v154, off
	v_sub_f32_e32 v146, v141, v145
	v_mul_f32_e32 v146, 0x3fb8aa3b, v146
	v_exp_f32_e32 v146, v146
	s_nop 0
	v_mul_f32_e32 v146, v146, v156
	v_bfe_u32 v147, v146, 16, 1
	v_add3_u32 v154, v146, v147, s73
	v_lshlrev_b32_e32 v146, 1, v54
	v_mov_b32_e32 v147, v3
	v_lshl_add_u64 v[146:147], v[6:7], 0, v[146:147]
	v_and_or_b32 v222, v154, s98, v222
	ds_read_u16 v147, v85 offset:24576
	v_cndmask_b32_e64 v146, v213, v195, s[4:5]
	v_add_f32_e32 v145, v146, v145
	ds_read_u16 v146, v85 offset:8192
	s_waitcnt lgkmcnt(1)
	v_lshlrev_b32_e32 v156, 16, v147
	v_mul_f32_e32 v147, 0x3fb8aa3b, v145
	v_exp_f32_e32 v147, v147
	s_waitcnt lgkmcnt(0)
	v_lshlrev_b32_e32 v146, 16, v146
	v_mul_f32_e32 v146, 0x3db504f3, v146
	v_mul_f32_e32 v146, v147, v146
	v_bfe_u32 v147, v146, 16, 1
	v_add3_u32 v157, v146, v147, s73
	v_or_b32_e32 v146, v142, v56
	v_mov_b32_e32 v147, v143
	v_lshlrev_b64 v[146:147], 8, v[146:147]
	v_or_b32_e32 v146, v146, v144
	v_lshl_add_u64 v[154:155], s[36:37], 0, v[146:147]
	global_store_short_d16_hi v[154:155], v157, off
	v_mul_f32_e32 v154, 0xbfb8aa3b, v145
	v_exp_f32_e32 v154, v154
	v_lshl_add_u64 v[146:147], s[38:39], 0, v[146:147]
	v_mul_f32_e32 v154, v154, v156
	v_bfe_u32 v155, v154, 16, 1
	v_add3_u32 v154, v154, v155, s73
	global_store_short_d16_hi v[146:147], v154, off
	v_sub_f32_e32 v146, v141, v145
	v_mul_f32_e32 v146, 0x3fb8aa3b, v146
	v_exp_f32_e32 v146, v146
	s_nop 0
	v_mul_f32_e32 v146, v146, v156
	v_bfe_u32 v147, v146, 16, 1
	v_add3_u32 v154, v146, v147, s73
	v_lshlrev_b32_e32 v146, 1, v56
	v_mov_b32_e32 v147, v3
	v_lshl_add_u64 v[146:147], v[6:7], 0, v[146:147]
	v_lshrrev_b32_e32 v223, 16, v154
	ds_read_u16 v147, v87 offset:24576
	v_cndmask_b32_e64 v146, v208, v196, s[4:5]
	v_add_f32_e32 v145, v146, v145
	ds_read_u16 v146, v87 offset:8192
	s_waitcnt lgkmcnt(1)
	v_lshlrev_b32_e32 v156, 16, v147
	v_mul_f32_e32 v147, 0x3fb8aa3b, v145
	v_exp_f32_e32 v147, v147
	s_waitcnt lgkmcnt(0)
	v_lshlrev_b32_e32 v146, 16, v146
	v_mul_f32_e32 v146, 0x3db504f3, v146
	v_mul_f32_e32 v146, v147, v146
	v_bfe_u32 v147, v146, 16, 1
	v_add3_u32 v157, v146, v147, s73
	v_or_b32_e32 v146, v142, v58
	v_mov_b32_e32 v147, v143
	v_lshlrev_b64 v[146:147], 8, v[146:147]
	v_or_b32_e32 v146, v146, v144
	v_lshl_add_u64 v[154:155], s[36:37], 0, v[146:147]
	global_store_short_d16_hi v[154:155], v157, off
	v_mul_f32_e32 v154, 0xbfb8aa3b, v145
	v_exp_f32_e32 v154, v154
	v_lshl_add_u64 v[146:147], s[38:39], 0, v[146:147]
	v_mul_f32_e32 v154, v154, v156
	v_bfe_u32 v155, v154, 16, 1
	v_add3_u32 v154, v154, v155, s73
	global_store_short_d16_hi v[146:147], v154, off
	v_sub_f32_e32 v146, v141, v145
	v_mul_f32_e32 v146, 0x3fb8aa3b, v146
	v_exp_f32_e32 v146, v146
	s_nop 0
	v_mul_f32_e32 v146, v146, v156
	v_bfe_u32 v147, v146, 16, 1
	v_add3_u32 v154, v146, v147, s73
	v_lshlrev_b32_e32 v146, 1, v58
	v_mov_b32_e32 v147, v3
	v_lshl_add_u64 v[146:147], v[6:7], 0, v[146:147]
	v_and_or_b32 v223, v154, s98, v223
	v_alignbit_b32 v226, v223, v223, 16
	v_alignbit_b32 v218, v220, v220, 16
	v_cndmask_b32_e64 v220, v226, v220, s[4:5]
	v_cndmask_b32_e64 v223, v218, v223, s[4:5]
	v_alignbit_b32 v226, v222, v222, 16
	v_alignbit_b32 v218, v221, v221, 16
	v_cndmask_b32_e64 v221, v226, v221, s[4:5]
	v_cndmask_b32_e64 v222, v218, v222, s[4:5]
	v_lshl_add_u64 v[218:219], v[146:147], 0, v[224:225]
	global_store_dwordx4 v[218:219], v[220:223], off
	s_nop 1
	ds_read_u16 v147, v89 offset:24576
	v_cndmask_b32_e64 v146, v216, v197, s[4:5]
	v_add_f32_e32 v145, v146, v145
	ds_read_u16 v146, v89 offset:8192
	s_waitcnt lgkmcnt(1)
	v_lshlrev_b32_e32 v156, 16, v147
	v_mul_f32_e32 v147, 0x3fb8aa3b, v145
	v_exp_f32_e32 v147, v147
	s_waitcnt lgkmcnt(0)
	v_lshlrev_b32_e32 v146, 16, v146
	v_mul_f32_e32 v146, 0x3db504f3, v146
	v_mul_f32_e32 v146, v147, v146
	v_bfe_u32 v147, v146, 16, 1
	v_add3_u32 v157, v146, v147, s73
	v_or_b32_e32 v146, v142, v60
	v_mov_b32_e32 v147, v143
	v_lshlrev_b64 v[146:147], 8, v[146:147]
	v_or_b32_e32 v146, v146, v144
	v_lshl_add_u64 v[154:155], s[36:37], 0, v[146:147]
	global_store_short_d16_hi v[154:155], v157, off
	v_mul_f32_e32 v154, 0xbfb8aa3b, v145
	v_exp_f32_e32 v154, v154
	v_lshl_add_u64 v[146:147], s[38:39], 0, v[146:147]
	v_mul_f32_e32 v154, v154, v156
	v_bfe_u32 v155, v154, 16, 1
	v_add3_u32 v154, v154, v155, s73
	global_store_short_d16_hi v[146:147], v154, off
	v_sub_f32_e32 v146, v141, v145
	v_mul_f32_e32 v146, 0x3fb8aa3b, v146
	v_exp_f32_e32 v146, v146
	s_nop 0
	v_mul_f32_e32 v146, v146, v156
	v_bfe_u32 v147, v146, 16, 1
	v_add3_u32 v154, v146, v147, s73
	v_lshlrev_b32_e32 v146, 1, v60
	v_mov_b32_e32 v147, v3
	v_lshl_add_u64 v[146:147], v[6:7], 0, v[146:147]
	v_lshrrev_b32_e32 v220, 16, v154
	ds_read_u16 v147, v91 offset:24576
	v_cndmask_b32_e64 v146, v214, v198, s[4:5]
	v_add_f32_e32 v145, v146, v145
	ds_read_u16 v146, v91 offset:8192
	s_waitcnt lgkmcnt(1)
	v_lshlrev_b32_e32 v156, 16, v147
	v_mul_f32_e32 v147, 0x3fb8aa3b, v145
	v_exp_f32_e32 v147, v147
	s_waitcnt lgkmcnt(0)
	v_lshlrev_b32_e32 v146, 16, v146
	v_mul_f32_e32 v146, 0x3db504f3, v146
	v_mul_f32_e32 v146, v147, v146
	v_bfe_u32 v147, v146, 16, 1
	v_add3_u32 v157, v146, v147, s73
	v_or_b32_e32 v146, v142, v62
	v_mov_b32_e32 v147, v143
	v_lshlrev_b64 v[146:147], 8, v[146:147]
	v_or_b32_e32 v146, v146, v144
	v_lshl_add_u64 v[154:155], s[36:37], 0, v[146:147]
	global_store_short_d16_hi v[154:155], v157, off
	v_mul_f32_e32 v154, 0xbfb8aa3b, v145
	v_exp_f32_e32 v154, v154
	v_lshl_add_u64 v[146:147], s[38:39], 0, v[146:147]
	v_mul_f32_e32 v154, v154, v156
	v_bfe_u32 v155, v154, 16, 1
	v_add3_u32 v154, v154, v155, s73
	global_store_short_d16_hi v[146:147], v154, off
	v_sub_f32_e32 v146, v141, v145
	v_mul_f32_e32 v146, 0x3fb8aa3b, v146
	v_exp_f32_e32 v146, v146
	s_nop 0
	v_mul_f32_e32 v146, v146, v156
	v_bfe_u32 v147, v146, 16, 1
	v_add3_u32 v154, v146, v147, s73
	v_lshlrev_b32_e32 v146, 1, v62
	v_mov_b32_e32 v147, v3
	v_lshl_add_u64 v[146:147], v[6:7], 0, v[146:147]
	v_and_or_b32 v220, v154, s98, v220
	ds_read_u16 v147, v93 offset:24576
	v_cndmask_b32_e64 v146, v209, v199, s[4:5]
	v_add_f32_e32 v145, v146, v145
	ds_read_u16 v146, v93 offset:8192
	s_waitcnt lgkmcnt(1)
	v_lshlrev_b32_e32 v156, 16, v147
	v_mul_f32_e32 v147, 0x3fb8aa3b, v145
	v_exp_f32_e32 v147, v147
	s_waitcnt lgkmcnt(0)
	v_lshlrev_b32_e32 v146, 16, v146
	v_mul_f32_e32 v146, 0x3db504f3, v146
	v_mul_f32_e32 v146, v147, v146
	v_bfe_u32 v147, v146, 16, 1
	v_add3_u32 v157, v146, v147, s73
	v_or_b32_e32 v146, v142, v64
	v_mov_b32_e32 v147, v143
	v_lshlrev_b64 v[146:147], 8, v[146:147]
	v_or_b32_e32 v146, v146, v144
	v_lshl_add_u64 v[154:155], s[36:37], 0, v[146:147]
	global_store_short_d16_hi v[154:155], v157, off
	v_mul_f32_e32 v154, 0xbfb8aa3b, v145
	v_exp_f32_e32 v154, v154
	v_lshl_add_u64 v[146:147], s[38:39], 0, v[146:147]
	v_mul_f32_e32 v154, v154, v156
	v_bfe_u32 v155, v154, 16, 1
	v_add3_u32 v154, v154, v155, s73
	global_store_short_d16_hi v[146:147], v154, off
	v_sub_f32_e32 v146, v141, v145
	v_mul_f32_e32 v146, 0x3fb8aa3b, v146
	v_exp_f32_e32 v146, v146
	s_nop 0
	v_mul_f32_e32 v146, v146, v156
	v_bfe_u32 v147, v146, 16, 1
	v_add3_u32 v154, v146, v147, s73
	v_lshlrev_b32_e32 v146, 1, v64
	v_mov_b32_e32 v147, v3
	v_lshl_add_u64 v[146:147], v[6:7], 0, v[146:147]
	v_lshrrev_b32_e32 v221, 16, v154
	ds_read_u16 v147, v95 offset:24576
	v_cndmask_b32_e64 v146, v206, v200, s[4:5]
	v_add_f32_e32 v145, v146, v145
	ds_read_u16 v146, v95 offset:8192
	s_waitcnt lgkmcnt(1)
	v_lshlrev_b32_e32 v156, 16, v147
	v_mul_f32_e32 v147, 0x3fb8aa3b, v145
	v_exp_f32_e32 v147, v147
	s_waitcnt lgkmcnt(0)
	v_lshlrev_b32_e32 v146, 16, v146
	v_mul_f32_e32 v146, 0x3db504f3, v146
	v_mul_f32_e32 v146, v147, v146
	v_bfe_u32 v147, v146, 16, 1
	v_add3_u32 v157, v146, v147, s73
	v_or_b32_e32 v146, v142, v66
	v_mov_b32_e32 v147, v143
	v_lshlrev_b64 v[146:147], 8, v[146:147]
	v_or_b32_e32 v146, v146, v144
	v_lshl_add_u64 v[154:155], s[36:37], 0, v[146:147]
	global_store_short_d16_hi v[154:155], v157, off
	v_mul_f32_e32 v154, 0xbfb8aa3b, v145
	v_exp_f32_e32 v154, v154
	v_lshl_add_u64 v[146:147], s[38:39], 0, v[146:147]
	v_mul_f32_e32 v154, v154, v156
	v_bfe_u32 v155, v154, 16, 1
	v_add3_u32 v154, v154, v155, s73
	global_store_short_d16_hi v[146:147], v154, off
	v_sub_f32_e32 v146, v141, v145
	v_mul_f32_e32 v146, 0x3fb8aa3b, v146
	v_exp_f32_e32 v146, v146
	s_nop 0
	v_mul_f32_e32 v146, v146, v156
	v_bfe_u32 v147, v146, 16, 1
	v_add3_u32 v154, v146, v147, s73
	v_lshlrev_b32_e32 v146, 1, v66
	v_mov_b32_e32 v147, v3
	v_lshl_add_u64 v[146:147], v[6:7], 0, v[146:147]
	v_and_or_b32 v221, v154, s98, v221
	ds_read_u16 v147, v97 offset:24576
	v_cndmask_b32_e64 v146, v212, v201, s[4:5]
	v_add_f32_e32 v145, v146, v145
	ds_read_u16 v146, v97 offset:8192
	s_waitcnt lgkmcnt(1)
	v_lshlrev_b32_e32 v156, 16, v147
	v_mul_f32_e32 v147, 0x3fb8aa3b, v145
	v_exp_f32_e32 v147, v147
	s_waitcnt lgkmcnt(0)
	v_lshlrev_b32_e32 v146, 16, v146
	v_mul_f32_e32 v146, 0x3db504f3, v146
	v_mul_f32_e32 v146, v147, v146
	v_bfe_u32 v147, v146, 16, 1
	v_add3_u32 v157, v146, v147, s73
	v_or_b32_e32 v146, v142, v68
	v_mov_b32_e32 v147, v143
	v_lshlrev_b64 v[146:147], 8, v[146:147]
	v_or_b32_e32 v146, v146, v144
	v_lshl_add_u64 v[154:155], s[36:37], 0, v[146:147]
	global_store_short_d16_hi v[154:155], v157, off
	v_mul_f32_e32 v154, 0xbfb8aa3b, v145
	v_exp_f32_e32 v154, v154
	v_lshl_add_u64 v[146:147], s[38:39], 0, v[146:147]
	v_mul_f32_e32 v154, v154, v156
	v_bfe_u32 v155, v154, 16, 1
	v_add3_u32 v154, v154, v155, s73
	global_store_short_d16_hi v[146:147], v154, off
	v_sub_f32_e32 v146, v141, v145
	v_mul_f32_e32 v146, 0x3fb8aa3b, v146
	v_exp_f32_e32 v146, v146
	s_nop 0
	v_mul_f32_e32 v146, v146, v156
	v_bfe_u32 v147, v146, 16, 1
	v_add3_u32 v154, v146, v147, s73
	v_lshlrev_b32_e32 v146, 1, v68
	v_mov_b32_e32 v147, v3
	v_lshl_add_u64 v[146:147], v[6:7], 0, v[146:147]
	v_lshrrev_b32_e32 v222, 16, v154
	ds_read_u16 v147, v99 offset:24576
	v_cndmask_b32_e64 v146, v210, v202, s[4:5]
	v_add_f32_e32 v145, v146, v145
	ds_read_u16 v146, v99 offset:8192
	s_waitcnt lgkmcnt(1)
	v_lshlrev_b32_e32 v156, 16, v147
	v_mul_f32_e32 v147, 0x3fb8aa3b, v145
	v_exp_f32_e32 v147, v147
	s_waitcnt lgkmcnt(0)
	v_lshlrev_b32_e32 v146, 16, v146
	v_mul_f32_e32 v146, 0x3db504f3, v146
	v_mul_f32_e32 v146, v147, v146
	v_bfe_u32 v147, v146, 16, 1
	v_add3_u32 v157, v146, v147, s73
	v_or_b32_e32 v146, v142, v70
	v_mov_b32_e32 v147, v143
	v_lshlrev_b64 v[146:147], 8, v[146:147]
	v_or_b32_e32 v146, v146, v144
	v_lshl_add_u64 v[154:155], s[36:37], 0, v[146:147]
	global_store_short_d16_hi v[154:155], v157, off
	v_mul_f32_e32 v154, 0xbfb8aa3b, v145
	v_exp_f32_e32 v154, v154
	v_lshl_add_u64 v[146:147], s[38:39], 0, v[146:147]
	v_mul_f32_e32 v154, v154, v156
	v_bfe_u32 v155, v154, 16, 1
	v_add3_u32 v154, v154, v155, s73
	global_store_short_d16_hi v[146:147], v154, off
	v_sub_f32_e32 v146, v141, v145
	v_mul_f32_e32 v146, 0x3fb8aa3b, v146
	v_exp_f32_e32 v146, v146
	s_nop 0
	v_mul_f32_e32 v146, v146, v156
	v_bfe_u32 v147, v146, 16, 1
	v_add3_u32 v154, v146, v147, s73
	v_lshlrev_b32_e32 v146, 1, v70
	v_mov_b32_e32 v147, v3
	v_lshl_add_u64 v[146:147], v[6:7], 0, v[146:147]
	v_and_or_b32 v222, v154, s98, v222
	ds_read_u16 v147, v101 offset:24576
	v_cndmask_b32_e64 v146, v207, v203, s[4:5]
	v_add_f32_e32 v145, v146, v145
	ds_read_u16 v146, v101 offset:8192
	s_waitcnt lgkmcnt(1)
	v_lshlrev_b32_e32 v156, 16, v147
	v_mul_f32_e32 v147, 0x3fb8aa3b, v145
	v_exp_f32_e32 v147, v147
	s_waitcnt lgkmcnt(0)
	v_lshlrev_b32_e32 v146, 16, v146
	v_mul_f32_e32 v146, 0x3db504f3, v146
	v_mul_f32_e32 v146, v147, v146
	v_bfe_u32 v147, v146, 16, 1
	v_add3_u32 v157, v146, v147, s73
	v_or_b32_e32 v146, v142, v72
	v_mov_b32_e32 v147, v143
	v_lshlrev_b64 v[146:147], 8, v[146:147]
	v_or_b32_e32 v146, v146, v144
	v_lshl_add_u64 v[154:155], s[36:37], 0, v[146:147]
	global_store_short_d16_hi v[154:155], v157, off
	v_mul_f32_e32 v154, 0xbfb8aa3b, v145
	v_exp_f32_e32 v154, v154
	v_lshl_add_u64 v[146:147], s[38:39], 0, v[146:147]
	v_mul_f32_e32 v154, v154, v156
	v_bfe_u32 v155, v154, 16, 1
	v_add3_u32 v154, v154, v155, s73
	global_store_short_d16_hi v[146:147], v154, off
	v_sub_f32_e32 v146, v141, v145
	v_mul_f32_e32 v146, 0x3fb8aa3b, v146
	v_exp_f32_e32 v146, v146
	s_nop 0
	v_mul_f32_e32 v146, v146, v156
	v_bfe_u32 v147, v146, 16, 1
	v_add3_u32 v154, v146, v147, s73
	v_lshlrev_b32_e32 v146, 1, v72
	v_mov_b32_e32 v147, v3
	v_lshl_add_u64 v[146:147], v[6:7], 0, v[146:147]
	v_lshrrev_b32_e32 v223, 16, v154
	ds_read_u16 v147, v103 offset:24576
	v_cndmask_b32_e64 v146, v205, v204, s[4:5]
	v_add_f32_e32 v145, v146, v145
	ds_read_u16 v146, v103 offset:8192
	s_waitcnt lgkmcnt(1)
	v_lshlrev_b32_e32 v156, 16, v147
	v_mul_f32_e32 v147, 0x3fb8aa3b, v145
	v_exp_f32_e32 v147, v147
	s_waitcnt lgkmcnt(0)
	v_lshlrev_b32_e32 v146, 16, v146
	v_mul_f32_e32 v146, 0x3db504f3, v146
	v_mul_f32_e32 v146, v147, v146
	v_bfe_u32 v147, v146, 16, 1
	v_add3_u32 v157, v146, v147, s73
	v_or_b32_e32 v146, v142, v74
	v_mov_b32_e32 v147, v143
	v_lshlrev_b64 v[146:147], 8, v[146:147]
	v_or_b32_e32 v146, v146, v144
	v_lshl_add_u64 v[154:155], s[36:37], 0, v[146:147]
	global_store_short_d16_hi v[154:155], v157, off
	v_mul_f32_e32 v154, 0xbfb8aa3b, v145
	v_exp_f32_e32 v154, v154
	v_lshl_add_u64 v[146:147], s[38:39], 0, v[146:147]
	v_mul_f32_e32 v154, v154, v156
	v_bfe_u32 v155, v154, 16, 1
	v_add3_u32 v154, v154, v155, s73
	global_store_short_d16_hi v[146:147], v154, off
	v_sub_f32_e32 v146, v141, v145
	v_mul_f32_e32 v146, 0x3fb8aa3b, v146
	v_exp_f32_e32 v146, v146
	s_nop 0
	v_mul_f32_e32 v146, v146, v156
	v_bfe_u32 v147, v146, 16, 1
	v_add3_u32 v154, v146, v147, s73
	v_lshlrev_b32_e32 v146, 1, v74
	v_mov_b32_e32 v147, v3
	v_lshl_add_u64 v[146:147], v[6:7], 0, v[146:147]
	v_and_or_b32 v223, v154, s98, v223
	v_alignbit_b32 v226, v223, v223, 16
	v_alignbit_b32 v218, v220, v220, 16
	v_cndmask_b32_e64 v220, v226, v220, s[4:5]
	v_cndmask_b32_e64 v223, v218, v223, s[4:5]
	v_alignbit_b32 v226, v222, v222, 16
	v_alignbit_b32 v218, v221, v221, 16
	v_cndmask_b32_e64 v221, v226, v221, s[4:5]
	v_cndmask_b32_e64 v222, v218, v222, s[4:5]
	v_lshl_add_u64 v[218:219], v[146:147], 0, v[224:225]
	global_store_dwordx4 v[218:219], v[220:223], off
	s_nop 1
	ds_read_u16 v147, v105 offset:24576
	v_cndmask_b32_e64 v146, v204, v205, s[4:5]
	v_add_f32_e32 v145, v146, v145
	ds_read_u16 v146, v105 offset:8192
	s_waitcnt lgkmcnt(1)
	v_lshlrev_b32_e32 v156, 16, v147
	v_mul_f32_e32 v147, 0x3fb8aa3b, v145
	v_exp_f32_e32 v147, v147
	s_waitcnt lgkmcnt(0)
	v_lshlrev_b32_e32 v146, 16, v146
	v_mul_f32_e32 v146, 0x3db504f3, v146
	v_mul_f32_e32 v146, v147, v146
	v_bfe_u32 v147, v146, 16, 1
	v_add3_u32 v157, v146, v147, s73
	v_or_b32_e32 v146, v142, v76
	v_mov_b32_e32 v147, v143
	v_lshlrev_b64 v[146:147], 8, v[146:147]
	v_or_b32_e32 v146, v146, v144
	v_lshl_add_u64 v[154:155], s[36:37], 0, v[146:147]
	global_store_short_d16_hi v[154:155], v157, off
	v_mul_f32_e32 v154, 0xbfb8aa3b, v145
	v_exp_f32_e32 v154, v154
	v_lshl_add_u64 v[146:147], s[38:39], 0, v[146:147]
	v_mul_f32_e32 v154, v154, v156
	v_bfe_u32 v155, v154, 16, 1
	v_add3_u32 v154, v154, v155, s73
	global_store_short_d16_hi v[146:147], v154, off
	v_sub_f32_e32 v146, v141, v145
	v_mul_f32_e32 v146, 0x3fb8aa3b, v146
	v_exp_f32_e32 v146, v146
	s_nop 0
	v_mul_f32_e32 v146, v146, v156
	v_bfe_u32 v147, v146, 16, 1
	v_add3_u32 v154, v146, v147, s73
	v_lshlrev_b32_e32 v146, 1, v76
	v_mov_b32_e32 v147, v3
	v_lshl_add_u64 v[146:147], v[6:7], 0, v[146:147]
	v_lshrrev_b32_e32 v220, 16, v154
	ds_read_u16 v147, v107 offset:24576
	v_cndmask_b32_e64 v146, v203, v207, s[4:5]
	v_add_f32_e32 v145, v146, v145
	ds_read_u16 v146, v107 offset:8192
	s_waitcnt lgkmcnt(1)
	v_lshlrev_b32_e32 v156, 16, v147
	v_mul_f32_e32 v147, 0x3fb8aa3b, v145
	v_exp_f32_e32 v147, v147
	s_waitcnt lgkmcnt(0)
	v_lshlrev_b32_e32 v146, 16, v146
	v_mul_f32_e32 v146, 0x3db504f3, v146
	v_mul_f32_e32 v146, v147, v146
	v_bfe_u32 v147, v146, 16, 1
	v_add3_u32 v157, v146, v147, s73
	v_or_b32_e32 v146, v142, v78
	v_mov_b32_e32 v147, v143
	v_lshlrev_b64 v[146:147], 8, v[146:147]
	v_or_b32_e32 v146, v146, v144
	v_lshl_add_u64 v[154:155], s[36:37], 0, v[146:147]
	global_store_short_d16_hi v[154:155], v157, off
	v_mul_f32_e32 v154, 0xbfb8aa3b, v145
	v_exp_f32_e32 v154, v154
	v_lshl_add_u64 v[146:147], s[38:39], 0, v[146:147]
	v_mul_f32_e32 v154, v154, v156
	v_bfe_u32 v155, v154, 16, 1
	v_add3_u32 v154, v154, v155, s73
	global_store_short_d16_hi v[146:147], v154, off
	v_sub_f32_e32 v146, v141, v145
	v_mul_f32_e32 v146, 0x3fb8aa3b, v146
	v_exp_f32_e32 v146, v146
	s_nop 0
	v_mul_f32_e32 v146, v146, v156
	v_bfe_u32 v147, v146, 16, 1
	v_add3_u32 v154, v146, v147, s73
	v_lshlrev_b32_e32 v146, 1, v78
	v_mov_b32_e32 v147, v3
	v_lshl_add_u64 v[146:147], v[6:7], 0, v[146:147]
	v_and_or_b32 v220, v154, s98, v220
	ds_read_u16 v147, v109 offset:24576
	v_cndmask_b32_e64 v146, v202, v210, s[4:5]
	v_add_f32_e32 v145, v146, v145
	ds_read_u16 v146, v109 offset:8192
	s_waitcnt lgkmcnt(1)
	v_lshlrev_b32_e32 v156, 16, v147
	v_mul_f32_e32 v147, 0x3fb8aa3b, v145
	v_exp_f32_e32 v147, v147
	s_waitcnt lgkmcnt(0)
	v_lshlrev_b32_e32 v146, 16, v146
	v_mul_f32_e32 v146, 0x3db504f3, v146
	v_mul_f32_e32 v146, v147, v146
	v_bfe_u32 v147, v146, 16, 1
	v_add3_u32 v157, v146, v147, s73
	v_or_b32_e32 v146, v142, v80
	v_mov_b32_e32 v147, v143
	v_lshlrev_b64 v[146:147], 8, v[146:147]
	v_or_b32_e32 v146, v146, v144
	v_lshl_add_u64 v[154:155], s[36:37], 0, v[146:147]
	global_store_short_d16_hi v[154:155], v157, off
	v_mul_f32_e32 v154, 0xbfb8aa3b, v145
	v_exp_f32_e32 v154, v154
	v_lshl_add_u64 v[146:147], s[38:39], 0, v[146:147]
	v_mul_f32_e32 v154, v154, v156
	v_bfe_u32 v155, v154, 16, 1
	v_add3_u32 v154, v154, v155, s73
	global_store_short_d16_hi v[146:147], v154, off
	v_sub_f32_e32 v146, v141, v145
	v_mul_f32_e32 v146, 0x3fb8aa3b, v146
	v_exp_f32_e32 v146, v146
	s_nop 0
	v_mul_f32_e32 v146, v146, v156
	v_bfe_u32 v147, v146, 16, 1
	v_add3_u32 v154, v146, v147, s73
	v_lshlrev_b32_e32 v146, 1, v80
	v_mov_b32_e32 v147, v3
	v_lshl_add_u64 v[146:147], v[6:7], 0, v[146:147]
	v_lshrrev_b32_e32 v221, 16, v154
	ds_read_u16 v147, v111 offset:24576
	v_cndmask_b32_e64 v146, v201, v212, s[4:5]
	v_add_f32_e32 v145, v146, v145
	ds_read_u16 v146, v111 offset:8192
	s_waitcnt lgkmcnt(1)
	v_lshlrev_b32_e32 v156, 16, v147
	v_mul_f32_e32 v147, 0x3fb8aa3b, v145
	v_exp_f32_e32 v147, v147
	s_waitcnt lgkmcnt(0)
	v_lshlrev_b32_e32 v146, 16, v146
	v_mul_f32_e32 v146, 0x3db504f3, v146
	v_mul_f32_e32 v146, v147, v146
	v_bfe_u32 v147, v146, 16, 1
	v_add3_u32 v157, v146, v147, s73
	v_or_b32_e32 v146, v142, v82
	v_mov_b32_e32 v147, v143
	v_lshlrev_b64 v[146:147], 8, v[146:147]
	v_or_b32_e32 v146, v146, v144
	v_lshl_add_u64 v[154:155], s[36:37], 0, v[146:147]
	global_store_short_d16_hi v[154:155], v157, off
	v_mul_f32_e32 v154, 0xbfb8aa3b, v145
	v_exp_f32_e32 v154, v154
	v_lshl_add_u64 v[146:147], s[38:39], 0, v[146:147]
	v_mul_f32_e32 v154, v154, v156
	v_bfe_u32 v155, v154, 16, 1
	v_add3_u32 v154, v154, v155, s73
	global_store_short_d16_hi v[146:147], v154, off
	v_sub_f32_e32 v146, v141, v145
	v_mul_f32_e32 v146, 0x3fb8aa3b, v146
	v_exp_f32_e32 v146, v146
	s_nop 0
	v_mul_f32_e32 v146, v146, v156
	v_bfe_u32 v147, v146, 16, 1
	v_add3_u32 v154, v146, v147, s73
	v_lshlrev_b32_e32 v146, 1, v82
	v_mov_b32_e32 v147, v3
	v_lshl_add_u64 v[146:147], v[6:7], 0, v[146:147]
	v_and_or_b32 v221, v154, s98, v221
	ds_read_u16 v147, v113 offset:24576
	v_cndmask_b32_e64 v146, v200, v206, s[4:5]
	v_add_f32_e32 v145, v146, v145
	ds_read_u16 v146, v113 offset:8192
	s_waitcnt lgkmcnt(1)
	v_lshlrev_b32_e32 v156, 16, v147
	v_mul_f32_e32 v147, 0x3fb8aa3b, v145
	v_exp_f32_e32 v147, v147
	s_waitcnt lgkmcnt(0)
	v_lshlrev_b32_e32 v146, 16, v146
	v_mul_f32_e32 v146, 0x3db504f3, v146
	v_mul_f32_e32 v146, v147, v146
	v_bfe_u32 v147, v146, 16, 1
	v_add3_u32 v157, v146, v147, s73
	v_or_b32_e32 v146, v142, v84
	v_mov_b32_e32 v147, v143
	v_lshlrev_b64 v[146:147], 8, v[146:147]
	v_or_b32_e32 v146, v146, v144
	v_lshl_add_u64 v[154:155], s[36:37], 0, v[146:147]
	global_store_short_d16_hi v[154:155], v157, off
	v_mul_f32_e32 v154, 0xbfb8aa3b, v145
	v_exp_f32_e32 v154, v154
	v_lshl_add_u64 v[146:147], s[38:39], 0, v[146:147]
	v_mul_f32_e32 v154, v154, v156
	v_bfe_u32 v155, v154, 16, 1
	v_add3_u32 v154, v154, v155, s73
	global_store_short_d16_hi v[146:147], v154, off
	v_sub_f32_e32 v146, v141, v145
	v_mul_f32_e32 v146, 0x3fb8aa3b, v146
	v_exp_f32_e32 v146, v146
	s_nop 0
	v_mul_f32_e32 v146, v146, v156
	v_bfe_u32 v147, v146, 16, 1
	v_add3_u32 v154, v146, v147, s73
	v_lshlrev_b32_e32 v146, 1, v84
	v_mov_b32_e32 v147, v3
	v_lshl_add_u64 v[146:147], v[6:7], 0, v[146:147]
	v_lshrrev_b32_e32 v222, 16, v154
	ds_read_u16 v147, v115 offset:24576
	v_cndmask_b32_e64 v146, v199, v209, s[4:5]
	v_add_f32_e32 v145, v146, v145
	ds_read_u16 v146, v115 offset:8192
	s_waitcnt lgkmcnt(1)
	v_lshlrev_b32_e32 v156, 16, v147
	v_mul_f32_e32 v147, 0x3fb8aa3b, v145
	v_exp_f32_e32 v147, v147
	s_waitcnt lgkmcnt(0)
	v_lshlrev_b32_e32 v146, 16, v146
	v_mul_f32_e32 v146, 0x3db504f3, v146
	v_mul_f32_e32 v146, v147, v146
	v_bfe_u32 v147, v146, 16, 1
	v_add3_u32 v157, v146, v147, s73
	v_or_b32_e32 v146, v142, v86
	v_mov_b32_e32 v147, v143
	v_lshlrev_b64 v[146:147], 8, v[146:147]
	v_or_b32_e32 v146, v146, v144
	v_lshl_add_u64 v[154:155], s[36:37], 0, v[146:147]
	global_store_short_d16_hi v[154:155], v157, off
	v_mul_f32_e32 v154, 0xbfb8aa3b, v145
	v_exp_f32_e32 v154, v154
	v_lshl_add_u64 v[146:147], s[38:39], 0, v[146:147]
	v_mul_f32_e32 v154, v154, v156
	v_bfe_u32 v155, v154, 16, 1
	v_add3_u32 v154, v154, v155, s73
	global_store_short_d16_hi v[146:147], v154, off
	v_sub_f32_e32 v146, v141, v145
	v_mul_f32_e32 v146, 0x3fb8aa3b, v146
	v_exp_f32_e32 v146, v146
	s_nop 0
	v_mul_f32_e32 v146, v146, v156
	v_bfe_u32 v147, v146, 16, 1
	v_add3_u32 v154, v146, v147, s73
	v_lshlrev_b32_e32 v146, 1, v86
	v_mov_b32_e32 v147, v3
	v_lshl_add_u64 v[146:147], v[6:7], 0, v[146:147]
	v_and_or_b32 v222, v154, s98, v222
	ds_read_u16 v147, v117 offset:24576
	v_cndmask_b32_e64 v146, v198, v214, s[4:5]
	v_add_f32_e32 v145, v146, v145
	ds_read_u16 v146, v117 offset:8192
	s_waitcnt lgkmcnt(1)
	v_lshlrev_b32_e32 v156, 16, v147
	v_mul_f32_e32 v147, 0x3fb8aa3b, v145
	v_exp_f32_e32 v147, v147
	s_waitcnt lgkmcnt(0)
	v_lshlrev_b32_e32 v146, 16, v146
	v_mul_f32_e32 v146, 0x3db504f3, v146
	v_mul_f32_e32 v146, v147, v146
	v_bfe_u32 v147, v146, 16, 1
	v_add3_u32 v157, v146, v147, s73
	v_or_b32_e32 v146, v142, v88
	v_mov_b32_e32 v147, v143
	v_lshlrev_b64 v[146:147], 8, v[146:147]
	v_or_b32_e32 v146, v146, v144
	v_lshl_add_u64 v[154:155], s[36:37], 0, v[146:147]
	global_store_short_d16_hi v[154:155], v157, off
	v_mul_f32_e32 v154, 0xbfb8aa3b, v145
	v_exp_f32_e32 v154, v154
	v_lshl_add_u64 v[146:147], s[38:39], 0, v[146:147]
	v_mul_f32_e32 v154, v154, v156
	v_bfe_u32 v155, v154, 16, 1
	v_add3_u32 v154, v154, v155, s73
	global_store_short_d16_hi v[146:147], v154, off
	v_sub_f32_e32 v146, v141, v145
	v_mul_f32_e32 v146, 0x3fb8aa3b, v146
	v_exp_f32_e32 v146, v146
	s_nop 0
	v_mul_f32_e32 v146, v146, v156
	v_bfe_u32 v147, v146, 16, 1
	v_add3_u32 v154, v146, v147, s73
	v_lshlrev_b32_e32 v146, 1, v88
	v_mov_b32_e32 v147, v3
	v_lshl_add_u64 v[146:147], v[6:7], 0, v[146:147]
	v_lshrrev_b32_e32 v223, 16, v154
	ds_read_u16 v147, v119 offset:24576
	v_cndmask_b32_e64 v146, v197, v216, s[4:5]
	v_add_f32_e32 v145, v146, v145
	ds_read_u16 v146, v119 offset:8192
	s_waitcnt lgkmcnt(1)
	v_lshlrev_b32_e32 v156, 16, v147
	v_mul_f32_e32 v147, 0x3fb8aa3b, v145
	v_exp_f32_e32 v147, v147
	s_waitcnt lgkmcnt(0)
	v_lshlrev_b32_e32 v146, 16, v146
	v_mul_f32_e32 v146, 0x3db504f3, v146
	v_mul_f32_e32 v146, v147, v146
	v_bfe_u32 v147, v146, 16, 1
	v_add3_u32 v157, v146, v147, s73
	v_or_b32_e32 v146, v142, v90
	v_mov_b32_e32 v147, v143
	v_lshlrev_b64 v[146:147], 8, v[146:147]
	v_or_b32_e32 v146, v146, v144
	v_lshl_add_u64 v[154:155], s[36:37], 0, v[146:147]
	global_store_short_d16_hi v[154:155], v157, off
	v_mul_f32_e32 v154, 0xbfb8aa3b, v145
	v_exp_f32_e32 v154, v154
	v_lshl_add_u64 v[146:147], s[38:39], 0, v[146:147]
	v_mul_f32_e32 v154, v154, v156
	v_bfe_u32 v155, v154, 16, 1
	v_add3_u32 v154, v154, v155, s73
	global_store_short_d16_hi v[146:147], v154, off
	v_sub_f32_e32 v146, v141, v145
	v_mul_f32_e32 v146, 0x3fb8aa3b, v146
	v_exp_f32_e32 v146, v146
	s_nop 0
	v_mul_f32_e32 v146, v146, v156
	v_bfe_u32 v147, v146, 16, 1
	v_add3_u32 v154, v146, v147, s73
	v_lshlrev_b32_e32 v146, 1, v90
	v_mov_b32_e32 v147, v3
	v_lshl_add_u64 v[146:147], v[6:7], 0, v[146:147]
	v_and_or_b32 v223, v154, s98, v223
	v_alignbit_b32 v226, v223, v223, 16
	v_alignbit_b32 v218, v220, v220, 16
	v_cndmask_b32_e64 v220, v226, v220, s[4:5]
	v_cndmask_b32_e64 v223, v218, v223, s[4:5]
	v_alignbit_b32 v226, v222, v222, 16
	v_alignbit_b32 v218, v221, v221, 16
	v_cndmask_b32_e64 v221, v226, v221, s[4:5]
	v_cndmask_b32_e64 v222, v218, v222, s[4:5]
	v_lshl_add_u64 v[218:219], v[146:147], 0, v[224:225]
	global_store_dwordx4 v[218:219], v[220:223], off
	s_nop 1
	ds_read_u16 v147, v121 offset:24576
	v_cndmask_b32_e64 v146, v196, v208, s[4:5]
	v_add_f32_e32 v145, v146, v145
	ds_read_u16 v146, v121 offset:8192
	s_waitcnt lgkmcnt(1)
	v_lshlrev_b32_e32 v156, 16, v147
	v_mul_f32_e32 v147, 0x3fb8aa3b, v145
	v_exp_f32_e32 v147, v147
	s_waitcnt lgkmcnt(0)
	v_lshlrev_b32_e32 v146, 16, v146
	v_mul_f32_e32 v146, 0x3db504f3, v146
	v_mul_f32_e32 v146, v147, v146
	v_bfe_u32 v147, v146, 16, 1
	v_add3_u32 v157, v146, v147, s73
	v_or_b32_e32 v146, v142, v92
	v_mov_b32_e32 v147, v143
	v_lshlrev_b64 v[146:147], 8, v[146:147]
	v_or_b32_e32 v146, v146, v144
	v_lshl_add_u64 v[154:155], s[36:37], 0, v[146:147]
	global_store_short_d16_hi v[154:155], v157, off
	v_mul_f32_e32 v154, 0xbfb8aa3b, v145
	v_exp_f32_e32 v154, v154
	v_lshl_add_u64 v[146:147], s[38:39], 0, v[146:147]
	v_mul_f32_e32 v154, v154, v156
	v_bfe_u32 v155, v154, 16, 1
	v_add3_u32 v154, v154, v155, s73
	global_store_short_d16_hi v[146:147], v154, off
	v_sub_f32_e32 v146, v141, v145
	v_mul_f32_e32 v146, 0x3fb8aa3b, v146
	v_exp_f32_e32 v146, v146
	s_nop 0
	v_mul_f32_e32 v146, v146, v156
	v_bfe_u32 v147, v146, 16, 1
	v_add3_u32 v154, v146, v147, s73
	v_lshlrev_b32_e32 v146, 1, v92
	v_mov_b32_e32 v147, v3
	v_lshl_add_u64 v[146:147], v[6:7], 0, v[146:147]
	v_lshrrev_b32_e32 v220, 16, v154
	ds_read_u16 v147, v123 offset:24576
	v_cndmask_b32_e64 v146, v195, v213, s[4:5]
	v_add_f32_e32 v145, v146, v145
	ds_read_u16 v146, v123 offset:8192
	s_waitcnt lgkmcnt(1)
	v_lshlrev_b32_e32 v156, 16, v147
	v_mul_f32_e32 v147, 0x3fb8aa3b, v145
	v_exp_f32_e32 v147, v147
	s_waitcnt lgkmcnt(0)
	v_lshlrev_b32_e32 v146, 16, v146
	v_mul_f32_e32 v146, 0x3db504f3, v146
	v_mul_f32_e32 v146, v147, v146
	v_bfe_u32 v147, v146, 16, 1
	v_add3_u32 v157, v146, v147, s73
	v_or_b32_e32 v146, v142, v94
	v_mov_b32_e32 v147, v143
	v_lshlrev_b64 v[146:147], 8, v[146:147]
	v_or_b32_e32 v146, v146, v144
	v_lshl_add_u64 v[154:155], s[36:37], 0, v[146:147]
	global_store_short_d16_hi v[154:155], v157, off
	v_mul_f32_e32 v154, 0xbfb8aa3b, v145
	v_exp_f32_e32 v154, v154
	v_lshl_add_u64 v[146:147], s[38:39], 0, v[146:147]
	v_mul_f32_e32 v154, v154, v156
	v_bfe_u32 v155, v154, 16, 1
	v_add3_u32 v154, v154, v155, s73
	global_store_short_d16_hi v[146:147], v154, off
	v_sub_f32_e32 v146, v141, v145
	v_mul_f32_e32 v146, 0x3fb8aa3b, v146
	v_exp_f32_e32 v146, v146
	s_nop 0
	v_mul_f32_e32 v146, v146, v156
	v_bfe_u32 v147, v146, 16, 1
	v_add3_u32 v154, v146, v147, s73
	v_lshlrev_b32_e32 v146, 1, v94
	v_mov_b32_e32 v147, v3
	v_lshl_add_u64 v[146:147], v[6:7], 0, v[146:147]
	v_and_or_b32 v220, v154, s98, v220
	ds_read_u16 v147, v125 offset:24576
	v_cndmask_b32_e64 v146, v194, v234, s[4:5]
	v_add_f32_e32 v145, v146, v145
	ds_read_u16 v146, v125 offset:8192
	s_waitcnt lgkmcnt(1)
	v_lshlrev_b32_e32 v156, 16, v147
	v_mul_f32_e32 v147, 0x3fb8aa3b, v145
	v_exp_f32_e32 v147, v147
	s_waitcnt lgkmcnt(0)
	v_lshlrev_b32_e32 v146, 16, v146
	v_mul_f32_e32 v146, 0x3db504f3, v146
	v_mul_f32_e32 v146, v147, v146
	v_bfe_u32 v147, v146, 16, 1
	v_add3_u32 v157, v146, v147, s73
	v_or_b32_e32 v146, v142, v96
	v_mov_b32_e32 v147, v143
	v_lshlrev_b64 v[146:147], 8, v[146:147]
	v_or_b32_e32 v146, v146, v144
	v_lshl_add_u64 v[154:155], s[36:37], 0, v[146:147]
	global_store_short_d16_hi v[154:155], v157, off
	v_mul_f32_e32 v154, 0xbfb8aa3b, v145
	v_exp_f32_e32 v154, v154
	v_lshl_add_u64 v[146:147], s[38:39], 0, v[146:147]
	v_mul_f32_e32 v154, v154, v156
	v_bfe_u32 v155, v154, 16, 1
	v_add3_u32 v154, v154, v155, s73
	global_store_short_d16_hi v[146:147], v154, off
	v_sub_f32_e32 v146, v141, v145
	v_mul_f32_e32 v146, 0x3fb8aa3b, v146
	v_exp_f32_e32 v146, v146
	s_nop 0
	v_mul_f32_e32 v146, v146, v156
	v_bfe_u32 v147, v146, 16, 1
	v_add3_u32 v154, v146, v147, s73
	v_lshlrev_b32_e32 v146, 1, v96
	v_mov_b32_e32 v147, v3
	v_lshl_add_u64 v[146:147], v[6:7], 0, v[146:147]
	v_lshrrev_b32_e32 v221, 16, v154
	ds_read_u16 v147, v127 offset:24576
	v_cndmask_b32_e64 v146, v193, v236, s[4:5]
	v_add_f32_e32 v145, v146, v145
	ds_read_u16 v146, v127 offset:8192
	s_waitcnt lgkmcnt(1)
	v_lshlrev_b32_e32 v156, 16, v147
	v_mul_f32_e32 v147, 0x3fb8aa3b, v145
	v_exp_f32_e32 v147, v147
	s_waitcnt lgkmcnt(0)
	v_lshlrev_b32_e32 v146, 16, v146
	v_mul_f32_e32 v146, 0x3db504f3, v146
	v_mul_f32_e32 v146, v147, v146
	v_bfe_u32 v147, v146, 16, 1
	v_add3_u32 v157, v146, v147, s73
	v_or_b32_e32 v146, v142, v98
	v_mov_b32_e32 v147, v143
	v_lshlrev_b64 v[146:147], 8, v[146:147]
	v_or_b32_e32 v146, v146, v144
	v_lshl_add_u64 v[154:155], s[36:37], 0, v[146:147]
	global_store_short_d16_hi v[154:155], v157, off
	v_mul_f32_e32 v154, 0xbfb8aa3b, v145
	v_exp_f32_e32 v154, v154
	v_lshl_add_u64 v[146:147], s[38:39], 0, v[146:147]
	v_mul_f32_e32 v154, v154, v156
	v_bfe_u32 v155, v154, 16, 1
	v_add3_u32 v154, v154, v155, s73
	global_store_short_d16_hi v[146:147], v154, off
	v_sub_f32_e32 v146, v141, v145
	v_mul_f32_e32 v146, 0x3fb8aa3b, v146
	v_exp_f32_e32 v146, v146
	s_nop 0
	v_mul_f32_e32 v146, v146, v156
	v_bfe_u32 v147, v146, 16, 1
	v_add3_u32 v154, v146, v147, s73
	v_lshlrev_b32_e32 v146, 1, v98
	v_mov_b32_e32 v147, v3
	v_lshl_add_u64 v[146:147], v[6:7], 0, v[146:147]
	v_and_or_b32 v221, v154, s98, v221
	ds_read_u16 v147, v129 offset:24576
	v_cndmask_b32_e64 v146, v192, v211, s[4:5]
	v_add_f32_e32 v145, v146, v145
	ds_read_u16 v146, v129 offset:8192
	s_waitcnt lgkmcnt(1)
	v_lshlrev_b32_e32 v156, 16, v147
	v_mul_f32_e32 v147, 0x3fb8aa3b, v145
	v_exp_f32_e32 v147, v147
	s_waitcnt lgkmcnt(0)
	v_lshlrev_b32_e32 v146, 16, v146
	v_mul_f32_e32 v146, 0x3db504f3, v146
	v_mul_f32_e32 v146, v147, v146
	v_bfe_u32 v147, v146, 16, 1
	v_add3_u32 v157, v146, v147, s73
	v_or_b32_e32 v146, v142, v100
	v_mov_b32_e32 v147, v143
	v_lshlrev_b64 v[146:147], 8, v[146:147]
	v_or_b32_e32 v146, v146, v144
	v_lshl_add_u64 v[154:155], s[36:37], 0, v[146:147]
	global_store_short_d16_hi v[154:155], v157, off
	v_mul_f32_e32 v154, 0xbfb8aa3b, v145
	v_exp_f32_e32 v154, v154
	v_lshl_add_u64 v[146:147], s[38:39], 0, v[146:147]
	v_mul_f32_e32 v154, v154, v156
	v_bfe_u32 v155, v154, 16, 1
	v_add3_u32 v154, v154, v155, s73
	global_store_short_d16_hi v[146:147], v154, off
	v_sub_f32_e32 v146, v141, v145
	v_mul_f32_e32 v146, 0x3fb8aa3b, v146
	v_exp_f32_e32 v146, v146
	s_nop 0
	v_mul_f32_e32 v146, v146, v156
	v_bfe_u32 v147, v146, 16, 1
	v_add3_u32 v154, v146, v147, s73
	v_lshlrev_b32_e32 v146, 1, v100
	v_mov_b32_e32 v147, v3
	v_lshl_add_u64 v[146:147], v[6:7], 0, v[146:147]
	v_lshrrev_b32_e32 v222, 16, v154
	ds_read_u16 v147, v131 offset:24576
	v_cndmask_b32_e64 v146, v191, v217, s[4:5]
	v_add_f32_e32 v145, v146, v145
	ds_read_u16 v146, v131 offset:8192
	s_waitcnt lgkmcnt(1)
	v_lshlrev_b32_e32 v156, 16, v147
	v_mul_f32_e32 v147, 0x3fb8aa3b, v145
	v_exp_f32_e32 v147, v147
	s_waitcnt lgkmcnt(0)
	v_lshlrev_b32_e32 v146, 16, v146
	v_mul_f32_e32 v146, 0x3db504f3, v146
	v_mul_f32_e32 v146, v147, v146
	v_bfe_u32 v147, v146, 16, 1
	v_add3_u32 v157, v146, v147, s73
	v_or_b32_e32 v146, v142, v102
	v_mov_b32_e32 v147, v143
	v_lshlrev_b64 v[146:147], 8, v[146:147]
	v_or_b32_e32 v146, v146, v144
	v_lshl_add_u64 v[154:155], s[36:37], 0, v[146:147]
	global_store_short_d16_hi v[154:155], v157, off
	v_mul_f32_e32 v154, 0xbfb8aa3b, v145
	v_exp_f32_e32 v154, v154
	v_lshl_add_u64 v[146:147], s[38:39], 0, v[146:147]
	v_mul_f32_e32 v154, v154, v156
	v_bfe_u32 v155, v154, 16, 1
	v_add3_u32 v154, v154, v155, s73
	global_store_short_d16_hi v[146:147], v154, off
	v_sub_f32_e32 v146, v141, v145
	v_mul_f32_e32 v146, 0x3fb8aa3b, v146
	v_exp_f32_e32 v146, v146
	s_nop 0
	v_mul_f32_e32 v146, v146, v156
	v_bfe_u32 v147, v146, 16, 1
	v_add3_u32 v154, v146, v147, s73
	v_lshlrev_b32_e32 v146, 1, v102
	v_mov_b32_e32 v147, v3
	v_lshl_add_u64 v[146:147], v[6:7], 0, v[146:147]
	v_and_or_b32 v222, v154, s98, v222
	ds_read_u16 v147, v133 offset:24576
	v_cndmask_b32_e64 v146, v190, v238, s[4:5]
	v_add_f32_e32 v145, v146, v145
	ds_read_u16 v146, v133 offset:8192
	s_waitcnt lgkmcnt(1)
	v_lshlrev_b32_e32 v156, 16, v147
	v_mul_f32_e32 v147, 0x3fb8aa3b, v145
	v_exp_f32_e32 v147, v147
	s_waitcnt lgkmcnt(0)
	v_lshlrev_b32_e32 v146, 16, v146
	v_mul_f32_e32 v146, 0x3db504f3, v146
	v_mul_f32_e32 v146, v147, v146
	v_bfe_u32 v147, v146, 16, 1
	v_add3_u32 v157, v146, v147, s73
	v_or_b32_e32 v146, v142, v104
	v_mov_b32_e32 v147, v143
	v_lshlrev_b64 v[146:147], 8, v[146:147]
	v_or_b32_e32 v146, v146, v144
	v_lshl_add_u64 v[154:155], s[36:37], 0, v[146:147]
	global_store_short_d16_hi v[154:155], v157, off
	v_mul_f32_e32 v154, 0xbfb8aa3b, v145
	v_exp_f32_e32 v154, v154
	v_lshl_add_u64 v[146:147], s[38:39], 0, v[146:147]
	v_mul_f32_e32 v154, v154, v156
	v_bfe_u32 v155, v154, 16, 1
	v_add3_u32 v154, v154, v155, s73
	global_store_short_d16_hi v[146:147], v154, off
	v_sub_f32_e32 v146, v141, v145
	v_mul_f32_e32 v146, 0x3fb8aa3b, v146
	v_exp_f32_e32 v146, v146
	s_nop 0
	v_mul_f32_e32 v146, v146, v156
	v_bfe_u32 v147, v146, 16, 1
	v_add3_u32 v154, v146, v147, s73
	v_lshlrev_b32_e32 v146, 1, v104
	v_mov_b32_e32 v147, v3
	v_lshl_add_u64 v[146:147], v[6:7], 0, v[146:147]
	v_lshrrev_b32_e32 v223, 16, v154
	ds_read_u16 v147, v135 offset:24576
	v_cndmask_b32_e64 v146, v189, v240, s[4:5]
	v_add_f32_e32 v145, v146, v145
	ds_read_u16 v146, v135 offset:8192
	s_waitcnt lgkmcnt(1)
	v_lshlrev_b32_e32 v156, 16, v147
	v_mul_f32_e32 v147, 0x3fb8aa3b, v145
	v_exp_f32_e32 v147, v147
	s_waitcnt lgkmcnt(0)
	v_lshlrev_b32_e32 v146, 16, v146
	v_mul_f32_e32 v146, 0x3db504f3, v146
	v_mul_f32_e32 v146, v147, v146
	v_bfe_u32 v147, v146, 16, 1
	v_add3_u32 v157, v146, v147, s73
	v_or_b32_e32 v146, v142, v106
	v_mov_b32_e32 v147, v143
	v_lshlrev_b64 v[146:147], 8, v[146:147]
	v_or_b32_e32 v146, v146, v144
	v_lshl_add_u64 v[154:155], s[36:37], 0, v[146:147]
	global_store_short_d16_hi v[154:155], v157, off
	v_mul_f32_e32 v154, 0xbfb8aa3b, v145
	v_exp_f32_e32 v154, v154
	v_lshl_add_u64 v[146:147], s[38:39], 0, v[146:147]
	v_mul_f32_e32 v154, v154, v156
	v_bfe_u32 v155, v154, 16, 1
	v_add3_u32 v154, v154, v155, s73
	global_store_short_d16_hi v[146:147], v154, off
	v_sub_f32_e32 v146, v141, v145
	v_mul_f32_e32 v146, 0x3fb8aa3b, v146
	v_exp_f32_e32 v146, v146
	s_nop 0
	v_mul_f32_e32 v146, v146, v156
	v_bfe_u32 v147, v146, 16, 1
	v_add3_u32 v154, v146, v147, s73
	v_lshlrev_b32_e32 v146, 1, v106
	v_mov_b32_e32 v147, v3
	v_lshl_add_u64 v[146:147], v[6:7], 0, v[146:147]
	v_and_or_b32 v223, v154, s98, v223
	v_alignbit_b32 v226, v223, v223, 16
	v_alignbit_b32 v218, v220, v220, 16
	v_cndmask_b32_e64 v220, v226, v220, s[4:5]
	v_cndmask_b32_e64 v223, v218, v223, s[4:5]
	v_alignbit_b32 v226, v222, v222, 16
	v_alignbit_b32 v218, v221, v221, 16
	v_cndmask_b32_e64 v221, v226, v221, s[4:5]
	v_cndmask_b32_e64 v222, v218, v222, s[4:5]
	v_lshl_add_u64 v[218:219], v[146:147], 0, v[224:225]
	global_store_dwordx4 v[218:219], v[220:223], off
	s_nop 1
	ds_read_u16 v147, v137 offset:24576
	v_cndmask_b32_e64 v146, v188, v215, s[4:5]
	v_add_f32_e32 v145, v146, v145
	ds_read_u16 v146, v137 offset:8192
	s_waitcnt lgkmcnt(1)
	v_lshlrev_b32_e32 v156, 16, v147
	v_mul_f32_e32 v147, 0x3fb8aa3b, v145
	v_exp_f32_e32 v147, v147
	s_waitcnt lgkmcnt(0)
	v_lshlrev_b32_e32 v146, 16, v146
	v_mul_f32_e32 v146, 0x3db504f3, v146
	v_mul_f32_e32 v146, v147, v146
	v_bfe_u32 v147, v146, 16, 1
	v_add3_u32 v157, v146, v147, s73
	v_or_b32_e32 v146, v142, v108
	v_mov_b32_e32 v147, v143
	v_lshlrev_b64 v[146:147], 8, v[146:147]
	v_or_b32_e32 v146, v146, v144
	v_lshl_add_u64 v[154:155], s[36:37], 0, v[146:147]
	global_store_short_d16_hi v[154:155], v157, off
	v_mul_f32_e32 v154, 0xbfb8aa3b, v145
	v_exp_f32_e32 v154, v154
	v_lshl_add_u64 v[146:147], s[38:39], 0, v[146:147]
	v_mul_f32_e32 v154, v154, v156
	v_bfe_u32 v155, v154, 16, 1
	v_add3_u32 v154, v154, v155, s73
	global_store_short_d16_hi v[146:147], v154, off
	v_sub_f32_e32 v146, v141, v145
	v_mul_f32_e32 v146, 0x3fb8aa3b, v146
	v_exp_f32_e32 v146, v146
	s_nop 0
	v_mul_f32_e32 v146, v146, v156
	v_bfe_u32 v147, v146, 16, 1
	v_add3_u32 v154, v146, v147, s73
	v_lshlrev_b32_e32 v146, 1, v108
	v_mov_b32_e32 v147, v3
	v_lshl_add_u64 v[146:147], v[6:7], 0, v[146:147]
	v_lshrrev_b32_e32 v220, 16, v154
	ds_read_u16 v147, v139 offset:24576
	v_cndmask_b32_e64 v146, v187, v237, s[4:5]
	v_add_f32_e32 v145, v146, v145
	ds_read_u16 v146, v139 offset:8192
	s_waitcnt lgkmcnt(1)
	v_lshlrev_b32_e32 v156, 16, v147
	v_mul_f32_e32 v147, 0x3fb8aa3b, v145
	v_exp_f32_e32 v147, v147
	s_waitcnt lgkmcnt(0)
	v_lshlrev_b32_e32 v146, 16, v146
	v_mul_f32_e32 v146, 0x3db504f3, v146
	v_mul_f32_e32 v146, v147, v146
	v_bfe_u32 v147, v146, 16, 1
	v_add3_u32 v157, v146, v147, s73
	v_or_b32_e32 v146, v142, v110
	v_mov_b32_e32 v147, v143
	v_lshlrev_b64 v[146:147], 8, v[146:147]
	v_or_b32_e32 v146, v146, v144
	v_lshl_add_u64 v[154:155], s[36:37], 0, v[146:147]
	global_store_short_d16_hi v[154:155], v157, off
	v_mul_f32_e32 v154, 0xbfb8aa3b, v145
	v_exp_f32_e32 v154, v154
	v_lshl_add_u64 v[146:147], s[38:39], 0, v[146:147]
	v_mul_f32_e32 v154, v154, v156
	v_bfe_u32 v155, v154, 16, 1
	v_add3_u32 v154, v154, v155, s73
	global_store_short_d16_hi v[146:147], v154, off
	v_sub_f32_e32 v146, v141, v145
	v_mul_f32_e32 v146, 0x3fb8aa3b, v146
	v_exp_f32_e32 v146, v146
	s_nop 0
	v_mul_f32_e32 v146, v146, v156
	v_bfe_u32 v147, v146, 16, 1
	v_add3_u32 v154, v146, v147, s73
	v_lshlrev_b32_e32 v146, 1, v110
	v_mov_b32_e32 v147, v3
	v_lshl_add_u64 v[146:147], v[6:7], 0, v[146:147]
	v_and_or_b32 v220, v154, s98, v220
	ds_read_u16 v147, v148 offset:24576
	v_cndmask_b32_e64 v146, v186, v242, s[4:5]
	v_add_f32_e32 v145, v146, v145
	ds_read_u16 v146, v148 offset:8192
	s_waitcnt lgkmcnt(1)
	v_lshlrev_b32_e32 v156, 16, v147
	v_mul_f32_e32 v147, 0x3fb8aa3b, v145
	v_exp_f32_e32 v147, v147
	s_waitcnt lgkmcnt(0)
	v_lshlrev_b32_e32 v146, 16, v146
	v_mul_f32_e32 v146, 0x3db504f3, v146
	v_mul_f32_e32 v146, v147, v146
	v_bfe_u32 v147, v146, 16, 1
	v_add3_u32 v157, v146, v147, s73
	v_or_b32_e32 v146, v142, v112
	v_mov_b32_e32 v147, v143
	v_lshlrev_b64 v[146:147], 8, v[146:147]
	v_or_b32_e32 v146, v146, v144
	v_lshl_add_u64 v[154:155], s[36:37], 0, v[146:147]
	global_store_short_d16_hi v[154:155], v157, off
	v_mul_f32_e32 v154, 0xbfb8aa3b, v145
	v_exp_f32_e32 v154, v154
	v_lshl_add_u64 v[146:147], s[38:39], 0, v[146:147]
	v_mul_f32_e32 v154, v154, v156
	v_bfe_u32 v155, v154, 16, 1
	v_add3_u32 v154, v154, v155, s73
	global_store_short_d16_hi v[146:147], v154, off
	v_sub_f32_e32 v146, v141, v145
	v_mul_f32_e32 v146, 0x3fb8aa3b, v146
	v_exp_f32_e32 v146, v146
	s_nop 0
	v_mul_f32_e32 v146, v146, v156
	v_bfe_u32 v147, v146, 16, 1
	v_add3_u32 v154, v146, v147, s73
	v_lshlrev_b32_e32 v146, 1, v112
	v_mov_b32_e32 v147, v3
	v_lshl_add_u64 v[146:147], v[6:7], 0, v[146:147]
	v_lshrrev_b32_e32 v221, 16, v154
	ds_read_u16 v147, v149 offset:24576
	v_cndmask_b32_e64 v146, v185, v244, s[4:5]
	v_add_f32_e32 v145, v146, v145
	ds_read_u16 v146, v149 offset:8192
	s_waitcnt lgkmcnt(1)
	v_lshlrev_b32_e32 v156, 16, v147
	v_mul_f32_e32 v147, 0x3fb8aa3b, v145
	v_exp_f32_e32 v147, v147
	s_waitcnt lgkmcnt(0)
	v_lshlrev_b32_e32 v146, 16, v146
	v_mul_f32_e32 v146, 0x3db504f3, v146
	v_mul_f32_e32 v146, v147, v146
	v_bfe_u32 v147, v146, 16, 1
	v_add3_u32 v157, v146, v147, s73
	v_or_b32_e32 v146, v142, v114
	v_mov_b32_e32 v147, v143
	v_lshlrev_b64 v[146:147], 8, v[146:147]
	v_or_b32_e32 v146, v146, v144
	v_lshl_add_u64 v[154:155], s[36:37], 0, v[146:147]
	global_store_short_d16_hi v[154:155], v157, off
	v_mul_f32_e32 v154, 0xbfb8aa3b, v145
	v_exp_f32_e32 v154, v154
	v_lshl_add_u64 v[146:147], s[38:39], 0, v[146:147]
	v_mul_f32_e32 v154, v154, v156
	v_bfe_u32 v155, v154, 16, 1
	v_add3_u32 v154, v154, v155, s73
	global_store_short_d16_hi v[146:147], v154, off
	v_sub_f32_e32 v146, v141, v145
	v_mul_f32_e32 v146, 0x3fb8aa3b, v146
	v_exp_f32_e32 v146, v146
	s_nop 0
	v_mul_f32_e32 v146, v146, v156
	v_bfe_u32 v147, v146, 16, 1
	v_add3_u32 v154, v146, v147, s73
	v_lshlrev_b32_e32 v146, 1, v114
	v_mov_b32_e32 v147, v3
	v_lshl_add_u64 v[146:147], v[6:7], 0, v[146:147]
	v_and_or_b32 v221, v154, s98, v221
	ds_read_u16 v147, v150 offset:24576
	v_cndmask_b32_e64 v146, v184, v235, s[4:5]
	v_add_f32_e32 v145, v146, v145
	ds_read_u16 v146, v150 offset:8192
	s_waitcnt lgkmcnt(1)
	v_lshlrev_b32_e32 v156, 16, v147
	v_mul_f32_e32 v147, 0x3fb8aa3b, v145
	v_exp_f32_e32 v147, v147
	s_waitcnt lgkmcnt(0)
	v_lshlrev_b32_e32 v146, 16, v146
	v_mul_f32_e32 v146, 0x3db504f3, v146
	v_mul_f32_e32 v146, v147, v146
	v_bfe_u32 v147, v146, 16, 1
	v_add3_u32 v157, v146, v147, s73
	v_or_b32_e32 v146, v142, v116
	v_mov_b32_e32 v147, v143
	v_lshlrev_b64 v[146:147], 8, v[146:147]
	v_or_b32_e32 v146, v146, v144
	v_lshl_add_u64 v[154:155], s[36:37], 0, v[146:147]
	global_store_short_d16_hi v[154:155], v157, off
	v_mul_f32_e32 v154, 0xbfb8aa3b, v145
	v_exp_f32_e32 v154, v154
	v_lshl_add_u64 v[146:147], s[38:39], 0, v[146:147]
	v_mul_f32_e32 v154, v154, v156
	v_bfe_u32 v155, v154, 16, 1
	v_add3_u32 v154, v154, v155, s73
	global_store_short_d16_hi v[146:147], v154, off
	v_sub_f32_e32 v146, v141, v145
	v_mul_f32_e32 v146, 0x3fb8aa3b, v146
	v_exp_f32_e32 v146, v146
	s_nop 0
	v_mul_f32_e32 v146, v146, v156
	v_bfe_u32 v147, v146, 16, 1
	v_add3_u32 v154, v146, v147, s73
	v_lshlrev_b32_e32 v146, 1, v116
	v_mov_b32_e32 v147, v3
	v_lshl_add_u64 v[146:147], v[6:7], 0, v[146:147]
	v_lshrrev_b32_e32 v222, 16, v154
	ds_read_u16 v147, v151 offset:24576
	v_cndmask_b32_e64 v146, v183, v241, s[4:5]
	v_add_f32_e32 v145, v146, v145
	ds_read_u16 v146, v151 offset:8192
	s_waitcnt lgkmcnt(1)
	v_lshlrev_b32_e32 v156, 16, v147
	v_mul_f32_e32 v147, 0x3fb8aa3b, v145
	v_exp_f32_e32 v147, v147
	s_waitcnt lgkmcnt(0)
	v_lshlrev_b32_e32 v146, 16, v146
	v_mul_f32_e32 v146, 0x3db504f3, v146
	v_mul_f32_e32 v146, v147, v146
	v_bfe_u32 v147, v146, 16, 1
	v_add3_u32 v157, v146, v147, s73
	v_or_b32_e32 v146, v142, v118
	v_mov_b32_e32 v147, v143
	v_lshlrev_b64 v[146:147], 8, v[146:147]
	v_or_b32_e32 v146, v146, v144
	v_lshl_add_u64 v[154:155], s[36:37], 0, v[146:147]
	global_store_short_d16_hi v[154:155], v157, off
	v_mul_f32_e32 v154, 0xbfb8aa3b, v145
	v_exp_f32_e32 v154, v154
	v_lshl_add_u64 v[146:147], s[38:39], 0, v[146:147]
	v_mul_f32_e32 v154, v154, v156
	v_bfe_u32 v155, v154, 16, 1
	v_add3_u32 v154, v154, v155, s73
	global_store_short_d16_hi v[146:147], v154, off
	v_sub_f32_e32 v146, v141, v145
	v_mul_f32_e32 v146, 0x3fb8aa3b, v146
	v_exp_f32_e32 v146, v146
	s_nop 0
	v_mul_f32_e32 v146, v146, v156
	v_bfe_u32 v147, v146, 16, 1
	v_add3_u32 v154, v146, v147, s73
	v_lshlrev_b32_e32 v146, 1, v118
	v_mov_b32_e32 v147, v3
	v_lshl_add_u64 v[146:147], v[6:7], 0, v[146:147]
	v_and_or_b32 v222, v154, s98, v222
	ds_read_u16 v147, v152 offset:24576
	v_cndmask_b32_e64 v146, v182, v246, s[4:5]
	v_add_f32_e32 v145, v146, v145
	ds_read_u16 v146, v152 offset:8192
	s_waitcnt lgkmcnt(1)
	v_lshlrev_b32_e32 v156, 16, v147
	v_mul_f32_e32 v147, 0x3fb8aa3b, v145
	v_exp_f32_e32 v147, v147
	s_waitcnt lgkmcnt(0)
	v_lshlrev_b32_e32 v146, 16, v146
	v_mul_f32_e32 v146, 0x3db504f3, v146
	v_mul_f32_e32 v146, v147, v146
	v_bfe_u32 v147, v146, 16, 1
	v_add3_u32 v157, v146, v147, s73
	v_or_b32_e32 v146, v142, v120
	v_mov_b32_e32 v147, v143
	v_lshlrev_b64 v[146:147], 8, v[146:147]
	v_or_b32_e32 v146, v146, v144
	v_lshl_add_u64 v[154:155], s[36:37], 0, v[146:147]
	global_store_short_d16_hi v[154:155], v157, off
	v_mul_f32_e32 v154, 0xbfb8aa3b, v145
	v_exp_f32_e32 v154, v154
	v_lshl_add_u64 v[146:147], s[38:39], 0, v[146:147]
	v_mul_f32_e32 v154, v154, v156
	v_bfe_u32 v155, v154, 16, 1
	v_add3_u32 v154, v154, v155, s73
	global_store_short_d16_hi v[146:147], v154, off
	v_sub_f32_e32 v146, v141, v145
	v_mul_f32_e32 v146, 0x3fb8aa3b, v146
	v_exp_f32_e32 v146, v146
	s_nop 0
	v_mul_f32_e32 v146, v146, v156
	v_bfe_u32 v147, v146, 16, 1
	v_add3_u32 v154, v146, v147, s73
	v_lshlrev_b32_e32 v146, 1, v120
	v_mov_b32_e32 v147, v3
	v_lshl_add_u64 v[146:147], v[6:7], 0, v[146:147]
	v_lshrrev_b32_e32 v223, 16, v154
	ds_read_u16 v147, v153 offset:24576
	v_cndmask_b32_e64 v146, v181, v247, s[4:5]
	v_add_f32_e32 v145, v146, v145
	ds_read_u16 v146, v153 offset:8192
	s_waitcnt lgkmcnt(1)
	v_lshlrev_b32_e32 v156, 16, v147
	v_mul_f32_e32 v147, 0x3fb8aa3b, v145
	v_exp_f32_e32 v147, v147
	s_waitcnt lgkmcnt(0)
	v_lshlrev_b32_e32 v146, 16, v146
	v_mul_f32_e32 v146, 0x3db504f3, v146
	v_mul_f32_e32 v146, v147, v146
	v_bfe_u32 v147, v146, 16, 1
	v_add3_u32 v157, v146, v147, s73
	v_or_b32_e32 v146, v142, v122
	v_mov_b32_e32 v147, v143
	v_lshlrev_b64 v[146:147], 8, v[146:147]
	v_or_b32_e32 v146, v146, v144
	v_lshl_add_u64 v[154:155], s[36:37], 0, v[146:147]
	global_store_short_d16_hi v[154:155], v157, off
	v_mul_f32_e32 v154, 0xbfb8aa3b, v145
	v_exp_f32_e32 v154, v154
	v_lshl_add_u64 v[146:147], s[38:39], 0, v[146:147]
	v_mul_f32_e32 v154, v154, v156
	v_bfe_u32 v155, v154, 16, 1
	v_add3_u32 v154, v154, v155, s73
	global_store_short_d16_hi v[146:147], v154, off
	v_sub_f32_e32 v146, v141, v145
	v_mul_f32_e32 v146, 0x3fb8aa3b, v146
	v_exp_f32_e32 v146, v146
	s_nop 0
	v_mul_f32_e32 v146, v146, v156
	v_bfe_u32 v147, v146, 16, 1
	v_add3_u32 v154, v146, v147, s73
	v_lshlrev_b32_e32 v146, 1, v122
	v_mov_b32_e32 v147, v3
	v_lshl_add_u64 v[146:147], v[6:7], 0, v[146:147]
	v_and_or_b32 v223, v154, s98, v223
	v_alignbit_b32 v226, v223, v223, 16
	v_alignbit_b32 v218, v220, v220, 16
	v_cndmask_b32_e64 v220, v226, v220, s[4:5]
	v_cndmask_b32_e64 v223, v218, v223, s[4:5]
	v_alignbit_b32 v226, v222, v222, 16
	v_alignbit_b32 v218, v221, v221, 16
	v_cndmask_b32_e64 v221, v226, v221, s[4:5]
	v_cndmask_b32_e64 v222, v218, v222, s[4:5]
	v_lshl_add_u64 v[218:219], v[146:147], 0, v[224:225]
	global_store_dwordx4 v[218:219], v[220:223], off
	s_nop 1
	ds_read_u16 v147, v162 offset:24576
	v_cndmask_b32_e64 v146, v180, v239, s[4:5]
	v_add_f32_e32 v145, v146, v145
	ds_read_u16 v146, v162 offset:8192
	s_waitcnt lgkmcnt(1)
	v_lshlrev_b32_e32 v156, 16, v147
	v_mul_f32_e32 v147, 0x3fb8aa3b, v145
	v_exp_f32_e32 v147, v147
	s_waitcnt lgkmcnt(0)
	v_lshlrev_b32_e32 v146, 16, v146
	v_mul_f32_e32 v146, 0x3db504f3, v146
	v_mul_f32_e32 v146, v147, v146
	v_bfe_u32 v147, v146, 16, 1
	v_add3_u32 v157, v146, v147, s73
	v_or_b32_e32 v146, v142, v124
	v_mov_b32_e32 v147, v143
	v_lshlrev_b64 v[146:147], 8, v[146:147]
	v_or_b32_e32 v146, v146, v144
	v_lshl_add_u64 v[154:155], s[36:37], 0, v[146:147]
	global_store_short_d16_hi v[154:155], v157, off
	v_mul_f32_e32 v154, 0xbfb8aa3b, v145
	v_exp_f32_e32 v154, v154
	v_lshl_add_u64 v[146:147], s[38:39], 0, v[146:147]
	v_mul_f32_e32 v154, v154, v156
	v_bfe_u32 v155, v154, 16, 1
	v_add3_u32 v154, v154, v155, s73
	global_store_short_d16_hi v[146:147], v154, off
	v_sub_f32_e32 v146, v141, v145
	v_mul_f32_e32 v146, 0x3fb8aa3b, v146
	v_exp_f32_e32 v146, v146
	s_nop 0
	v_mul_f32_e32 v146, v146, v156
	v_bfe_u32 v147, v146, 16, 1
	v_add3_u32 v154, v146, v147, s73
	v_lshlrev_b32_e32 v146, 1, v124
	v_mov_b32_e32 v147, v3
	v_lshl_add_u64 v[146:147], v[6:7], 0, v[146:147]
	v_lshrrev_b32_e32 v220, 16, v154
	ds_read_u16 v147, v163 offset:24576
	v_cndmask_b32_e64 v146, v179, v245, s[4:5]
	v_add_f32_e32 v145, v146, v145
	ds_read_u16 v146, v163 offset:8192
	s_waitcnt lgkmcnt(1)
	v_lshlrev_b32_e32 v156, 16, v147
	v_mul_f32_e32 v147, 0x3fb8aa3b, v145
	v_exp_f32_e32 v147, v147
	s_waitcnt lgkmcnt(0)
	v_lshlrev_b32_e32 v146, 16, v146
	v_mul_f32_e32 v146, 0x3db504f3, v146
	v_mul_f32_e32 v146, v147, v146
	v_bfe_u32 v147, v146, 16, 1
	v_add3_u32 v157, v146, v147, s73
	v_or_b32_e32 v146, v142, v126
	v_mov_b32_e32 v147, v143
	v_lshlrev_b64 v[146:147], 8, v[146:147]
	v_or_b32_e32 v146, v146, v144
	v_lshl_add_u64 v[154:155], s[36:37], 0, v[146:147]
	global_store_short_d16_hi v[154:155], v157, off
	v_mul_f32_e32 v154, 0xbfb8aa3b, v145
	v_exp_f32_e32 v154, v154
	v_lshl_add_u64 v[146:147], s[38:39], 0, v[146:147]
	v_mul_f32_e32 v154, v154, v156
	v_bfe_u32 v155, v154, 16, 1
	v_add3_u32 v154, v154, v155, s73
	global_store_short_d16_hi v[146:147], v154, off
	v_sub_f32_e32 v146, v141, v145
	v_mul_f32_e32 v146, 0x3fb8aa3b, v146
	v_exp_f32_e32 v146, v146
	s_nop 0
	v_mul_f32_e32 v146, v146, v156
	v_bfe_u32 v147, v146, 16, 1
	v_add3_u32 v154, v146, v147, s73
	v_lshlrev_b32_e32 v146, 1, v126
	v_mov_b32_e32 v147, v3
	v_lshl_add_u64 v[146:147], v[6:7], 0, v[146:147]
	v_and_or_b32 v220, v154, s98, v220
	ds_read_u16 v147, v164 offset:24576
	v_cndmask_b32_e64 v146, v178, v249, s[4:5]
	v_add_f32_e32 v145, v146, v145
	ds_read_u16 v146, v164 offset:8192
	s_waitcnt lgkmcnt(1)
	v_lshlrev_b32_e32 v156, 16, v147
	v_mul_f32_e32 v147, 0x3fb8aa3b, v145
	v_exp_f32_e32 v147, v147
	s_waitcnt lgkmcnt(0)
	v_lshlrev_b32_e32 v146, 16, v146
	v_mul_f32_e32 v146, 0x3db504f3, v146
	v_mul_f32_e32 v146, v147, v146
	v_bfe_u32 v147, v146, 16, 1
	v_add3_u32 v157, v146, v147, s73
	v_or_b32_e32 v146, v142, v128
	v_mov_b32_e32 v147, v143
	v_lshlrev_b64 v[146:147], 8, v[146:147]
	v_or_b32_e32 v146, v146, v144
	v_lshl_add_u64 v[154:155], s[36:37], 0, v[146:147]
	global_store_short_d16_hi v[154:155], v157, off
	v_mul_f32_e32 v154, 0xbfb8aa3b, v145
	v_exp_f32_e32 v154, v154
	v_lshl_add_u64 v[146:147], s[38:39], 0, v[146:147]
	v_mul_f32_e32 v154, v154, v156
	v_bfe_u32 v155, v154, 16, 1
	v_add3_u32 v154, v154, v155, s73
	global_store_short_d16_hi v[146:147], v154, off
	v_sub_f32_e32 v146, v141, v145
	v_mul_f32_e32 v146, 0x3fb8aa3b, v146
	v_exp_f32_e32 v146, v146
	s_nop 0
	v_mul_f32_e32 v146, v146, v156
	v_bfe_u32 v147, v146, 16, 1
	v_add3_u32 v154, v146, v147, s73
	v_lshlrev_b32_e32 v146, 1, v128
	v_mov_b32_e32 v147, v3
	v_lshl_add_u64 v[146:147], v[6:7], 0, v[146:147]
	v_lshrrev_b32_e32 v221, 16, v154
	ds_read_u16 v147, v165 offset:24576
	v_cndmask_b32_e64 v146, v177, v250, s[4:5]
	v_add_f32_e32 v145, v146, v145
	ds_read_u16 v146, v165 offset:8192
	s_waitcnt lgkmcnt(1)
	v_lshlrev_b32_e32 v156, 16, v147
	v_mul_f32_e32 v147, 0x3fb8aa3b, v145
	v_exp_f32_e32 v147, v147
	s_waitcnt lgkmcnt(0)
	v_lshlrev_b32_e32 v146, 16, v146
	v_mul_f32_e32 v146, 0x3db504f3, v146
	v_mul_f32_e32 v146, v147, v146
	v_bfe_u32 v147, v146, 16, 1
	v_add3_u32 v157, v146, v147, s73
	v_or_b32_e32 v146, v142, v130
	v_mov_b32_e32 v147, v143
	v_lshlrev_b64 v[146:147], 8, v[146:147]
	v_or_b32_e32 v146, v146, v144
	v_lshl_add_u64 v[154:155], s[36:37], 0, v[146:147]
	global_store_short_d16_hi v[154:155], v157, off
	v_mul_f32_e32 v154, 0xbfb8aa3b, v145
	v_exp_f32_e32 v154, v154
	v_lshl_add_u64 v[146:147], s[38:39], 0, v[146:147]
	v_mul_f32_e32 v154, v154, v156
	v_bfe_u32 v155, v154, 16, 1
	v_add3_u32 v154, v154, v155, s73
	global_store_short_d16_hi v[146:147], v154, off
	v_sub_f32_e32 v146, v141, v145
	v_mul_f32_e32 v146, 0x3fb8aa3b, v146
	v_exp_f32_e32 v146, v146
	s_nop 0
	v_mul_f32_e32 v146, v146, v156
	v_bfe_u32 v147, v146, 16, 1
	v_add3_u32 v154, v146, v147, s73
	v_lshlrev_b32_e32 v146, 1, v130
	v_mov_b32_e32 v147, v3
	v_lshl_add_u64 v[146:147], v[6:7], 0, v[146:147]
	v_and_or_b32 v221, v154, s98, v221
	ds_read_u16 v147, v166 offset:24576
	v_cndmask_b32_e64 v146, v176, v243, s[4:5]
	v_add_f32_e32 v145, v146, v145
	ds_read_u16 v146, v166 offset:8192
	s_waitcnt lgkmcnt(1)
	v_lshlrev_b32_e32 v156, 16, v147
	v_mul_f32_e32 v147, 0x3fb8aa3b, v145
	v_exp_f32_e32 v147, v147
	s_waitcnt lgkmcnt(0)
	v_lshlrev_b32_e32 v146, 16, v146
	v_mul_f32_e32 v146, 0x3db504f3, v146
	v_mul_f32_e32 v146, v147, v146
	v_bfe_u32 v147, v146, 16, 1
	v_add3_u32 v157, v146, v147, s73
	v_or_b32_e32 v146, v142, v132
	v_mov_b32_e32 v147, v143
	v_lshlrev_b64 v[146:147], 8, v[146:147]
	v_or_b32_e32 v146, v146, v144
	v_lshl_add_u64 v[154:155], s[36:37], 0, v[146:147]
	global_store_short_d16_hi v[154:155], v157, off
	v_mul_f32_e32 v154, 0xbfb8aa3b, v145
	v_exp_f32_e32 v154, v154
	v_lshl_add_u64 v[146:147], s[38:39], 0, v[146:147]
	v_mul_f32_e32 v154, v154, v156
	v_bfe_u32 v155, v154, 16, 1
	v_add3_u32 v154, v154, v155, s73
	global_store_short_d16_hi v[146:147], v154, off
	v_sub_f32_e32 v146, v141, v145
	v_mul_f32_e32 v146, 0x3fb8aa3b, v146
	v_exp_f32_e32 v146, v146
	s_nop 0
	v_mul_f32_e32 v146, v146, v156
	v_bfe_u32 v147, v146, 16, 1
	v_add3_u32 v154, v146, v147, s73
	v_lshlrev_b32_e32 v146, 1, v132
	v_mov_b32_e32 v147, v3
	v_lshl_add_u64 v[146:147], v[6:7], 0, v[146:147]
	v_lshrrev_b32_e32 v222, 16, v154
	ds_read_u16 v147, v167 offset:24576
	v_cndmask_b32_e64 v146, v175, v248, s[4:5]
	v_add_f32_e32 v145, v146, v145
	ds_read_u16 v146, v167 offset:8192
	s_waitcnt lgkmcnt(1)
	v_lshlrev_b32_e32 v156, 16, v147
	v_mul_f32_e32 v147, 0x3fb8aa3b, v145
	v_exp_f32_e32 v147, v147
	s_waitcnt lgkmcnt(0)
	v_lshlrev_b32_e32 v146, 16, v146
	v_mul_f32_e32 v146, 0x3db504f3, v146
	v_mul_f32_e32 v146, v147, v146
	v_bfe_u32 v147, v146, 16, 1
	v_add3_u32 v157, v146, v147, s73
	v_or_b32_e32 v146, v142, v134
	v_mov_b32_e32 v147, v143
	v_lshlrev_b64 v[146:147], 8, v[146:147]
	v_or_b32_e32 v146, v146, v144
	v_lshl_add_u64 v[154:155], s[36:37], 0, v[146:147]
	global_store_short_d16_hi v[154:155], v157, off
	v_mul_f32_e32 v154, 0xbfb8aa3b, v145
	v_exp_f32_e32 v154, v154
	v_lshl_add_u64 v[146:147], s[38:39], 0, v[146:147]
	v_mul_f32_e32 v154, v154, v156
	v_bfe_u32 v155, v154, 16, 1
	v_add3_u32 v154, v154, v155, s73
	global_store_short_d16_hi v[146:147], v154, off
	v_sub_f32_e32 v146, v141, v145
	v_mul_f32_e32 v146, 0x3fb8aa3b, v146
	v_exp_f32_e32 v146, v146
	s_nop 0
	v_mul_f32_e32 v146, v146, v156
	v_bfe_u32 v147, v146, 16, 1
	v_add3_u32 v154, v146, v147, s73
	v_lshlrev_b32_e32 v146, 1, v134
	v_mov_b32_e32 v147, v3
	v_lshl_add_u64 v[146:147], v[6:7], 0, v[146:147]
	v_and_or_b32 v222, v154, s98, v222
	ds_read_u16 v147, v168 offset:24576
	v_cndmask_b32_e64 v146, v174, v251, s[4:5]
	v_add_f32_e32 v145, v146, v145
	ds_read_u16 v146, v168 offset:8192
	s_waitcnt lgkmcnt(1)
	v_lshlrev_b32_e32 v156, 16, v147
	v_mul_f32_e32 v147, 0x3fb8aa3b, v145
	v_exp_f32_e32 v147, v147
	s_waitcnt lgkmcnt(0)
	v_lshlrev_b32_e32 v146, 16, v146
	v_mul_f32_e32 v146, 0x3db504f3, v146
	v_mul_f32_e32 v146, v147, v146
	v_bfe_u32 v147, v146, 16, 1
	v_add3_u32 v157, v146, v147, s73
	v_or_b32_e32 v146, v142, v136
	v_mov_b32_e32 v147, v143
	v_lshlrev_b64 v[146:147], 8, v[146:147]
	v_or_b32_e32 v146, v146, v144
	v_lshl_add_u64 v[154:155], s[36:37], 0, v[146:147]
	global_store_short_d16_hi v[154:155], v157, off
	v_mul_f32_e32 v154, 0xbfb8aa3b, v145
	v_exp_f32_e32 v154, v154
	v_lshl_add_u64 v[146:147], s[38:39], 0, v[146:147]
	v_or_b32_e32 v142, v142, v138
	v_lshlrev_b64 v[142:143], 8, v[142:143]
	v_mul_f32_e32 v154, v154, v156
	v_bfe_u32 v155, v154, 16, 1
	v_add3_u32 v154, v154, v155, s73
	global_store_short_d16_hi v[146:147], v154, off
	v_sub_f32_e32 v146, v141, v145
	v_mul_f32_e32 v146, 0x3fb8aa3b, v146
	v_exp_f32_e32 v146, v146
	v_or_b32_e32 v142, v142, v144
	v_mul_f32_e32 v146, v146, v156
	v_bfe_u32 v147, v146, 16, 1
	v_add3_u32 v154, v146, v147, s73
	v_lshlrev_b32_e32 v146, 1, v136
	v_mov_b32_e32 v147, v3
	v_lshl_add_u64 v[146:147], v[6:7], 0, v[146:147]
	v_lshrrev_b32_e32 v223, 16, v154
	v_cndmask_b32_e64 v146, v173, v252, s[4:5]
	v_add_f32_e32 v146, v146, v145
	ds_read_u16 v145, v169 offset:8192
	v_mul_f32_e32 v154, 0x3fb8aa3b, v146
	v_exp_f32_e32 v154, v154
	ds_read_u16 v147, v169 offset:24576
	s_waitcnt lgkmcnt(1)
	v_lshlrev_b32_e32 v145, 16, v145
	v_mul_f32_e32 v145, 0x3db504f3, v145
	v_mul_f32_e32 v145, v154, v145
	v_bfe_u32 v154, v145, 16, 1
	v_add3_u32 v154, v145, v154, s73
	v_lshl_add_u64 v[144:145], s[36:37], 0, v[142:143]
	global_store_short_d16_hi v[144:145], v154, off
	v_mul_f32_e32 v144, 0xbfb8aa3b, v146
	v_exp_f32_e32 v144, v144
	s_waitcnt lgkmcnt(0)
	v_lshlrev_b32_e32 v147, 16, v147
	v_lshl_add_u64 v[142:143], s[38:39], 0, v[142:143]
	v_mul_f32_e32 v144, v144, v147
	v_bfe_u32 v145, v144, 16, 1
	v_add3_u32 v144, v144, v145, s73
	global_store_short_d16_hi v[142:143], v144, off
	v_sub_f32_e32 v142, v141, v146
	v_mul_f32_e32 v142, 0x3fb8aa3b, v142
	v_exp_f32_e32 v142, v142
	s_nop 0
	v_mul_f32_e32 v142, v142, v147
	v_bfe_u32 v143, v142, 16, 1
	v_add3_u32 v144, v142, v143, s73
	v_lshlrev_b32_e32 v142, 1, v138
	v_mov_b32_e32 v143, v3
	v_lshl_add_u64 v[6:7], v[6:7], 0, v[142:143]
	v_and_or_b32 v223, v144, s98, v223
	v_alignbit_b32 v226, v223, v223, 16
	v_alignbit_b32 v218, v220, v220, 16
	v_cndmask_b32_e64 v220, v226, v220, s[4:5]
	v_cndmask_b32_e64 v223, v218, v223, s[4:5]
	v_alignbit_b32 v226, v222, v222, 16
	v_alignbit_b32 v218, v221, v221, 16
	v_cndmask_b32_e64 v221, v226, v221, s[4:5]
	v_cndmask_b32_e64 v222, v218, v222, s[4:5]
	v_lshl_add_u64 v[218:219], v[6:7], 0, v[224:225]
	global_store_dwordx4 v[218:219], v[220:223], off
	s_nop 1
	v_and_b32_e32 v227, 0xff, v0
	v_lshrrev_b32_e32 v228, 8, v0
	v_lshlrev_b32_e32 v227, 2, v227
	v_lshl_add_u32 v227, v228, 16, v227
	ds_read_b32 v218, v227 offset:40960
	ds_read_b32 v219, v227 offset:41984
	ds_read_b32 v220, v227 offset:43008
	ds_read_b32 v221, v227 offset:44032
	ds_read_b32 v222, v227 offset:45056
	ds_read_b32 v223, v227 offset:46080
	ds_read_b32 v224, v227 offset:47104
	ds_read_b32 v225, v227 offset:48128
	ds_read_b32 v226, v227 offset:49152
	s_waitcnt lgkmcnt(0)
	v_mul_f32_e32 v6, 0x3fb8aa3b, v141
	v_exp_f32_e32 v6, v6
	global_store_dword v[4:5], v6, off
	s_andn2_b64 exec, exec, s[12:13]
	s_cbranch_execnz .LBB0_759
.LBB0_762:
	s_or_b64 exec, exec, s[6:7]
	s_cmp_eq_u32 s99, 1
	s_cbranch_scc1 .LBB0_766
	s_mov_b32 s0, s87
	v_mov_b32_e32 v1, v0
	s_nop 0
	v_lshl_add_u32 v1, s0, 9, v1
	v_cmp_gt_i32_e32 vcc, s43, v1
	s_and_saveexec_b64 s[0:1], vcc
	s_cbranch_execz .LBB0_765
	s_load_dword s2, s[20:21], 0x0
	s_mov_b64 s[4:5], 0
	s_waitcnt lgkmcnt(0)
	s_lshl_b32 s2, s2, 9

.LBB0_767:
	s_andn2_b64 vcc, exec, s[0:1]
	s_cbranch_vccnz .LBB0_786
	s_mov_b32 s0, s87
	v_mov_b32_e32 v2, v0
	s_mov_b32 s1, 0x200000
	v_lshl_add_u32 v1, s0, 9, v2
	v_cmp_gt_i32_e32 vcc, s1, v1
	s_and_saveexec_b64 s[6:7], vcc
	s_mov_b32 s14, 0xffff
	s_mov_b32 s12, 0x7ffff
	s_mov_b32 s13, 0x100000
	s_mov_b32 s15, 0xfffff
	s_movk_i32 s16, 0xf0
	s_mov_b32 s17, 0x504010c
	s_mov_b32 s18, 0x7060302
	s_cbranch_execz .LBB0_773
	v_and_b32_e32 v5, 64, v223
	v_xor_b32_e32 v4, 1, v223
	v_add_u32_e32 v5, 64, v5
	v_cmp_lt_i32_e32 vcc, v4, v5
	s_load_dwordx2 s[2:3], s[30:31], 0x170
	s_load_dword s1, s[20:21], 0x0
	v_cndmask_b32_e32 v4, v223, v4, vcc
	v_lshlrev_b32_e32 v12, 2, v4
	v_xor_b32_e32 v4, 2, v223
	v_cmp_lt_i32_e32 vcc, v4, v5
	s_waitcnt lgkmcnt(0)
	s_add_u32 s8, s2, 0x2000000
	v_lshlrev_b32_e32 v2, 3, v2
	v_cndmask_b32_e32 v4, v223, v4, vcc
	v_lshlrev_b32_e32 v13, 2, v4
	v_xor_b32_e32 v4, 4, v223
	v_cmp_lt_i32_e32 vcc, v4, v5
	s_addc_u32 s9, s3, 0
	s_lshl_b32 s2, s1, 9
	v_cndmask_b32_e32 v4, v223, v4, vcc
	v_lshlrev_b32_e32 v14, 2, v4
	v_lshl_add_u32 v15, s0, 12, v2
	s_lshl_b32 s3, s1, 12
	s_mov_b64 s[10:11], 0
	v_mov_b32_e32 v104, 0xa8
	global_load_dwordx4 v[100:103], v104, s[30:31]
	v_and_b32_e32 v106, 56, v15
	v_lshlrev_b32_e32 v106, 2, v106
	v_mov_b32_e32 v107, 0
	s_waitcnt vmcnt(0)
	v_lshl_add_u64 v[100:101], v[100:101], 0, v[106:107]
	v_lshl_add_u64 v[102:103], v[102:103], 0, v[106:107]
	global_load_dwordx4 v[80:83], v[100:101], off
	global_load_dwordx4 v[84:87], v[100:101], off offset:16
	global_load_dwordx4 v[88:91], v[102:103], off
	global_load_dwordx4 v[92:95], v[102:103], off offset:16
	s_waitcnt vmcnt(0)

.Lp0_t3:
	s_or_b64 exec, exec, s[0:1]
	v_add_u32_e32 v1, s2, v1
	v_add_u32_e32 v15, s3, v15
	v_cmp_lt_i32_e32 vcc, s33, v1
	s_or_b64 s[10:11], vcc, s[10:11]
	s_andn2_b64 exec, exec, s[10:11]
	s_cbranch_execz .LBB0_773
	s_branch .Lp0_loop
.LBB0_773:
	s_or_b64 exec, exec, s[6:7]
	s_mov_b32 s2, s87
	v_mov_b32_e32 v2, v0
	s_mov_b32 s0, 0x80000
	v_lshl_add_u32 v1, s2, 9, v2
	v_cmp_gt_i32_e32 vcc, s0, v1
	s_and_saveexec_b64 s[0:1], vcc
	s_movk_i32 s10, 0x1000
	s_cbranch_execz .LBB0_776
	s_load_dwordx2 s[4:5], s[30:31], 0x170
	s_load_dword s3, s[20:21], 0x0
	v_lshlrev_b32_e32 v2, 3, v2
	v_lshl_add_u32 v4, s2, 12, v2
	s_mov_b64 s[6:7], 0
	s_waitcnt lgkmcnt(0)
	s_add_u32 s4, s4, 0x3000000
	s_addc_u32 s5, s5, 0
	s_lshl_b32 s2, s3, 9
	s_lshl_b32 s3, s3, 12
